# G1 gate pre-activation on the f32 matrix cores: 64 v_mfma_f32_16x16x4_f32 (C = bias, k in order = same fma chain) + LDS transpose instead of 1024 readlane/fmac triples per unit; hazard pads restored
# baseline (speedup 1.0000x reference)
.LBB0_284:
	s_mul_hi_i32 s4, s18, 0x2aaaaaab
	s_lshr_b32 s5, s4, 31
	s_load_dwordx4 s[8:11], s[14:15], 0x60
	s_add_i32 s31, s4, s5
	v_and_b32_e32 v54, 63, v108
	s_lshl_b32 s4, s31, 12
	s_add_i32 s4, s4, 0
	v_lshlrev_b32_e32 v70, 2, v54
	v_add_u32_e32 v55, s4, v70
	s_mul_i32 s4, s42, 0x6000
	s_waitcnt lgkmcnt(0)
	s_add_u32 s6, s8, s4
	s_addc_u32 s7, s9, 0
	s_mul_i32 s4, s42, 0x600
	s_add_u32 s4, s10, s4
	s_addc_u32 s5, s11, 0
	s_add_i32 s8, s31, s27
	s_mul_i32 s9, s31, -6
	s_add_i32 s30, s18, s9
	v_mbcnt_lo_u32_b32 v248, -1, 0
	v_mbcnt_hi_u32_b32 v248, -1, v248
	v_and_b32_e32 v249, 15, v248
	v_lshrrev_b32_e32 v250, 4, v248
	s_lshl_b32 s88, s30, 8
	v_mul_u32_u24_e32 v251, 0x600, v250
	v_lshl_add_u32 v251, v249, 2, v251
	v_add_u32_e32 v251, s88, v251
	global_load_dword v194, v251, s[6:7]
	global_load_dword v195, v251, s[6:7] offset:64
	global_load_dword v196, v251, s[6:7] offset:128
	global_load_dword v197, v251, s[6:7] offset:192
	v_add_u32_e32 v251, 0x1800, v251
	global_load_dword v198, v251, s[6:7]
	global_load_dword v199, v251, s[6:7] offset:64
	global_load_dword v200, v251, s[6:7] offset:128
	global_load_dword v201, v251, s[6:7] offset:192
	v_add_u32_e32 v251, 0x1800, v251
	global_load_dword v202, v251, s[6:7]
	global_load_dword v203, v251, s[6:7] offset:64
	global_load_dword v204, v251, s[6:7] offset:128
	global_load_dword v205, v251, s[6:7] offset:192
	v_add_u32_e32 v251, 0x1800, v251
	global_load_dword v206, v251, s[6:7]
	global_load_dword v207, v251, s[6:7] offset:64
	global_load_dword v208, v251, s[6:7] offset:128
	global_load_dword v209, v251, s[6:7] offset:192
	v_lshl_add_u32 v251, v249, 2, s88
	global_load_dword v236, v251, s[4:5]
	global_load_dword v237, v251, s[4:5] offset:64
	global_load_dword v238, v251, s[4:5] offset:128
	global_load_dword v239, v251, s[4:5] offset:192
	s_ashr_i32 s9, s8, 31
	s_mul_i32 s11, s8, 0xb0000
	s_mul_hi_i32 s10, s8, 0xb0000
	s_add_u32 s33, s16, s11
	s_addc_u32 s35, s17, s10
	s_mul_i32 s10, s31, 0xfffffe80
	s_add_i32 s10, s28, s10
	s_ashr_i32 s11, s10, 31
	s_lshl_b64 s[10:11], s[10:11], 1
	s_add_u32 s34, s33, s10
	v_lshlrev_b32_e32 v4, 1, v54
	s_addc_u32 s35, s35, s11
	v_lshl_add_u64 v[52:53], s[34:35], 0, v[4:5]
	s_lshl_b64 s[34:35], s[8:9], 6
	v_bfe_u32 v72, v108, 3, 3
	v_or_b32_e32 v6, s34, v72
	v_mov_b64_e32 v[2:3], s[16:17]
	s_mul_i32 s9, s31, 0xfffffd00
	v_mad_u64_u32 v[2:3], s[38:39], v6, s2, v[2:3]
	s_add_i32 s34, s29, s9
	v_mad_i32_i24 v3, s35, v243, v3
	s_ashr_i32 s35, s34, 31
	v_and_b32_e32 v6, 7, v108
	v_lshl_add_u64 v[2:3], s[34:35], 1, v[2:3]
	v_lshlrev_b32_e32 v6, 4, v6
	v_mov_b32_e32 v7, v5
	v_lshl_add_u64 v[30:31], v[2:3], 0, v[6:7]
	v_add_co_u32_e32 v6, vcc, s75, v30
	s_mulk_i32 s31, 0x180
	s_nop 0
	v_addc_co_u32_e32 v7, vcc, 0, v31, vcc
	v_add_co_u32_e32 v38, vcc, s64, v30
	v_subrev_u32_e32 v54, s31, v54
	s_nop 0
	v_addc_co_u32_e32 v39, vcc, 0, v31, vcc
	v_add_co_u32_e32 v40, vcc, s57, v30
	v_add_u32_e32 v54, s28, v54
	s_nop 0
	v_addc_co_u32_e32 v41, vcc, 0, v31, vcc
	v_add_co_u32_e32 v42, vcc, s58, v30
	v_add_u32_e32 v73, 0x20000, v55
	s_nop 0
	v_addc_co_u32_e32 v43, vcc, 0, v31, vcc
	v_add_co_u32_e32 v44, vcc, s59, v30
	v_ashrrev_i32_e32 v55, 31, v54
	s_nop 0
	v_addc_co_u32_e32 v45, vcc, 0, v31, vcc
	v_add_co_u32_e32 v46, vcc, s60, v30
	v_lshlrev_b64 v[74:75], 2, v[54:55]
	s_nop 0
	v_addc_co_u32_e32 v47, vcc, 0, v31, vcc
	v_add_co_u32_e32 v48, vcc, s97, v30
	v_lshl_add_u64 v[54:55], s[6:7], 0, v[74:75]
	s_nop 0
	v_addc_co_u32_e32 v49, vcc, 0, v31, vcc
	v_add_co_u32_e32 v50, vcc, s47, v30
	s_mov_b64 s[34:35], 0x2000
	s_nop 0
	v_addc_co_u32_e32 v51, vcc, 0, v31, vcc
	v_add_co_u32_e32 v56, vcc, s1, v54
	v_lshl_add_u64 v[2:3], v[30:31], 0, s[34:35]
	s_nop 0
	v_addc_co_u32_e32 v57, vcc, 0, v55, vcc
	global_load_dwordx4 v[34:37], v[6:7], off
	global_load_dwordx4 v[10:13], v[40:41], off
	global_load_dwordx4 v[14:17], v[42:43], off
	global_load_dwordx4 v[18:21], v[44:45], off
	global_load_dwordx4 v[22:25], v[46:47], off
	global_load_dwordx4 v[26:29], v[48:49], off
	global_load_dwordx4 v[30:33], v[50:51], off
	global_load_dwordx4 v[6:9], v[38:39], off
	global_load_dword v99, v[54:55], off
	ds_read2st64_b32 v[68:69], v73 offset1:1
	global_load_dword v130, v[54:55], off offset:1536
	global_load_dword v98, v[54:55], off offset:3072
	ds_read2st64_b32 v[66:67], v73 offset0:2 offset1:3
	global_load_dword v133, v[56:57], off offset:512
	global_load_dword v131, v[56:57], off offset:2048
	global_load_dword v132, v[56:57], off offset:3584
	v_add_co_u32_e32 v56, vcc, s75, v54
	v_lshl_add_u64 v[74:75], s[4:5], 0, v[74:75]
	s_nop 0
	v_addc_co_u32_e32 v57, vcc, 0, v55, vcc
	global_load_dword v134, v[56:57], off offset:1024
	global_load_dword v135, v[56:57], off offset:2560
	v_add_co_u32_e32 v56, vcc, s74, v54
	ds_read2st64_b32 v[64:65], v73 offset0:4 offset1:5
	ds_read2st64_b32 v[62:63], v73 offset0:6 offset1:7
	ds_read2st64_b32 v[60:61], v73 offset0:8 offset1:9
	v_addc_co_u32_e32 v57, vcc, 0, v55, vcc
	v_add_co_u32_e32 v76, vcc, s79, v54
	global_load_dword v137, v[56:57], off
	s_nop 0
	v_addc_co_u32_e32 v77, vcc, 0, v55, vcc
	global_load_dword v138, v[56:57], off offset:1536
	global_load_dword v136, v[56:57], off offset:3072
	ds_read2st64_b32 v[58:59], v73 offset0:10 offset1:11
	global_load_dword v141, v[76:77], off offset:512
	global_load_dword v139, v[76:77], off offset:2048
	global_load_dword v144, v[74:75], off
	global_load_dword v140, v[76:77], off offset:3584
	v_add_co_u32_e32 v76, vcc, s40, v54
	s_waitcnt lgkmcnt(5)
	s_nop 0
	v_addc_co_u32_e32 v77, vcc, 0, v55, vcc
	global_load_dword v142, v[76:77], off offset:1024
	global_load_dword v143, v[76:77], off offset:2560
	ds_read2st64_b32 v[56:57], v73 offset0:12 offset1:13
	ds_read2st64_b32 v[54:55], v73 offset0:14 offset1:15
	s_mul_i32 s5, s8, 6
	v_and_b32_e32 v71, 15, v108
	v_lshlrev_b32_e32 v147, 1, v71
	s_waitcnt vmcnt(3)
	s_waitcnt vmcnt(0) lgkmcnt(0)
	v_lshlrev_b32_e32 v251, 2, v248
	v_sub_u32_e32 v251, v73, v251
	v_lshl_add_u32 v251, v249, 6, v251
	v_lshl_add_u32 v251, v250, 2, v251
	v_and_b32_e32 v212, 3, v249
	v_xor_b32_e32 v212, v212, v250
	v_lshlrev_b32_e32 v212, 4, v212
	v_lshrrev_b32_e32 v213, 2, v249
	v_lshl_or_b32 v212, v213, 6, v212
	v_lshl_or_b32 v212, v249, 8, v212
	v_add_u32_e32 v250, s13, v212
	v_lshlrev_b32_e32 v212, 8, v248
	v_lshl_or_b32 v212, v249, 4, v212
	v_add_u32_e32 v248, s13, v212
	ds_read_b32 v212, v251 offset:0
	ds_read_b32 v213, v251 offset:16
	ds_read_b32 v214, v251 offset:32
	ds_read_b32 v215, v251 offset:48
	v_mov_b32_e32 v216, v236
	v_mov_b32_e32 v217, v236
	v_mov_b32_e32 v218, v236
	v_mov_b32_e32 v219, v236
	v_mov_b32_e32 v220, v237
	v_mov_b32_e32 v221, v237
	v_mov_b32_e32 v222, v237
	v_mov_b32_e32 v223, v237
	v_mov_b32_e32 v224, v238
	v_mov_b32_e32 v225, v238
	v_mov_b32_e32 v226, v238
	v_mov_b32_e32 v227, v238
	v_mov_b32_e32 v228, v239
	v_mov_b32_e32 v229, v239
	v_mov_b32_e32 v230, v239
	v_mov_b32_e32 v231, v239
	s_waitcnt lgkmcnt(0)
	s_nop 1
	v_mfma_f32_16x16x4_f32 v[216:219], v212, v194, v[216:219]
	v_mfma_f32_16x16x4_f32 v[220:223], v212, v195, v[220:223]
	v_mfma_f32_16x16x4_f32 v[224:227], v212, v196, v[224:227]
	v_mfma_f32_16x16x4_f32 v[228:231], v212, v197, v[228:231]
	v_mfma_f32_16x16x4_f32 v[216:219], v213, v198, v[216:219]
	v_mfma_f32_16x16x4_f32 v[220:223], v213, v199, v[220:223]
	v_mfma_f32_16x16x4_f32 v[224:227], v213, v200, v[224:227]
	v_mfma_f32_16x16x4_f32 v[228:231], v213, v201, v[228:231]
	v_mfma_f32_16x16x4_f32 v[216:219], v214, v202, v[216:219]
	v_mfma_f32_16x16x4_f32 v[220:223], v214, v203, v[220:223]
	v_mfma_f32_16x16x4_f32 v[224:227], v214, v204, v[224:227]
	v_mfma_f32_16x16x4_f32 v[228:231], v214, v205, v[228:231]
	v_mfma_f32_16x16x4_f32 v[216:219], v215, v206, v[216:219]
	v_mfma_f32_16x16x4_f32 v[220:223], v215, v207, v[220:223]
	v_mfma_f32_16x16x4_f32 v[224:227], v215, v208, v[224:227]
	v_mfma_f32_16x16x4_f32 v[228:231], v215, v209, v[228:231]
	s_nop 7
	s_nop 3
	v_xor_b32_e32 v249, 0, v250
	ds_write_b128 v249, v[216:219]
	ds_write_b128 v249, v[220:223] offset:4096
	ds_write_b128 v249, v[224:227] offset:8192
	ds_write_b128 v249, v[228:231] offset:12288
	ds_read_b32 v212, v251 offset:1024
	ds_read_b32 v213, v251 offset:1040
	ds_read_b32 v214, v251 offset:1056
	ds_read_b32 v215, v251 offset:1072
	v_mov_b32_e32 v216, v236
	v_mov_b32_e32 v217, v236
	v_mov_b32_e32 v218, v236
	v_mov_b32_e32 v219, v236
	v_mov_b32_e32 v220, v237
	v_mov_b32_e32 v221, v237
	v_mov_b32_e32 v222, v237
	v_mov_b32_e32 v223, v237
	v_mov_b32_e32 v224, v238
	v_mov_b32_e32 v225, v238
	v_mov_b32_e32 v226, v238
	v_mov_b32_e32 v227, v238
	v_mov_b32_e32 v228, v239
	v_mov_b32_e32 v229, v239
	v_mov_b32_e32 v230, v239
	v_mov_b32_e32 v231, v239
	s_waitcnt lgkmcnt(0)
	s_nop 1
	v_mfma_f32_16x16x4_f32 v[216:219], v212, v194, v[216:219]
	v_mfma_f32_16x16x4_f32 v[220:223], v212, v195, v[220:223]
	v_mfma_f32_16x16x4_f32 v[224:227], v212, v196, v[224:227]
	v_mfma_f32_16x16x4_f32 v[228:231], v212, v197, v[228:231]
	v_mfma_f32_16x16x4_f32 v[216:219], v213, v198, v[216:219]
	v_mfma_f32_16x16x4_f32 v[220:223], v213, v199, v[220:223]
	v_mfma_f32_16x16x4_f32 v[224:227], v213, v200, v[224:227]
	v_mfma_f32_16x16x4_f32 v[228:231], v213, v201, v[228:231]
	v_mfma_f32_16x16x4_f32 v[216:219], v214, v202, v[216:219]
	v_mfma_f32_16x16x4_f32 v[220:223], v214, v203, v[220:223]
	v_mfma_f32_16x16x4_f32 v[224:227], v214, v204, v[224:227]
	v_mfma_f32_16x16x4_f32 v[228:231], v214, v205, v[228:231]
	v_mfma_f32_16x16x4_f32 v[216:219], v215, v206, v[216:219]
	v_mfma_f32_16x16x4_f32 v[220:223], v215, v207, v[220:223]
	v_mfma_f32_16x16x4_f32 v[224:227], v215, v208, v[224:227]
	v_mfma_f32_16x16x4_f32 v[228:231], v215, v209, v[228:231]
	s_nop 7
	s_nop 3
	v_xor_b32_e32 v249, 64, v250
	ds_write_b128 v249, v[216:219]
	ds_write_b128 v249, v[220:223] offset:4096
	ds_write_b128 v249, v[224:227] offset:8192
	ds_write_b128 v249, v[228:231] offset:12288
	ds_read_b32 v212, v251 offset:2048
	ds_read_b32 v213, v251 offset:2064
	ds_read_b32 v214, v251 offset:2080
	ds_read_b32 v215, v251 offset:2096
	v_mov_b32_e32 v216, v236
	v_mov_b32_e32 v217, v236
	v_mov_b32_e32 v218, v236
	v_mov_b32_e32 v219, v236
	v_mov_b32_e32 v220, v237
	v_mov_b32_e32 v221, v237
	v_mov_b32_e32 v222, v237
	v_mov_b32_e32 v223, v237
	v_mov_b32_e32 v224, v238
	v_mov_b32_e32 v225, v238
	v_mov_b32_e32 v226, v238
	v_mov_b32_e32 v227, v238
	v_mov_b32_e32 v228, v239
	v_mov_b32_e32 v229, v239
	v_mov_b32_e32 v230, v239
	v_mov_b32_e32 v231, v239
	s_waitcnt lgkmcnt(0)
	s_nop 1
	v_mfma_f32_16x16x4_f32 v[216:219], v212, v194, v[216:219]
	v_mfma_f32_16x16x4_f32 v[220:223], v212, v195, v[220:223]
	v_mfma_f32_16x16x4_f32 v[224:227], v212, v196, v[224:227]
	v_mfma_f32_16x16x4_f32 v[228:231], v212, v197, v[228:231]
	v_mfma_f32_16x16x4_f32 v[216:219], v213, v198, v[216:219]
	v_mfma_f32_16x16x4_f32 v[220:223], v213, v199, v[220:223]
	v_mfma_f32_16x16x4_f32 v[224:227], v213, v200, v[224:227]
	v_mfma_f32_16x16x4_f32 v[228:231], v213, v201, v[228:231]
	v_mfma_f32_16x16x4_f32 v[216:219], v214, v202, v[216:219]
	v_mfma_f32_16x16x4_f32 v[220:223], v214, v203, v[220:223]
	v_mfma_f32_16x16x4_f32 v[224:227], v214, v204, v[224:227]
	v_mfma_f32_16x16x4_f32 v[228:231], v214, v205, v[228:231]
	v_mfma_f32_16x16x4_f32 v[216:219], v215, v206, v[216:219]
	v_mfma_f32_16x16x4_f32 v[220:223], v215, v207, v[220:223]
	v_mfma_f32_16x16x4_f32 v[224:227], v215, v208, v[224:227]
	v_mfma_f32_16x16x4_f32 v[228:231], v215, v209, v[228:231]
	s_nop 7
	s_nop 3
	v_xor_b32_e32 v249, 0x80, v250
	ds_write_b128 v249, v[216:219]
	ds_write_b128 v249, v[220:223] offset:4096
	ds_write_b128 v249, v[224:227] offset:8192
	ds_write_b128 v249, v[228:231] offset:12288
	ds_read_b32 v212, v251 offset:3072
	ds_read_b32 v213, v251 offset:3088
	ds_read_b32 v214, v251 offset:3104
	ds_read_b32 v215, v251 offset:3120
	v_mov_b32_e32 v216, v236
	v_mov_b32_e32 v217, v236
	v_mov_b32_e32 v218, v236
	v_mov_b32_e32 v219, v236
	v_mov_b32_e32 v220, v237
	v_mov_b32_e32 v221, v237
	v_mov_b32_e32 v222, v237
	v_mov_b32_e32 v223, v237
	v_mov_b32_e32 v224, v238
	v_mov_b32_e32 v225, v238
	v_mov_b32_e32 v226, v238
	v_mov_b32_e32 v227, v238
	v_mov_b32_e32 v228, v239
	v_mov_b32_e32 v229, v239
	v_mov_b32_e32 v230, v239
	v_mov_b32_e32 v231, v239
	s_waitcnt lgkmcnt(0)
	s_nop 1
	v_mfma_f32_16x16x4_f32 v[216:219], v212, v194, v[216:219]
	v_mfma_f32_16x16x4_f32 v[220:223], v212, v195, v[220:223]
	v_mfma_f32_16x16x4_f32 v[224:227], v212, v196, v[224:227]
	v_mfma_f32_16x16x4_f32 v[228:231], v212, v197, v[228:231]
	v_mfma_f32_16x16x4_f32 v[216:219], v213, v198, v[216:219]
	v_mfma_f32_16x16x4_f32 v[220:223], v213, v199, v[220:223]
	v_mfma_f32_16x16x4_f32 v[224:227], v213, v200, v[224:227]
	v_mfma_f32_16x16x4_f32 v[228:231], v213, v201, v[228:231]
	v_mfma_f32_16x16x4_f32 v[216:219], v214, v202, v[216:219]
	v_mfma_f32_16x16x4_f32 v[220:223], v214, v203, v[220:223]
	v_mfma_f32_16x16x4_f32 v[224:227], v214, v204, v[224:227]
	v_mfma_f32_16x16x4_f32 v[228:231], v214, v205, v[228:231]
	v_mfma_f32_16x16x4_f32 v[216:219], v215, v206, v[216:219]
	v_mfma_f32_16x16x4_f32 v[220:223], v215, v207, v[220:223]
	v_mfma_f32_16x16x4_f32 v[224:227], v215, v208, v[224:227]
	v_mfma_f32_16x16x4_f32 v[228:231], v215, v209, v[228:231]
	s_nop 7
	s_nop 3
	v_xor_b32_e32 v249, 0xc0, v250
	ds_write_b128 v249, v[216:219]
	ds_write_b128 v249, v[220:223] offset:4096
	ds_write_b128 v249, v[224:227] offset:8192
	ds_write_b128 v249, v[228:231] offset:12288
	s_waitcnt lgkmcnt(0)
	s_waitcnt vmcnt(2)
	s_waitcnt vmcnt(1)
	s_waitcnt vmcnt(0)
	v_xor_b32_e32 v249, 0, v248
	ds_read_b128 v[216:219], v249
	s_waitcnt lgkmcnt(0)
	v_mov_b32_e32 v73, v216
	v_min_f32_e32 v74, 0, v73
	v_mul_f32_e64 v73, |v73|, s0
	v_exp_f32_e32 v73, v73
	s_mov_b32 s4, 0x3d800000
	v_add_f32_e32 v73, 1.0, v73
	v_cmp_gt_f32_e32 vcc, s92, v73
	s_nop 1
	v_cndmask_b32_e64 v75, 0, 32, vcc
	v_ldexp_f32 v73, v73, v75
	v_log_f32_e32 v73, v73
	s_nop 0
	v_mul_f32_e32 v75, 0x3f317217, v73
	v_fma_f32 v75, v73, s3, -v75
	v_fmac_f32_e32 v75, 0x3377d1cf, v73
	v_fmac_f32_e32 v75, 0x3f317217, v73
	v_cmp_lt_f32_e64 s[6:7], |v73|, s96
	s_nop 1
	v_cndmask_b32_e64 v73, v73, v75, s[6:7]
	v_cndmask_b32_e32 v75, 0, v244, vcc
	v_sub_f32_e32 v73, v73, v75
	v_sub_f32_e32 v73, v74, v73
	v_fma_f32 v129, v73, s4, 0
	v_mov_b32_e32 v73, v217
	v_min_f32_e32 v74, 0, v73
	v_mul_f32_e64 v73, |v73|, s0
	v_exp_f32_e32 v73, v73
	s_nop 0
	v_add_f32_e32 v73, 1.0, v73
	v_cmp_gt_f32_e32 vcc, s92, v73
	s_nop 1
	v_cndmask_b32_e64 v75, 0, 32, vcc
	v_ldexp_f32 v73, v73, v75
	v_log_f32_e32 v73, v73
	s_nop 0
	v_mul_f32_e32 v75, 0x3f317217, v73
	v_fma_f32 v75, v73, s3, -v75
	v_fmac_f32_e32 v75, 0x3377d1cf, v73
	v_fmac_f32_e32 v75, 0x3f317217, v73
	v_cmp_lt_f32_e64 s[6:7], |v73|, s96
	s_nop 1
	v_cndmask_b32_e64 v73, v73, v75, s[6:7]
	v_cndmask_b32_e32 v75, 0, v244, vcc
	v_sub_f32_e32 v73, v73, v75
	v_sub_f32_e32 v73, v74, v73
	v_fmamk_f32 v113, v73, 0x3d800000, v129
	v_mov_b32_e32 v73, v218
	v_min_f32_e32 v74, 0, v73
	v_mul_f32_e64 v73, |v73|, s0
	v_exp_f32_e32 v73, v73
	s_nop 0
	v_add_f32_e32 v73, 1.0, v73
	v_cmp_gt_f32_e32 vcc, s92, v73
	s_nop 1
	v_cndmask_b32_e64 v75, 0, 32, vcc
	v_ldexp_f32 v73, v73, v75
	v_log_f32_e32 v73, v73
	s_nop 0
	v_mul_f32_e32 v75, 0x3f317217, v73
	v_fma_f32 v75, v73, s3, -v75
	v_fmac_f32_e32 v75, 0x3377d1cf, v73
	v_fmac_f32_e32 v75, 0x3f317217, v73
	v_cmp_lt_f32_e64 s[6:7], |v73|, s96
	s_nop 1
	v_cndmask_b32_e64 v73, v73, v75, s[6:7]
	v_cndmask_b32_e32 v75, 0, v244, vcc
	v_sub_f32_e32 v73, v73, v75
	v_sub_f32_e32 v73, v74, v73
	v_fmamk_f32 v114, v73, 0x3d800000, v113
	v_mov_b32_e32 v73, v219
	v_min_f32_e32 v68, 0, v73
	v_mul_f32_e64 v73, |v73|, s0
	v_exp_f32_e32 v73, v73
	s_nop 0
	v_add_f32_e32 v73, 1.0, v73
	v_cmp_gt_f32_e32 vcc, s92, v73
	s_nop 1
	v_cndmask_b32_e64 v74, 0, 32, vcc
	v_ldexp_f32 v73, v73, v74
	v_log_f32_e32 v73, v73
	s_nop 0
	v_mul_f32_e32 v74, 0x3f317217, v73
	v_fma_f32 v74, v73, s3, -v74
	v_fmac_f32_e32 v74, 0x3377d1cf, v73
	v_fmac_f32_e32 v74, 0x3f317217, v73
	v_cmp_lt_f32_e64 s[6:7], |v73|, s96
	s_nop 1
	v_cndmask_b32_e64 v73, v73, v74, s[6:7]
	v_cndmask_b32_e32 v74, 0, v244, vcc
	v_sub_f32_e32 v73, v73, v74
	v_sub_f32_e32 v68, v68, v73
	v_fmamk_f32 v115, v68, 0x3d800000, v114
	v_xor_b32_e32 v249, 16, v248
	ds_read_b128 v[216:219], v249
	s_waitcnt lgkmcnt(0)
	v_mov_b32_e32 v68, v216
	v_min_f32_e32 v73, 0, v68
	v_mul_f32_e64 v68, |v68|, s0
	v_exp_f32_e32 v68, v68
	s_nop 0
	v_add_f32_e32 v68, 1.0, v68
	v_cmp_gt_f32_e32 vcc, s92, v68
	s_nop 1
	v_cndmask_b32_e64 v74, 0, 32, vcc
	v_ldexp_f32 v68, v68, v74
	v_log_f32_e32 v68, v68
	s_nop 0
	v_mul_f32_e32 v74, 0x3f317217, v68
	v_fma_f32 v74, v68, s3, -v74
	v_fmac_f32_e32 v74, 0x3377d1cf, v68
	v_fmac_f32_e32 v74, 0x3f317217, v68
	v_cmp_lt_f32_e64 s[6:7], |v68|, s96
	s_nop 1
	v_cndmask_b32_e64 v68, v68, v74, s[6:7]
	v_cndmask_b32_e32 v74, 0, v244, vcc
	v_sub_f32_e32 v68, v68, v74
	v_sub_f32_e32 v68, v73, v68
	v_fmamk_f32 v116, v68, 0x3d800000, v115
	v_mov_b32_e32 v68, v217
	v_min_f32_e32 v73, 0, v68
	v_mul_f32_e64 v68, |v68|, s0
	v_exp_f32_e32 v68, v68
	s_nop 0
	v_add_f32_e32 v68, 1.0, v68
	v_cmp_gt_f32_e32 vcc, s92, v68
	s_nop 1
	v_cndmask_b32_e64 v74, 0, 32, vcc
	v_ldexp_f32 v68, v68, v74
	v_log_f32_e32 v68, v68
	s_nop 0
	v_mul_f32_e32 v74, 0x3f317217, v68
	v_fma_f32 v74, v68, s3, -v74
	v_fmac_f32_e32 v74, 0x3377d1cf, v68
	v_fmac_f32_e32 v74, 0x3f317217, v68
	v_cmp_lt_f32_e64 s[6:7], |v68|, s96
	s_nop 1
	v_cndmask_b32_e64 v68, v68, v74, s[6:7]
	v_cndmask_b32_e32 v74, 0, v244, vcc
	v_sub_f32_e32 v68, v68, v74
	v_sub_f32_e32 v68, v73, v68
	v_fmamk_f32 v117, v68, 0x3d800000, v116
	v_mov_b32_e32 v68, v218
	v_min_f32_e32 v73, 0, v68
	v_mul_f32_e64 v68, |v68|, s0
	v_exp_f32_e32 v68, v68
	s_nop 0
	v_add_f32_e32 v68, 1.0, v68
	v_cmp_gt_f32_e32 vcc, s92, v68
	s_nop 1
	v_cndmask_b32_e64 v74, 0, 32, vcc
	v_ldexp_f32 v68, v68, v74
	v_log_f32_e32 v68, v68
	s_nop 0
	v_mul_f32_e32 v74, 0x3f317217, v68
	v_fma_f32 v74, v68, s3, -v74
	v_fmac_f32_e32 v74, 0x3377d1cf, v68
	v_fmac_f32_e32 v74, 0x3f317217, v68
	v_cmp_lt_f32_e64 s[6:7], |v68|, s96
	s_nop 1
	v_cndmask_b32_e64 v68, v68, v74, s[6:7]
	v_cndmask_b32_e32 v74, 0, v244, vcc
	v_sub_f32_e32 v68, v68, v74
	v_sub_f32_e32 v68, v73, v68
	v_fmamk_f32 v118, v68, 0x3d800000, v117
	v_mov_b32_e32 v68, v219
	v_min_f32_e32 v69, 0, v68
	v_mul_f32_e64 v68, |v68|, s0
	v_exp_f32_e32 v68, v68
	s_waitcnt lgkmcnt(6)
	v_add_f32_e32 v68, 1.0, v68
	v_cmp_gt_f32_e32 vcc, s92, v68
	s_nop 1
	v_cndmask_b32_e64 v73, 0, 32, vcc
	v_ldexp_f32 v68, v68, v73
	v_log_f32_e32 v68, v68
	s_nop 0
	v_mul_f32_e32 v73, 0x3f317217, v68
	v_fma_f32 v73, v68, s3, -v73
	v_fmac_f32_e32 v73, 0x3377d1cf, v68
	v_fmac_f32_e32 v73, 0x3f317217, v68
	v_cmp_lt_f32_e64 s[6:7], |v68|, s96
	s_nop 1
	v_cndmask_b32_e64 v68, v68, v73, s[6:7]
	v_cndmask_b32_e32 v73, 0, v244, vcc
	v_sub_f32_e32 v68, v68, v73
	v_sub_f32_e32 v68, v69, v68
	v_fmamk_f32 v119, v68, 0x3d800000, v118
	v_xor_b32_e32 v249, 32, v248
	ds_read_b128 v[216:219], v249
	s_waitcnt lgkmcnt(0)
	v_mov_b32_e32 v68, v216
	v_min_f32_e32 v69, 0, v68
	v_mul_f32_e64 v68, |v68|, s0
	v_exp_f32_e32 v68, v68
	s_nop 0
	v_add_f32_e32 v68, 1.0, v68
	v_cmp_gt_f32_e32 vcc, s92, v68
	s_nop 1
	v_cndmask_b32_e64 v73, 0, 32, vcc
	v_ldexp_f32 v68, v68, v73
	v_log_f32_e32 v68, v68
	s_nop 0
	v_mul_f32_e32 v73, 0x3f317217, v68
	v_fma_f32 v73, v68, s3, -v73
	v_fmac_f32_e32 v73, 0x3377d1cf, v68
	v_fmac_f32_e32 v73, 0x3f317217, v68
	v_cmp_lt_f32_e64 s[6:7], |v68|, s96
	s_nop 1
	v_cndmask_b32_e64 v68, v68, v73, s[6:7]
	v_cndmask_b32_e32 v73, 0, v244, vcc
	v_sub_f32_e32 v68, v68, v73
	v_sub_f32_e32 v68, v69, v68
	v_fmamk_f32 v120, v68, 0x3d800000, v119
	v_mov_b32_e32 v68, v217
	v_min_f32_e32 v69, 0, v68
	v_mul_f32_e64 v68, |v68|, s0
	v_exp_f32_e32 v68, v68
	s_nop 0
	v_add_f32_e32 v68, 1.0, v68
	v_cmp_gt_f32_e32 vcc, s92, v68
	s_nop 1
	v_cndmask_b32_e64 v73, 0, 32, vcc
	v_ldexp_f32 v68, v68, v73
	v_log_f32_e32 v68, v68
	s_nop 0
	v_mul_f32_e32 v73, 0x3f317217, v68
	v_fma_f32 v73, v68, s3, -v73
	v_fmac_f32_e32 v73, 0x3377d1cf, v68
	v_fmac_f32_e32 v73, 0x3f317217, v68
	v_cmp_lt_f32_e64 s[6:7], |v68|, s96
	s_nop 1
	v_cndmask_b32_e64 v68, v68, v73, s[6:7]
	v_cndmask_b32_e32 v73, 0, v244, vcc
	v_sub_f32_e32 v68, v68, v73
	v_sub_f32_e32 v68, v69, v68
	v_fmamk_f32 v121, v68, 0x3d800000, v120
	v_mov_b32_e32 v68, v218
	v_min_f32_e32 v69, 0, v68
	v_mul_f32_e64 v68, |v68|, s0
	v_exp_f32_e32 v68, v68
	s_nop 0
	v_add_f32_e32 v68, 1.0, v68
	v_cmp_gt_f32_e32 vcc, s92, v68
	s_nop 1
	v_cndmask_b32_e64 v73, 0, 32, vcc
	v_ldexp_f32 v68, v68, v73
	v_log_f32_e32 v68, v68
	s_nop 0
	v_mul_f32_e32 v73, 0x3f317217, v68
	v_fma_f32 v73, v68, s3, -v73
	v_fmac_f32_e32 v73, 0x3377d1cf, v68
	v_fmac_f32_e32 v73, 0x3f317217, v68
	v_cmp_lt_f32_e64 s[6:7], |v68|, s96
	s_nop 1
	v_cndmask_b32_e64 v68, v68, v73, s[6:7]
	v_cndmask_b32_e32 v73, 0, v244, vcc
	v_sub_f32_e32 v68, v68, v73
	v_sub_f32_e32 v68, v69, v68
	v_fmamk_f32 v122, v68, 0x3d800000, v121
	v_mov_b32_e32 v68, v219
	v_min_f32_e32 v66, 0, v68
	v_mul_f32_e64 v68, |v68|, s0
	v_exp_f32_e32 v68, v68
	s_nop 0
	v_add_f32_e32 v68, 1.0, v68
	v_cmp_gt_f32_e32 vcc, s92, v68
	s_nop 1
	v_cndmask_b32_e64 v69, 0, 32, vcc
	v_ldexp_f32 v68, v68, v69
	v_log_f32_e32 v68, v68
	s_nop 0
	v_mul_f32_e32 v69, 0x3f317217, v68
	v_fma_f32 v69, v68, s3, -v69
	v_fmac_f32_e32 v69, 0x3377d1cf, v68
	v_fmac_f32_e32 v69, 0x3f317217, v68
	v_cmp_lt_f32_e64 s[6:7], |v68|, s96
	s_nop 1
	v_cndmask_b32_e64 v68, v68, v69, s[6:7]
	v_cndmask_b32_e32 v69, 0, v244, vcc
	v_sub_f32_e32 v68, v68, v69
	v_sub_f32_e32 v66, v66, v68
	v_fmamk_f32 v123, v66, 0x3d800000, v122
	v_xor_b32_e32 v249, 48, v248
	ds_read_b128 v[216:219], v249
	s_waitcnt lgkmcnt(0)
	v_mov_b32_e32 v66, v216
	v_min_f32_e32 v68, 0, v66
	v_mul_f32_e64 v66, |v66|, s0
	v_exp_f32_e32 v66, v66
	s_nop 0
	v_add_f32_e32 v66, 1.0, v66
	v_cmp_gt_f32_e32 vcc, s92, v66
	s_nop 1
	v_cndmask_b32_e64 v69, 0, 32, vcc
	v_ldexp_f32 v66, v66, v69
	v_log_f32_e32 v66, v66
	s_nop 0
	v_mul_f32_e32 v69, 0x3f317217, v66
	v_fma_f32 v69, v66, s3, -v69
	v_fmac_f32_e32 v69, 0x3377d1cf, v66
	v_fmac_f32_e32 v69, 0x3f317217, v66
	v_cmp_lt_f32_e64 s[6:7], |v66|, s96
	s_nop 1
	v_cndmask_b32_e64 v66, v66, v69, s[6:7]
	v_cndmask_b32_e32 v69, 0, v244, vcc
	v_sub_f32_e32 v66, v66, v69
	v_sub_f32_e32 v66, v68, v66
	v_fmamk_f32 v124, v66, 0x3d800000, v123
	v_mov_b32_e32 v66, v217
	v_min_f32_e32 v68, 0, v66
	v_mul_f32_e64 v66, |v66|, s0
	v_exp_f32_e32 v66, v66
	s_nop 0
	v_add_f32_e32 v66, 1.0, v66
	v_cmp_gt_f32_e32 vcc, s92, v66
	s_nop 1
	v_cndmask_b32_e64 v69, 0, 32, vcc
	v_ldexp_f32 v66, v66, v69
	v_log_f32_e32 v66, v66
	s_nop 0
	v_mul_f32_e32 v69, 0x3f317217, v66
	v_fma_f32 v69, v66, s3, -v69
	v_fmac_f32_e32 v69, 0x3377d1cf, v66
	v_fmac_f32_e32 v69, 0x3f317217, v66
	v_cmp_lt_f32_e64 s[6:7], |v66|, s96
	s_nop 1
	v_cndmask_b32_e64 v66, v66, v69, s[6:7]
	v_cndmask_b32_e32 v69, 0, v244, vcc
	v_sub_f32_e32 v66, v66, v69
	v_sub_f32_e32 v66, v68, v66
	v_fmamk_f32 v125, v66, 0x3d800000, v124
	v_mov_b32_e32 v66, v218
	v_min_f32_e32 v68, 0, v66
	v_mul_f32_e64 v66, |v66|, s0
	v_exp_f32_e32 v66, v66
	s_nop 0
	v_add_f32_e32 v66, 1.0, v66
	v_cmp_gt_f32_e32 vcc, s92, v66
	s_nop 1
	v_cndmask_b32_e64 v69, 0, 32, vcc
	v_ldexp_f32 v66, v66, v69
	v_log_f32_e32 v66, v66
	s_nop 0
	v_mul_f32_e32 v69, 0x3f317217, v66
	v_fma_f32 v69, v66, s3, -v69
	v_fmac_f32_e32 v69, 0x3377d1cf, v66
	v_fmac_f32_e32 v69, 0x3f317217, v66
	v_cmp_lt_f32_e64 s[6:7], |v66|, s96
	s_nop 1
	v_cndmask_b32_e64 v66, v66, v69, s[6:7]
	v_cndmask_b32_e32 v69, 0, v244, vcc
	v_sub_f32_e32 v66, v66, v69
	v_sub_f32_e32 v66, v68, v66
	v_fmamk_f32 v126, v66, 0x3d800000, v125
	v_mov_b32_e32 v66, v219
	v_min_f32_e32 v67, 0, v66
	v_mul_f32_e64 v66, |v66|, s0
	v_exp_f32_e32 v66, v66
	s_waitcnt lgkmcnt(5)
	v_add_f32_e32 v66, 1.0, v66
	v_cmp_gt_f32_e32 vcc, s92, v66
	s_nop 1
	v_cndmask_b32_e64 v68, 0, 32, vcc
	v_ldexp_f32 v66, v66, v68
	v_log_f32_e32 v66, v66
	s_nop 0
	v_mul_f32_e32 v68, 0x3f317217, v66
	v_fma_f32 v68, v66, s3, -v68
	v_fmac_f32_e32 v68, 0x3377d1cf, v66
	v_fmac_f32_e32 v68, 0x3f317217, v66
	v_cmp_lt_f32_e64 s[6:7], |v66|, s96
	s_nop 1
	v_cndmask_b32_e64 v66, v66, v68, s[6:7]
	v_cndmask_b32_e32 v68, 0, v244, vcc
	v_sub_f32_e32 v66, v66, v68
	v_sub_f32_e32 v66, v67, v66
	v_fmamk_f32 v127, v66, 0x3d800000, v126
	v_xor_b32_e32 v249, 64, v248
	ds_read_b128 v[216:219], v249
	s_waitcnt lgkmcnt(0)
	v_mov_b32_e32 v66, v216
	v_min_f32_e32 v67, 0, v66
	v_mul_f32_e64 v66, |v66|, s0
	v_exp_f32_e32 v66, v66
	s_nop 0
	v_add_f32_e32 v66, 1.0, v66
	v_cmp_gt_f32_e32 vcc, s92, v66
	s_nop 1
	v_cndmask_b32_e64 v68, 0, 32, vcc
	v_ldexp_f32 v66, v66, v68
	v_log_f32_e32 v66, v66
	s_nop 0
	v_mul_f32_e32 v68, 0x3f317217, v66
	v_fma_f32 v68, v66, s3, -v68
	v_fmac_f32_e32 v68, 0x3377d1cf, v66
	v_fmac_f32_e32 v68, 0x3f317217, v66
	v_cmp_lt_f32_e64 s[6:7], |v66|, s96
	s_nop 1
	v_cndmask_b32_e64 v66, v66, v68, s[6:7]
	v_cndmask_b32_e32 v68, 0, v244, vcc
	v_sub_f32_e32 v66, v66, v68
	v_sub_f32_e32 v66, v67, v66
	v_fmamk_f32 v128, v66, 0x3d800000, v127
	v_mov_b32_e32 v66, v217
	v_min_f32_e32 v67, 0, v66
	v_mul_f32_e64 v66, |v66|, s0
	v_exp_f32_e32 v66, v66
	s_nop 0
	v_add_f32_e32 v66, 1.0, v66
	v_cmp_gt_f32_e32 vcc, s92, v66
	s_nop 1
	v_cndmask_b32_e64 v68, 0, 32, vcc
	v_ldexp_f32 v66, v66, v68
	v_log_f32_e32 v66, v66
	s_nop 0
	v_mul_f32_e32 v68, 0x3f317217, v66
	v_fma_f32 v68, v66, s3, -v68
	v_fmac_f32_e32 v68, 0x3377d1cf, v66
	v_fmac_f32_e32 v68, 0x3f317217, v66
	v_cmp_lt_f32_e64 s[6:7], |v66|, s96
	s_nop 1
	v_cndmask_b32_e64 v66, v66, v68, s[6:7]
	v_cndmask_b32_e32 v68, 0, v244, vcc
	v_sub_f32_e32 v66, v66, v68
	v_sub_f32_e32 v66, v67, v66
	v_fmamk_f32 v91, v66, 0x3d800000, v128
	v_mov_b32_e32 v66, v218
	v_min_f32_e32 v67, 0, v66
	v_mul_f32_e64 v66, |v66|, s0
	v_exp_f32_e32 v66, v66
	s_nop 0
	v_add_f32_e32 v66, 1.0, v66
	v_cmp_gt_f32_e32 vcc, s92, v66
	s_nop 1
	v_cndmask_b32_e64 v68, 0, 32, vcc
	v_ldexp_f32 v66, v66, v68
	v_log_f32_e32 v66, v66
	s_nop 0
	v_mul_f32_e32 v68, 0x3f317217, v66
	v_fma_f32 v68, v66, s3, -v68
	v_fmac_f32_e32 v68, 0x3377d1cf, v66
	v_fmac_f32_e32 v68, 0x3f317217, v66
	v_cmp_lt_f32_e64 s[6:7], |v66|, s96
	s_nop 1
	v_cndmask_b32_e64 v66, v66, v68, s[6:7]
	v_cndmask_b32_e32 v68, 0, v244, vcc
	v_sub_f32_e32 v66, v66, v68
	v_sub_f32_e32 v66, v67, v66
	v_fmamk_f32 v93, v66, 0x3d800000, v91
	v_mov_b32_e32 v66, v219
	v_min_f32_e32 v64, 0, v66
	v_mul_f32_e64 v66, |v66|, s0
	v_exp_f32_e32 v66, v66
	s_nop 0
	v_add_f32_e32 v66, 1.0, v66
	v_cmp_gt_f32_e32 vcc, s92, v66
	s_nop 1
	v_cndmask_b32_e64 v67, 0, 32, vcc
	v_ldexp_f32 v66, v66, v67
	v_log_f32_e32 v66, v66
	s_nop 0
	v_mul_f32_e32 v67, 0x3f317217, v66
	v_fma_f32 v67, v66, s3, -v67
	v_fmac_f32_e32 v67, 0x3377d1cf, v66
	v_fmac_f32_e32 v67, 0x3f317217, v66
	v_cmp_lt_f32_e64 s[6:7], |v66|, s96
	s_nop 1
	v_cndmask_b32_e64 v66, v66, v67, s[6:7]
	v_cndmask_b32_e32 v67, 0, v244, vcc
	v_sub_f32_e32 v66, v66, v67
	v_sub_f32_e32 v64, v64, v66
	v_fmamk_f32 v95, v64, 0x3d800000, v93
	v_xor_b32_e32 v249, 0x50, v248
	ds_read_b128 v[216:219], v249
	s_waitcnt lgkmcnt(0)
	v_mov_b32_e32 v64, v216
	v_min_f32_e32 v66, 0, v64
	v_mul_f32_e64 v64, |v64|, s0
	v_exp_f32_e32 v64, v64
	s_nop 0
	v_add_f32_e32 v64, 1.0, v64
	v_cmp_gt_f32_e32 vcc, s92, v64
	s_nop 1
	v_cndmask_b32_e64 v67, 0, 32, vcc
	v_ldexp_f32 v64, v64, v67
	v_log_f32_e32 v64, v64
	s_nop 0
	v_mul_f32_e32 v67, 0x3f317217, v64
	v_fma_f32 v67, v64, s3, -v67
	v_fmac_f32_e32 v67, 0x3377d1cf, v64
	v_fmac_f32_e32 v67, 0x3f317217, v64
	v_cmp_lt_f32_e64 s[6:7], |v64|, s96
	s_nop 1
	v_cndmask_b32_e64 v64, v64, v67, s[6:7]
	v_cndmask_b32_e32 v67, 0, v244, vcc
	v_sub_f32_e32 v64, v64, v67
	v_sub_f32_e32 v64, v66, v64
	v_fmamk_f32 v97, v64, 0x3d800000, v95
	v_mov_b32_e32 v64, v217
	v_min_f32_e32 v66, 0, v64
	v_mul_f32_e64 v64, |v64|, s0
	v_exp_f32_e32 v64, v64
	s_nop 0
	v_add_f32_e32 v64, 1.0, v64
	v_cmp_gt_f32_e32 vcc, s92, v64
	s_nop 1
	v_cndmask_b32_e64 v67, 0, 32, vcc
	v_ldexp_f32 v64, v64, v67
	v_log_f32_e32 v64, v64
	s_nop 0
	v_mul_f32_e32 v67, 0x3f317217, v64
	v_fma_f32 v67, v64, s3, -v67
	v_fmac_f32_e32 v67, 0x3377d1cf, v64
	v_fmac_f32_e32 v67, 0x3f317217, v64
	v_cmp_lt_f32_e64 s[6:7], |v64|, s96
	s_nop 1
	v_cndmask_b32_e64 v64, v64, v67, s[6:7]
	v_cndmask_b32_e32 v67, 0, v244, vcc
	v_sub_f32_e32 v64, v64, v67
	v_sub_f32_e32 v64, v66, v64
	v_fmamk_f32 v100, v64, 0x3d800000, v97
	v_mov_b32_e32 v64, v218
	v_min_f32_e32 v66, 0, v64
	v_mul_f32_e64 v64, |v64|, s0
	v_exp_f32_e32 v64, v64
	s_nop 0
	v_add_f32_e32 v64, 1.0, v64
	v_cmp_gt_f32_e32 vcc, s92, v64
	s_nop 1
	v_cndmask_b32_e64 v67, 0, 32, vcc
	v_ldexp_f32 v64, v64, v67
	v_log_f32_e32 v64, v64
	s_nop 0
	v_mul_f32_e32 v67, 0x3f317217, v64
	v_fma_f32 v67, v64, s3, -v67
	v_fmac_f32_e32 v67, 0x3377d1cf, v64
	v_fmac_f32_e32 v67, 0x3f317217, v64
	v_cmp_lt_f32_e64 s[6:7], |v64|, s96
	s_nop 1
	v_cndmask_b32_e64 v64, v64, v67, s[6:7]
	v_cndmask_b32_e32 v67, 0, v244, vcc
	v_sub_f32_e32 v64, v64, v67
	v_sub_f32_e32 v64, v66, v64
	v_fmamk_f32 v101, v64, 0x3d800000, v100
	v_mov_b32_e32 v64, v219
	v_min_f32_e32 v65, 0, v64
	v_mul_f32_e64 v64, |v64|, s0
	v_exp_f32_e32 v64, v64
	s_waitcnt lgkmcnt(4)
	v_add_f32_e32 v64, 1.0, v64
	v_cmp_gt_f32_e32 vcc, s92, v64
	s_nop 1
	v_cndmask_b32_e64 v66, 0, 32, vcc
	v_ldexp_f32 v64, v64, v66
	v_log_f32_e32 v64, v64
	s_nop 0
	v_mul_f32_e32 v66, 0x3f317217, v64
	v_fma_f32 v66, v64, s3, -v66
	v_fmac_f32_e32 v66, 0x3377d1cf, v64
	v_fmac_f32_e32 v66, 0x3f317217, v64
	v_cmp_lt_f32_e64 s[6:7], |v64|, s96
	s_nop 1
	v_cndmask_b32_e64 v64, v64, v66, s[6:7]
	v_cndmask_b32_e32 v66, 0, v244, vcc
	v_sub_f32_e32 v64, v64, v66
	v_sub_f32_e32 v64, v65, v64
	v_fmamk_f32 v102, v64, 0x3d800000, v101
	v_xor_b32_e32 v249, 0x60, v248
	ds_read_b128 v[216:219], v249
	s_waitcnt lgkmcnt(0)
	v_mov_b32_e32 v64, v216
	v_min_f32_e32 v65, 0, v64
	v_mul_f32_e64 v64, |v64|, s0
	v_exp_f32_e32 v64, v64
	s_nop 0
	v_add_f32_e32 v64, 1.0, v64
	v_cmp_gt_f32_e32 vcc, s92, v64
	s_nop 1
	v_cndmask_b32_e64 v66, 0, 32, vcc
	v_ldexp_f32 v64, v64, v66
	v_log_f32_e32 v64, v64
	s_nop 0
	v_mul_f32_e32 v66, 0x3f317217, v64
	v_fma_f32 v66, v64, s3, -v66
	v_fmac_f32_e32 v66, 0x3377d1cf, v64
	v_fmac_f32_e32 v66, 0x3f317217, v64
	v_cmp_lt_f32_e64 s[6:7], |v64|, s96
	s_nop 1
	v_cndmask_b32_e64 v64, v64, v66, s[6:7]
	v_cndmask_b32_e32 v66, 0, v244, vcc
	v_sub_f32_e32 v64, v64, v66
	v_sub_f32_e32 v64, v65, v64
	v_fmamk_f32 v103, v64, 0x3d800000, v102
	v_mov_b32_e32 v64, v217
	v_min_f32_e32 v65, 0, v64
	v_mul_f32_e64 v64, |v64|, s0
	v_exp_f32_e32 v64, v64
	s_nop 0
	v_add_f32_e32 v64, 1.0, v64
	v_cmp_gt_f32_e32 vcc, s92, v64
	s_nop 1
	v_cndmask_b32_e64 v66, 0, 32, vcc
	v_ldexp_f32 v64, v64, v66
	v_log_f32_e32 v64, v64
	s_nop 0
	v_mul_f32_e32 v66, 0x3f317217, v64
	v_fma_f32 v66, v64, s3, -v66
	v_fmac_f32_e32 v66, 0x3377d1cf, v64
	v_fmac_f32_e32 v66, 0x3f317217, v64
	v_cmp_lt_f32_e64 s[6:7], |v64|, s96
	s_nop 1
	v_cndmask_b32_e64 v64, v64, v66, s[6:7]
	v_cndmask_b32_e32 v66, 0, v244, vcc
	v_sub_f32_e32 v64, v64, v66
	v_sub_f32_e32 v64, v65, v64
	v_fmamk_f32 v104, v64, 0x3d800000, v103
	v_mov_b32_e32 v64, v218
	v_min_f32_e32 v65, 0, v64
	v_mul_f32_e64 v64, |v64|, s0
	v_exp_f32_e32 v64, v64
	s_nop 0
	v_add_f32_e32 v64, 1.0, v64
	v_cmp_gt_f32_e32 vcc, s92, v64
	s_nop 1
	v_cndmask_b32_e64 v66, 0, 32, vcc
	v_ldexp_f32 v64, v64, v66
	v_log_f32_e32 v64, v64
	s_nop 0
	v_mul_f32_e32 v66, 0x3f317217, v64
	v_fma_f32 v66, v64, s3, -v66
	v_fmac_f32_e32 v66, 0x3377d1cf, v64
	v_fmac_f32_e32 v66, 0x3f317217, v64
	v_cmp_lt_f32_e64 s[6:7], |v64|, s96
	s_nop 1
	v_cndmask_b32_e64 v64, v64, v66, s[6:7]
	v_cndmask_b32_e32 v66, 0, v244, vcc
	v_sub_f32_e32 v64, v64, v66
	v_sub_f32_e32 v64, v65, v64
	v_fmamk_f32 v105, v64, 0x3d800000, v104
	v_mov_b32_e32 v64, v219
	v_min_f32_e32 v62, 0, v64
	v_mul_f32_e64 v64, |v64|, s0
	v_exp_f32_e32 v64, v64
	s_nop 0
	v_add_f32_e32 v64, 1.0, v64
	v_cmp_gt_f32_e32 vcc, s92, v64
	s_nop 1
	v_cndmask_b32_e64 v65, 0, 32, vcc
	v_ldexp_f32 v64, v64, v65
	v_log_f32_e32 v64, v64
	s_nop 0
	v_mul_f32_e32 v65, 0x3f317217, v64
	v_fma_f32 v65, v64, s3, -v65
	v_fmac_f32_e32 v65, 0x3377d1cf, v64
	v_fmac_f32_e32 v65, 0x3f317217, v64
	v_cmp_lt_f32_e64 s[6:7], |v64|, s96
	s_nop 1
	v_cndmask_b32_e64 v64, v64, v65, s[6:7]
	v_cndmask_b32_e32 v65, 0, v244, vcc
	v_sub_f32_e32 v64, v64, v65
	v_sub_f32_e32 v62, v62, v64
	v_fmamk_f32 v106, v62, 0x3d800000, v105
	v_xor_b32_e32 v249, 0x70, v248
	ds_read_b128 v[216:219], v249
	s_waitcnt lgkmcnt(0)
	v_mov_b32_e32 v62, v216
	v_min_f32_e32 v64, 0, v62
	v_mul_f32_e64 v62, |v62|, s0
	v_exp_f32_e32 v62, v62
	s_nop 0
	v_add_f32_e32 v62, 1.0, v62
	v_cmp_gt_f32_e32 vcc, s92, v62
	s_nop 1
	v_cndmask_b32_e64 v65, 0, 32, vcc
	v_ldexp_f32 v62, v62, v65
	v_log_f32_e32 v62, v62
	s_nop 0
	v_mul_f32_e32 v65, 0x3f317217, v62
	v_fma_f32 v65, v62, s3, -v65
	v_fmac_f32_e32 v65, 0x3377d1cf, v62
	v_fmac_f32_e32 v65, 0x3f317217, v62
	v_cmp_lt_f32_e64 s[6:7], |v62|, s96
	s_nop 1
	v_cndmask_b32_e64 v62, v62, v65, s[6:7]
	v_cndmask_b32_e32 v65, 0, v244, vcc
	v_sub_f32_e32 v62, v62, v65
	v_sub_f32_e32 v62, v64, v62
	v_fmamk_f32 v107, v62, 0x3d800000, v106
	v_mov_b32_e32 v62, v217
	v_min_f32_e32 v64, 0, v62
	v_mul_f32_e64 v62, |v62|, s0
	v_exp_f32_e32 v62, v62
	s_nop 0
	v_add_f32_e32 v62, 1.0, v62
	v_cmp_gt_f32_e32 vcc, s92, v62
	s_nop 1
	v_cndmask_b32_e64 v65, 0, 32, vcc
	v_ldexp_f32 v62, v62, v65
	v_log_f32_e32 v62, v62
	s_nop 0
	v_mul_f32_e32 v65, 0x3f317217, v62
	v_fma_f32 v65, v62, s3, -v65
	v_fmac_f32_e32 v65, 0x3377d1cf, v62
	v_fmac_f32_e32 v65, 0x3f317217, v62
	v_cmp_lt_f32_e64 s[6:7], |v62|, s96
	s_nop 1
	v_cndmask_b32_e64 v62, v62, v65, s[6:7]
	v_cndmask_b32_e32 v65, 0, v244, vcc
	v_sub_f32_e32 v62, v62, v65
	v_sub_f32_e32 v62, v64, v62
	v_fmamk_f32 v109, v62, 0x3d800000, v107
	v_mov_b32_e32 v62, v218
	v_min_f32_e32 v64, 0, v62
	v_mul_f32_e64 v62, |v62|, s0
	v_exp_f32_e32 v62, v62
	s_nop 0
	v_add_f32_e32 v62, 1.0, v62
	v_cmp_gt_f32_e32 vcc, s92, v62
	s_nop 1
	v_cndmask_b32_e64 v65, 0, 32, vcc
	v_ldexp_f32 v62, v62, v65
	v_log_f32_e32 v62, v62
	s_nop 0
	v_mul_f32_e32 v65, 0x3f317217, v62
	v_fma_f32 v65, v62, s3, -v65
	v_fmac_f32_e32 v65, 0x3377d1cf, v62
	v_fmac_f32_e32 v65, 0x3f317217, v62
	v_cmp_lt_f32_e64 s[6:7], |v62|, s96
	s_nop 1
	v_cndmask_b32_e64 v62, v62, v65, s[6:7]
	v_cndmask_b32_e32 v65, 0, v244, vcc
	v_sub_f32_e32 v62, v62, v65
	v_sub_f32_e32 v62, v64, v62
	v_fmamk_f32 v110, v62, 0x3d800000, v109
	v_mov_b32_e32 v62, v219
	v_min_f32_e32 v63, 0, v62
	v_mul_f32_e64 v62, |v62|, s0
	v_exp_f32_e32 v62, v62
	s_waitcnt lgkmcnt(3)
	v_add_f32_e32 v62, 1.0, v62
	v_cmp_gt_f32_e32 vcc, s92, v62
	s_nop 1
	v_cndmask_b32_e64 v64, 0, 32, vcc
	v_ldexp_f32 v62, v62, v64
	v_log_f32_e32 v62, v62
	s_nop 0
	v_mul_f32_e32 v64, 0x3f317217, v62
	v_fma_f32 v64, v62, s3, -v64
	v_fmac_f32_e32 v64, 0x3377d1cf, v62
	v_fmac_f32_e32 v64, 0x3f317217, v62
	v_cmp_lt_f32_e64 s[6:7], |v62|, s96
	s_nop 1
	v_cndmask_b32_e64 v62, v62, v64, s[6:7]
	v_cndmask_b32_e32 v64, 0, v244, vcc
	v_sub_f32_e32 v62, v62, v64
	v_sub_f32_e32 v62, v63, v62
	v_fmamk_f32 v111, v62, 0x3d800000, v110
	v_xor_b32_e32 v249, 0x80, v248
	ds_read_b128 v[216:219], v249
	s_waitcnt lgkmcnt(0)
	v_mov_b32_e32 v62, v216
	v_min_f32_e32 v63, 0, v62
	v_mul_f32_e64 v62, |v62|, s0
	v_exp_f32_e32 v62, v62
	s_nop 0
	v_add_f32_e32 v62, 1.0, v62
	v_cmp_gt_f32_e32 vcc, s92, v62
	s_nop 1
	v_cndmask_b32_e64 v64, 0, 32, vcc
	v_ldexp_f32 v62, v62, v64
	v_log_f32_e32 v62, v62
	s_nop 0
	v_mul_f32_e32 v64, 0x3f317217, v62
	v_fma_f32 v64, v62, s3, -v64
	v_fmac_f32_e32 v64, 0x3377d1cf, v62
	v_fmac_f32_e32 v64, 0x3f317217, v62
	v_cmp_lt_f32_e64 s[6:7], |v62|, s96
	s_nop 1
	v_cndmask_b32_e64 v62, v62, v64, s[6:7]
	v_cndmask_b32_e32 v64, 0, v244, vcc
	v_sub_f32_e32 v62, v62, v64
	v_sub_f32_e32 v62, v63, v62
	v_fmamk_f32 v112, v62, 0x3d800000, v111
	v_mov_b32_e32 v62, v217
	v_min_f32_e32 v63, 0, v62
	v_mul_f32_e64 v62, |v62|, s0
	v_exp_f32_e32 v62, v62
	s_nop 0
	v_add_f32_e32 v62, 1.0, v62
	v_cmp_gt_f32_e32 vcc, s92, v62
	s_nop 1
	v_cndmask_b32_e64 v64, 0, 32, vcc
	v_ldexp_f32 v62, v62, v64
	v_log_f32_e32 v62, v62
	s_nop 0
	v_mul_f32_e32 v64, 0x3f317217, v62
	v_fma_f32 v64, v62, s3, -v64
	v_fmac_f32_e32 v64, 0x3377d1cf, v62
	v_fmac_f32_e32 v64, 0x3f317217, v62
	v_cmp_lt_f32_e64 s[6:7], |v62|, s96
	s_nop 1
	v_cndmask_b32_e64 v62, v62, v64, s[6:7]
	v_cndmask_b32_e32 v64, 0, v244, vcc
	v_sub_f32_e32 v62, v62, v64
	v_sub_f32_e32 v62, v63, v62
	v_fmamk_f32 v62, v62, 0x3d800000, v112
	v_mov_b32_e32 v63, v218
	v_min_f32_e32 v64, 0, v63
	v_mul_f32_e64 v63, |v63|, s0
	v_exp_f32_e32 v63, v63
	s_nop 0
	v_add_f32_e32 v63, 1.0, v63
	v_cmp_gt_f32_e32 vcc, s92, v63
	s_nop 1
	v_cndmask_b32_e64 v65, 0, 32, vcc
	v_ldexp_f32 v63, v63, v65
	v_log_f32_e32 v63, v63
	s_nop 0
	v_mul_f32_e32 v65, 0x3f317217, v63
	v_fma_f32 v65, v63, s3, -v65
	v_fmac_f32_e32 v65, 0x3377d1cf, v63
	v_fmac_f32_e32 v65, 0x3f317217, v63
	v_cmp_lt_f32_e64 s[6:7], |v63|, s96
	s_nop 1
	v_cndmask_b32_e64 v63, v63, v65, s[6:7]
	v_cndmask_b32_e32 v65, 0, v244, vcc
	v_sub_f32_e32 v63, v63, v65
	v_sub_f32_e32 v63, v64, v63
	v_fmamk_f32 v63, v63, 0x3d800000, v62
	v_mov_b32_e32 v64, v219
	v_min_f32_e32 v60, 0, v64
	v_mul_f32_e64 v64, |v64|, s0
	v_exp_f32_e32 v64, v64
	s_nop 0
	v_add_f32_e32 v64, 1.0, v64
	v_cmp_gt_f32_e32 vcc, s92, v64
	s_nop 1
	v_cndmask_b32_e64 v65, 0, 32, vcc
	v_ldexp_f32 v64, v64, v65
	v_log_f32_e32 v64, v64
	s_nop 0
	v_mul_f32_e32 v65, 0x3f317217, v64
	v_fma_f32 v65, v64, s3, -v65
	v_fmac_f32_e32 v65, 0x3377d1cf, v64
	v_fmac_f32_e32 v65, 0x3f317217, v64
	v_cmp_lt_f32_e64 s[6:7], |v64|, s96
	s_nop 1
	v_cndmask_b32_e64 v64, v64, v65, s[6:7]
	v_cndmask_b32_e32 v65, 0, v244, vcc
	v_sub_f32_e32 v64, v64, v65
	v_sub_f32_e32 v60, v60, v64
	v_fmamk_f32 v64, v60, 0x3d800000, v63
	v_xor_b32_e32 v249, 0x90, v248
	ds_read_b128 v[216:219], v249
	s_waitcnt lgkmcnt(0)
	v_mov_b32_e32 v60, v216
	v_min_f32_e32 v65, 0, v60
	v_mul_f32_e64 v60, |v60|, s0
	v_exp_f32_e32 v60, v60
	s_nop 0
	v_add_f32_e32 v60, 1.0, v60
	v_cmp_gt_f32_e32 vcc, s92, v60
	s_nop 1
	v_cndmask_b32_e64 v66, 0, 32, vcc
	v_ldexp_f32 v60, v60, v66
	v_log_f32_e32 v60, v60
	s_nop 0
	v_mul_f32_e32 v66, 0x3f317217, v60
	v_fma_f32 v66, v60, s3, -v66
	v_fmac_f32_e32 v66, 0x3377d1cf, v60
	v_fmac_f32_e32 v66, 0x3f317217, v60
	v_cmp_lt_f32_e64 s[6:7], |v60|, s96
	s_nop 1
	v_cndmask_b32_e64 v60, v60, v66, s[6:7]
	v_cndmask_b32_e32 v66, 0, v244, vcc
	v_sub_f32_e32 v60, v60, v66
	v_sub_f32_e32 v60, v65, v60
	v_fmamk_f32 v65, v60, 0x3d800000, v64
	v_mov_b32_e32 v60, v217
	v_min_f32_e32 v66, 0, v60
	v_mul_f32_e64 v60, |v60|, s0
	v_exp_f32_e32 v60, v60
	s_nop 0
	v_add_f32_e32 v60, 1.0, v60
	v_cmp_gt_f32_e32 vcc, s92, v60
	s_nop 1
	v_cndmask_b32_e64 v67, 0, 32, vcc
	v_ldexp_f32 v60, v60, v67
	v_log_f32_e32 v60, v60
	s_nop 0
	v_mul_f32_e32 v67, 0x3f317217, v60
	v_fma_f32 v67, v60, s3, -v67
	v_fmac_f32_e32 v67, 0x3377d1cf, v60
	v_fmac_f32_e32 v67, 0x3f317217, v60
	v_cmp_lt_f32_e64 s[6:7], |v60|, s96
	s_nop 1
	v_cndmask_b32_e64 v60, v60, v67, s[6:7]
	v_cndmask_b32_e32 v67, 0, v244, vcc
	v_sub_f32_e32 v60, v60, v67
	v_sub_f32_e32 v60, v66, v60
	v_fmamk_f32 v66, v60, 0x3d800000, v65
	v_mov_b32_e32 v60, v218
	v_min_f32_e32 v67, 0, v60
	v_mul_f32_e64 v60, |v60|, s0
	v_exp_f32_e32 v60, v60
	s_nop 0
	v_add_f32_e32 v60, 1.0, v60
	v_cmp_gt_f32_e32 vcc, s92, v60
	s_nop 1
	v_cndmask_b32_e64 v68, 0, 32, vcc
	v_ldexp_f32 v60, v60, v68
	v_log_f32_e32 v60, v60
	s_nop 0
	v_mul_f32_e32 v68, 0x3f317217, v60
	v_fma_f32 v68, v60, s3, -v68
	v_fmac_f32_e32 v68, 0x3377d1cf, v60
	v_fmac_f32_e32 v68, 0x3f317217, v60
	v_cmp_lt_f32_e64 s[6:7], |v60|, s96
	s_nop 1
	v_cndmask_b32_e64 v60, v60, v68, s[6:7]
	v_cndmask_b32_e32 v68, 0, v244, vcc
	v_sub_f32_e32 v60, v60, v68
	v_sub_f32_e32 v60, v67, v60
	v_fmamk_f32 v67, v60, 0x3d800000, v66
	v_mov_b32_e32 v60, v219
	v_min_f32_e32 v61, 0, v60
	v_mul_f32_e64 v60, |v60|, s0
	v_exp_f32_e32 v60, v60
	s_waitcnt lgkmcnt(2)
	v_add_f32_e32 v60, 1.0, v60
	v_cmp_gt_f32_e32 vcc, s92, v60
	s_nop 1
	v_cndmask_b32_e64 v68, 0, 32, vcc
	v_ldexp_f32 v60, v60, v68
	v_log_f32_e32 v60, v60
	s_nop 0
	v_mul_f32_e32 v68, 0x3f317217, v60
	v_fma_f32 v68, v60, s3, -v68
	v_fmac_f32_e32 v68, 0x3377d1cf, v60
	v_fmac_f32_e32 v68, 0x3f317217, v60
	v_cmp_lt_f32_e64 s[6:7], |v60|, s96
	s_nop 1
	v_cndmask_b32_e64 v60, v60, v68, s[6:7]
	v_cndmask_b32_e32 v68, 0, v244, vcc
	v_sub_f32_e32 v60, v60, v68
	v_sub_f32_e32 v60, v61, v60
	v_fmamk_f32 v61, v60, 0x3d800000, v67
	v_xor_b32_e32 v249, 0xa0, v248
	ds_read_b128 v[216:219], v249
	s_waitcnt lgkmcnt(0)
	v_mov_b32_e32 v60, v216
	v_min_f32_e32 v68, 0, v60
	v_mul_f32_e64 v60, |v60|, s0
	v_exp_f32_e32 v60, v60
	s_nop 0
	v_add_f32_e32 v60, 1.0, v60
	v_cmp_gt_f32_e32 vcc, s92, v60
	s_nop 1
	v_cndmask_b32_e64 v69, 0, 32, vcc
	v_ldexp_f32 v60, v60, v69
	v_log_f32_e32 v60, v60
	s_nop 0
	v_mul_f32_e32 v69, 0x3f317217, v60
	v_fma_f32 v69, v60, s3, -v69
	v_fmac_f32_e32 v69, 0x3377d1cf, v60
	v_fmac_f32_e32 v69, 0x3f317217, v60
	v_cmp_lt_f32_e64 s[6:7], |v60|, s96
	s_nop 1
	v_cndmask_b32_e64 v60, v60, v69, s[6:7]
	v_cndmask_b32_e32 v69, 0, v244, vcc
	v_sub_f32_e32 v60, v60, v69
	v_sub_f32_e32 v60, v68, v60
	v_fmamk_f32 v68, v60, 0x3d800000, v61
	v_mov_b32_e32 v60, v217
	v_min_f32_e32 v69, 0, v60
	v_mul_f32_e64 v60, |v60|, s0
	v_exp_f32_e32 v60, v60
	s_nop 0
	v_add_f32_e32 v60, 1.0, v60
	v_cmp_gt_f32_e32 vcc, s92, v60
	s_nop 1
	v_cndmask_b32_e64 v73, 0, 32, vcc
	v_ldexp_f32 v60, v60, v73
	v_log_f32_e32 v60, v60
	s_nop 0
	v_mul_f32_e32 v73, 0x3f317217, v60
	v_fma_f32 v73, v60, s3, -v73
	v_fmac_f32_e32 v73, 0x3377d1cf, v60
	v_fmac_f32_e32 v73, 0x3f317217, v60
	v_cmp_lt_f32_e64 s[6:7], |v60|, s96
	s_nop 1
	v_cndmask_b32_e64 v60, v60, v73, s[6:7]
	v_cndmask_b32_e32 v73, 0, v244, vcc
	v_sub_f32_e32 v60, v60, v73
	v_sub_f32_e32 v60, v69, v60
	v_fmamk_f32 v69, v60, 0x3d800000, v68
	v_mov_b32_e32 v60, v218
	v_min_f32_e32 v73, 0, v60
	v_mul_f32_e64 v60, |v60|, s0
	v_exp_f32_e32 v60, v60
	s_nop 0
	v_add_f32_e32 v60, 1.0, v60
	v_cmp_gt_f32_e32 vcc, s92, v60
	s_nop 1
	v_cndmask_b32_e64 v74, 0, 32, vcc
	v_ldexp_f32 v60, v60, v74
	v_log_f32_e32 v60, v60
	s_nop 0
	v_mul_f32_e32 v74, 0x3f317217, v60
	v_fma_f32 v74, v60, s3, -v74
	v_fmac_f32_e32 v74, 0x3377d1cf, v60
	v_fmac_f32_e32 v74, 0x3f317217, v60
	v_cmp_lt_f32_e64 s[6:7], |v60|, s96
	s_nop 1
	v_cndmask_b32_e64 v60, v60, v74, s[6:7]
	v_cndmask_b32_e32 v74, 0, v244, vcc
	v_sub_f32_e32 v60, v60, v74
	v_sub_f32_e32 v60, v73, v60
	v_fmamk_f32 v73, v60, 0x3d800000, v69
	v_mov_b32_e32 v60, v219
	v_min_f32_e32 v58, 0, v60
	v_mul_f32_e64 v60, |v60|, s0
	v_exp_f32_e32 v60, v60
	s_nop 0
	v_add_f32_e32 v60, 1.0, v60
	v_cmp_gt_f32_e32 vcc, s92, v60
	s_nop 1
	v_cndmask_b32_e64 v74, 0, 32, vcc
	v_ldexp_f32 v60, v60, v74
	v_log_f32_e32 v60, v60
	s_nop 0
	v_mul_f32_e32 v74, 0x3f317217, v60
	v_fma_f32 v74, v60, s3, -v74
	v_fmac_f32_e32 v74, 0x3377d1cf, v60
	v_fmac_f32_e32 v74, 0x3f317217, v60
	v_cmp_lt_f32_e64 s[6:7], |v60|, s96
	s_nop 1
	v_cndmask_b32_e64 v60, v60, v74, s[6:7]
	v_cndmask_b32_e32 v74, 0, v244, vcc
	v_sub_f32_e32 v60, v60, v74
	v_sub_f32_e32 v58, v58, v60
	v_fmamk_f32 v74, v58, 0x3d800000, v73
	v_xor_b32_e32 v249, 0xb0, v248
	ds_read_b128 v[216:219], v249
	s_waitcnt lgkmcnt(0)
	v_mov_b32_e32 v58, v216
	v_min_f32_e32 v60, 0, v58
	v_mul_f32_e64 v58, |v58|, s0
	v_exp_f32_e32 v58, v58
	s_nop 0
	v_add_f32_e32 v58, 1.0, v58
	v_cmp_gt_f32_e32 vcc, s92, v58
	s_nop 1
	v_cndmask_b32_e64 v75, 0, 32, vcc
	v_ldexp_f32 v58, v58, v75
	v_log_f32_e32 v58, v58
	s_nop 0
	v_mul_f32_e32 v75, 0x3f317217, v58
	v_fma_f32 v75, v58, s3, -v75
	v_fmac_f32_e32 v75, 0x3377d1cf, v58
	v_fmac_f32_e32 v75, 0x3f317217, v58
	v_cmp_lt_f32_e64 s[6:7], |v58|, s96
	s_nop 1
	v_cndmask_b32_e64 v58, v58, v75, s[6:7]
	v_cndmask_b32_e32 v75, 0, v244, vcc
	v_sub_f32_e32 v58, v58, v75
	v_sub_f32_e32 v58, v60, v58
	v_fmamk_f32 v75, v58, 0x3d800000, v74
	v_mov_b32_e32 v58, v217
	v_min_f32_e32 v60, 0, v58
	v_mul_f32_e64 v58, |v58|, s0
	v_exp_f32_e32 v58, v58
	s_nop 0
	v_add_f32_e32 v58, 1.0, v58
	v_cmp_gt_f32_e32 vcc, s92, v58
	s_nop 1
	v_cndmask_b32_e64 v76, 0, 32, vcc
	v_ldexp_f32 v58, v58, v76
	v_log_f32_e32 v58, v58
	s_nop 0
	v_mul_f32_e32 v76, 0x3f317217, v58
	v_fma_f32 v76, v58, s3, -v76
	v_fmac_f32_e32 v76, 0x3377d1cf, v58
	v_fmac_f32_e32 v76, 0x3f317217, v58
	v_cmp_lt_f32_e64 s[6:7], |v58|, s96
	s_nop 1
	v_cndmask_b32_e64 v58, v58, v76, s[6:7]
	v_cndmask_b32_e32 v76, 0, v244, vcc
	v_sub_f32_e32 v58, v58, v76
	v_sub_f32_e32 v58, v60, v58
	v_fmamk_f32 v76, v58, 0x3d800000, v75
	v_mov_b32_e32 v58, v218
	v_min_f32_e32 v60, 0, v58
	v_mul_f32_e64 v58, |v58|, s0
	v_exp_f32_e32 v58, v58
	s_nop 0
	v_add_f32_e32 v58, 1.0, v58
	v_cmp_gt_f32_e32 vcc, s92, v58
	s_nop 1
	v_cndmask_b32_e64 v77, 0, 32, vcc
	v_ldexp_f32 v58, v58, v77
	v_log_f32_e32 v58, v58
	s_nop 0
	v_mul_f32_e32 v77, 0x3f317217, v58
	v_fma_f32 v77, v58, s3, -v77
	v_fmac_f32_e32 v77, 0x3377d1cf, v58
	v_fmac_f32_e32 v77, 0x3f317217, v58
	v_cmp_lt_f32_e64 s[6:7], |v58|, s96
	s_nop 1
	v_cndmask_b32_e64 v58, v58, v77, s[6:7]
	v_cndmask_b32_e32 v77, 0, v244, vcc
	v_sub_f32_e32 v58, v58, v77
	v_sub_f32_e32 v58, v60, v58
	v_fmamk_f32 v77, v58, 0x3d800000, v76
	v_mov_b32_e32 v58, v219
	v_min_f32_e32 v59, 0, v58
	v_mul_f32_e64 v58, |v58|, s0
	v_exp_f32_e32 v58, v58
	s_waitcnt lgkmcnt(1)
	v_add_f32_e32 v58, 1.0, v58
	v_cmp_gt_f32_e32 vcc, s92, v58
	s_nop 1
	v_cndmask_b32_e64 v60, 0, 32, vcc
	v_ldexp_f32 v58, v58, v60
	v_log_f32_e32 v58, v58
	s_nop 0
	v_mul_f32_e32 v60, 0x3f317217, v58
	v_fma_f32 v60, v58, s3, -v60
	v_fmac_f32_e32 v60, 0x3377d1cf, v58
	v_fmac_f32_e32 v60, 0x3f317217, v58
	v_cmp_lt_f32_e64 s[6:7], |v58|, s96
	s_nop 1
	v_cndmask_b32_e64 v58, v58, v60, s[6:7]
	v_cndmask_b32_e32 v60, 0, v244, vcc
	v_sub_f32_e32 v58, v58, v60
	v_sub_f32_e32 v58, v59, v58
	v_fmamk_f32 v78, v58, 0x3d800000, v77
	v_xor_b32_e32 v249, 0xc0, v248
	ds_read_b128 v[216:219], v249
	s_waitcnt lgkmcnt(0)
	v_mov_b32_e32 v58, v216
	v_min_f32_e32 v59, 0, v58
	v_mul_f32_e64 v58, |v58|, s0
	v_exp_f32_e32 v58, v58
	s_nop 0
	v_add_f32_e32 v58, 1.0, v58
	v_cmp_gt_f32_e32 vcc, s92, v58
	s_nop 1
	v_cndmask_b32_e64 v60, 0, 32, vcc
	v_ldexp_f32 v58, v58, v60
	v_log_f32_e32 v58, v58
	s_nop 0
	v_mul_f32_e32 v60, 0x3f317217, v58
	v_fma_f32 v60, v58, s3, -v60
	v_fmac_f32_e32 v60, 0x3377d1cf, v58
	v_fmac_f32_e32 v60, 0x3f317217, v58
	v_cmp_lt_f32_e64 s[6:7], |v58|, s96
	s_nop 1
	v_cndmask_b32_e64 v58, v58, v60, s[6:7]
	v_cndmask_b32_e32 v60, 0, v244, vcc
	v_sub_f32_e32 v58, v58, v60
	v_sub_f32_e32 v58, v59, v58
	v_fmamk_f32 v79, v58, 0x3d800000, v78
	v_mov_b32_e32 v58, v217
	v_min_f32_e32 v59, 0, v58
	v_mul_f32_e64 v58, |v58|, s0
	v_exp_f32_e32 v58, v58
	s_nop 0
	v_add_f32_e32 v58, 1.0, v58
	v_cmp_gt_f32_e32 vcc, s92, v58
	s_nop 1
	v_cndmask_b32_e64 v60, 0, 32, vcc
	v_ldexp_f32 v58, v58, v60
	v_log_f32_e32 v58, v58
	s_nop 0
	v_mul_f32_e32 v60, 0x3f317217, v58
	v_fma_f32 v60, v58, s3, -v60
	v_fmac_f32_e32 v60, 0x3377d1cf, v58
	v_fmac_f32_e32 v60, 0x3f317217, v58
	v_cmp_lt_f32_e64 s[6:7], |v58|, s96
	s_nop 1
	v_cndmask_b32_e64 v58, v58, v60, s[6:7]
	v_cndmask_b32_e32 v60, 0, v244, vcc
	v_sub_f32_e32 v58, v58, v60
	v_sub_f32_e32 v58, v59, v58
	v_fmamk_f32 v80, v58, 0x3d800000, v79
	v_mov_b32_e32 v58, v218
	v_min_f32_e32 v59, 0, v58
	v_mul_f32_e64 v58, |v58|, s0
	v_exp_f32_e32 v58, v58
	s_nop 0
	v_add_f32_e32 v58, 1.0, v58
	v_cmp_gt_f32_e32 vcc, s92, v58
	s_nop 1
	v_cndmask_b32_e64 v60, 0, 32, vcc
	v_ldexp_f32 v58, v58, v60
	v_log_f32_e32 v58, v58
	s_nop 0
	v_mul_f32_e32 v60, 0x3f317217, v58
	v_fma_f32 v60, v58, s3, -v60
	v_fmac_f32_e32 v60, 0x3377d1cf, v58
	v_fmac_f32_e32 v60, 0x3f317217, v58
	v_cmp_lt_f32_e64 s[6:7], |v58|, s96
	s_nop 1
	v_cndmask_b32_e64 v58, v58, v60, s[6:7]
	v_cndmask_b32_e32 v60, 0, v244, vcc
	v_sub_f32_e32 v58, v58, v60
	v_sub_f32_e32 v58, v59, v58
	v_fmamk_f32 v81, v58, 0x3d800000, v80
	v_bfe_u32 v60, v108, 4, 2
	v_mov_b32_e32 v58, v219
	v_min_f32_e32 v56, 0, v58
	v_mul_f32_e64 v58, |v58|, s0
	v_exp_f32_e32 v58, v58
	s_nop 0
	v_add_f32_e32 v58, 1.0, v58
	v_cmp_gt_f32_e32 vcc, s92, v58
	s_nop 1
	v_cndmask_b32_e64 v59, 0, 32, vcc
	v_ldexp_f32 v58, v58, v59
	v_log_f32_e32 v58, v58
	s_nop 0
	v_mul_f32_e32 v59, 0x3f317217, v58
	v_fma_f32 v59, v58, s3, -v59
	v_fmac_f32_e32 v59, 0x3377d1cf, v58
	v_fmac_f32_e32 v59, 0x3f317217, v58
	v_cmp_lt_f32_e64 s[6:7], |v58|, s96
	s_nop 1
	v_cndmask_b32_e64 v58, v58, v59, s[6:7]
	v_cndmask_b32_e32 v59, 0, v244, vcc
	v_sub_f32_e32 v58, v58, v59
	v_sub_f32_e32 v56, v56, v58
	v_fmamk_f32 v82, v56, 0x3d800000, v81
	v_xor_b32_e32 v249, 0xd0, v248
	ds_read_b128 v[216:219], v249
	s_waitcnt lgkmcnt(0)
	v_mov_b32_e32 v56, v216
	v_min_f32_e32 v58, 0, v56
	v_mul_f32_e64 v56, |v56|, s0
	v_exp_f32_e32 v56, v56
	s_nop 0
	v_add_f32_e32 v56, 1.0, v56
	v_cmp_gt_f32_e32 vcc, s92, v56
	s_nop 1
	v_cndmask_b32_e64 v59, 0, 32, vcc
	v_ldexp_f32 v56, v56, v59
	v_log_f32_e32 v56, v56
	s_nop 0
	v_mul_f32_e32 v59, 0x3f317217, v56
	v_fma_f32 v59, v56, s3, -v59
	v_fmac_f32_e32 v59, 0x3377d1cf, v56
	v_fmac_f32_e32 v59, 0x3f317217, v56
	v_cmp_lt_f32_e64 s[6:7], |v56|, s96
	s_nop 1
	v_cndmask_b32_e64 v56, v56, v59, s[6:7]
	v_cndmask_b32_e32 v59, 0, v244, vcc
	v_sub_f32_e32 v56, v56, v59
	v_sub_f32_e32 v56, v58, v56
	v_fmamk_f32 v83, v56, 0x3d800000, v82
	v_mov_b32_e32 v56, v217
	v_min_f32_e32 v58, 0, v56
	v_mul_f32_e64 v56, |v56|, s0
	v_exp_f32_e32 v56, v56
	s_nop 0
	v_add_f32_e32 v56, 1.0, v56
	v_cmp_gt_f32_e32 vcc, s92, v56
	s_nop 1
	v_cndmask_b32_e64 v59, 0, 32, vcc
	v_ldexp_f32 v56, v56, v59
	v_log_f32_e32 v56, v56
	s_nop 0
	v_mul_f32_e32 v59, 0x3f317217, v56
	v_fma_f32 v59, v56, s3, -v59
	v_fmac_f32_e32 v59, 0x3377d1cf, v56
	v_fmac_f32_e32 v59, 0x3f317217, v56
	v_cmp_lt_f32_e64 s[6:7], |v56|, s96
	s_nop 1
	v_cndmask_b32_e64 v56, v56, v59, s[6:7]
	v_cndmask_b32_e32 v59, 0, v244, vcc
	v_sub_f32_e32 v56, v56, v59
	v_sub_f32_e32 v56, v58, v56
	v_fmamk_f32 v84, v56, 0x3d800000, v83
	v_mov_b32_e32 v56, v218
	v_min_f32_e32 v58, 0, v56
	v_mul_f32_e64 v56, |v56|, s0
	v_exp_f32_e32 v56, v56
	s_nop 0
	v_add_f32_e32 v56, 1.0, v56
	v_cmp_gt_f32_e32 vcc, s92, v56
	s_nop 1
	v_cndmask_b32_e64 v59, 0, 32, vcc
	v_ldexp_f32 v56, v56, v59
	v_log_f32_e32 v56, v56
	s_nop 0
	v_mul_f32_e32 v59, 0x3f317217, v56
	v_fma_f32 v59, v56, s3, -v59
	v_fmac_f32_e32 v59, 0x3377d1cf, v56
	v_fmac_f32_e32 v59, 0x3f317217, v56
	v_cmp_lt_f32_e64 s[6:7], |v56|, s96
	s_nop 1
	v_cndmask_b32_e64 v56, v56, v59, s[6:7]
	v_cndmask_b32_e32 v59, 0, v244, vcc
	v_sub_f32_e32 v56, v56, v59
	v_sub_f32_e32 v56, v58, v56
	v_fmamk_f32 v85, v56, 0x3d800000, v84
	v_mov_b32_e32 v56, v219
	v_min_f32_e32 v57, 0, v56
	v_mul_f32_e64 v56, |v56|, s0
	v_exp_f32_e32 v56, v56
	s_waitcnt lgkmcnt(0)
	v_add_f32_e32 v56, 1.0, v56
	v_cmp_gt_f32_e32 vcc, s92, v56
	s_nop 1
	v_cndmask_b32_e64 v58, 0, 32, vcc
	v_ldexp_f32 v56, v56, v58
	v_log_f32_e32 v56, v56
	s_nop 0
	v_mul_f32_e32 v58, 0x3f317217, v56
	v_fma_f32 v58, v56, s3, -v58
	v_fmac_f32_e32 v58, 0x3377d1cf, v56
	v_fmac_f32_e32 v58, 0x3f317217, v56
	v_cmp_lt_f32_e64 s[6:7], |v56|, s96
	s_nop 1
	v_cndmask_b32_e64 v56, v56, v58, s[6:7]
	v_cndmask_b32_e32 v58, 0, v244, vcc
	v_sub_f32_e32 v56, v56, v58
	v_sub_f32_e32 v56, v57, v56
	v_fmamk_f32 v86, v56, 0x3d800000, v85
	v_xor_b32_e32 v249, 0xe0, v248
	ds_read_b128 v[216:219], v249
	s_waitcnt lgkmcnt(0)
	v_mov_b32_e32 v56, v216
	v_min_f32_e32 v57, 0, v56
	v_mul_f32_e64 v56, |v56|, s0
	v_exp_f32_e32 v56, v56
	s_nop 0
	v_add_f32_e32 v56, 1.0, v56
	v_cmp_gt_f32_e32 vcc, s92, v56
	s_nop 1
	v_cndmask_b32_e64 v58, 0, 32, vcc
	v_ldexp_f32 v56, v56, v58
	v_log_f32_e32 v56, v56
	s_nop 0
	v_mul_f32_e32 v58, 0x3f317217, v56
	v_fma_f32 v58, v56, s3, -v58
	v_fmac_f32_e32 v58, 0x3377d1cf, v56
	v_fmac_f32_e32 v58, 0x3f317217, v56
	v_cmp_lt_f32_e64 s[6:7], |v56|, s96
	s_nop 1
	v_cndmask_b32_e64 v56, v56, v58, s[6:7]
	v_cndmask_b32_e32 v58, 0, v244, vcc
	v_sub_f32_e32 v56, v56, v58
	v_sub_f32_e32 v56, v57, v56
	v_fmamk_f32 v87, v56, 0x3d800000, v86
	v_mov_b32_e32 v56, v217
	v_min_f32_e32 v57, 0, v56
	v_mul_f32_e64 v56, |v56|, s0
	v_exp_f32_e32 v56, v56
	s_nop 0
	v_add_f32_e32 v56, 1.0, v56
	v_cmp_gt_f32_e32 vcc, s92, v56
	s_nop 1
	v_cndmask_b32_e64 v58, 0, 32, vcc
	v_ldexp_f32 v56, v56, v58
	v_log_f32_e32 v56, v56
	s_nop 0
	v_mul_f32_e32 v58, 0x3f317217, v56
	v_fma_f32 v58, v56, s3, -v58
	v_fmac_f32_e32 v58, 0x3377d1cf, v56
	v_fmac_f32_e32 v58, 0x3f317217, v56
	v_cmp_lt_f32_e64 s[6:7], |v56|, s96
	s_nop 1
	v_cndmask_b32_e64 v56, v56, v58, s[6:7]
	v_cndmask_b32_e32 v58, 0, v244, vcc
	v_sub_f32_e32 v56, v56, v58
	v_sub_f32_e32 v56, v57, v56
	v_fmamk_f32 v88, v56, 0x3d800000, v87
	v_mov_b32_e32 v56, v218
	v_min_f32_e32 v57, 0, v56
	v_mul_f32_e64 v56, |v56|, s0
	v_exp_f32_e32 v56, v56
	s_nop 0
	v_add_f32_e32 v56, 1.0, v56
	v_cmp_gt_f32_e32 vcc, s92, v56
	s_nop 1
	v_cndmask_b32_e64 v58, 0, 32, vcc
	v_ldexp_f32 v56, v56, v58
	v_log_f32_e32 v56, v56
	s_nop 0
	v_mul_f32_e32 v58, 0x3f317217, v56
	v_fma_f32 v58, v56, s3, -v58
	v_fmac_f32_e32 v58, 0x3377d1cf, v56
	v_fmac_f32_e32 v58, 0x3f317217, v56
	v_cmp_lt_f32_e64 s[6:7], |v56|, s96
	s_nop 1
	v_cndmask_b32_e64 v56, v56, v58, s[6:7]
	v_cndmask_b32_e32 v58, 0, v244, vcc
	v_sub_f32_e32 v56, v56, v58
	v_sub_f32_e32 v56, v57, v56
	v_fmamk_f32 v89, v56, 0x3d800000, v88
	v_mov_b32_e32 v56, v219
	v_min_f32_e32 v54, 0, v56
	v_mul_f32_e64 v56, |v56|, s0
	v_exp_f32_e32 v56, v56
	s_nop 0
	v_add_f32_e32 v56, 1.0, v56
	v_cmp_gt_f32_e32 vcc, s92, v56
	s_nop 1
	v_cndmask_b32_e64 v57, 0, 32, vcc
	v_ldexp_f32 v56, v56, v57
	v_log_f32_e32 v56, v56
	s_nop 0
	v_mul_f32_e32 v57, 0x3f317217, v56
	v_fma_f32 v57, v56, s3, -v57
	v_fmac_f32_e32 v57, 0x3377d1cf, v56
	v_fmac_f32_e32 v57, 0x3f317217, v56
	v_cmp_lt_f32_e64 s[6:7], |v56|, s96
	s_nop 1
	v_cndmask_b32_e64 v56, v56, v57, s[6:7]
	v_cndmask_b32_e32 v57, 0, v244, vcc
	v_sub_f32_e32 v56, v56, v57
	v_sub_f32_e32 v54, v54, v56
	v_fmamk_f32 v90, v54, 0x3d800000, v89
	v_xor_b32_e32 v249, 0xf0, v248
	ds_read_b128 v[216:219], v249
	s_waitcnt lgkmcnt(0)
	v_mov_b32_e32 v54, v216
	v_min_f32_e32 v56, 0, v54
	v_mul_f32_e64 v54, |v54|, s0
	v_exp_f32_e32 v54, v54
	s_nop 0
	v_add_f32_e32 v54, 1.0, v54
	v_cmp_gt_f32_e32 vcc, s92, v54
	s_nop 1
	v_cndmask_b32_e64 v57, 0, 32, vcc
	v_ldexp_f32 v54, v54, v57
	v_log_f32_e32 v54, v54
	s_nop 0
	v_mul_f32_e32 v57, 0x3f317217, v54
	v_fma_f32 v57, v54, s3, -v57
	v_fmac_f32_e32 v57, 0x3377d1cf, v54
	v_fmac_f32_e32 v57, 0x3f317217, v54
	v_cmp_lt_f32_e64 s[6:7], |v54|, s96
	s_nop 1
	v_cndmask_b32_e64 v54, v54, v57, s[6:7]
	v_cndmask_b32_e32 v57, 0, v244, vcc
	v_sub_f32_e32 v54, v54, v57
	v_sub_f32_e32 v54, v56, v54
	v_fmamk_f32 v92, v54, 0x3d800000, v90
	v_mov_b32_e32 v54, v217
	v_min_f32_e32 v56, 0, v54
	v_mul_f32_e64 v54, |v54|, s0
	v_exp_f32_e32 v54, v54
	s_nop 0
	v_add_f32_e32 v54, 1.0, v54
	v_cmp_gt_f32_e32 vcc, s92, v54
	s_nop 1
	v_cndmask_b32_e64 v57, 0, 32, vcc
	v_ldexp_f32 v54, v54, v57
	v_log_f32_e32 v54, v54
	s_nop 0
	v_mul_f32_e32 v57, 0x3f317217, v54
	v_fma_f32 v57, v54, s3, -v57
	v_fmac_f32_e32 v57, 0x3377d1cf, v54
	v_fmac_f32_e32 v57, 0x3f317217, v54
	v_cmp_lt_f32_e64 s[6:7], |v54|, s96
	s_nop 1
	v_cndmask_b32_e64 v54, v54, v57, s[6:7]
	v_cndmask_b32_e32 v57, 0, v244, vcc
	v_sub_f32_e32 v54, v54, v57
	v_sub_f32_e32 v54, v56, v54
	v_fmamk_f32 v94, v54, 0x3d800000, v92
	v_mov_b32_e32 v54, v218
	v_min_f32_e32 v56, 0, v54
	v_mul_f32_e64 v54, |v54|, s0
	v_exp_f32_e32 v54, v54
	s_nop 0
	v_add_f32_e32 v54, 1.0, v54
	v_cmp_gt_f32_e32 vcc, s92, v54
	s_nop 1
	v_cndmask_b32_e64 v57, 0, 32, vcc
	v_ldexp_f32 v54, v54, v57
	v_log_f32_e32 v54, v54
	s_nop 0
	v_mul_f32_e32 v57, 0x3f317217, v54
	v_fma_f32 v57, v54, s3, -v57
	v_fmac_f32_e32 v57, 0x3377d1cf, v54
	v_fmac_f32_e32 v57, 0x3f317217, v54
	v_cmp_lt_f32_e64 s[6:7], |v54|, s96
	v_mul_f32_e32 v134, 0x3fb8aa3b, v129
	s_nop 0
	v_cndmask_b32_e64 v54, v54, v57, s[6:7]
	v_cndmask_b32_e32 v57, 0, v244, vcc
	v_sub_f32_e32 v54, v54, v57
	v_sub_f32_e32 v54, v56, v54
	v_fmamk_f32 v96, v54, 0x3d800000, v94
	v_mul_f32_e32 v129, 0xbfb8aa3b, v129
	v_exp_f32_e32 v129, v129
	v_exp_f32_e32 v134, v134
	v_mov_b32_e32 v144, v219
	v_mul_f32_e64 v55, |v144|, s0
	v_exp_f32_e32 v55, v55
	v_min_f32_e32 v54, 0, v144
	s_mul_hi_i32 s4, s8, 6
	v_add_f32_e32 v55, 1.0, v55
	v_cmp_gt_f32_e32 vcc, s92, v55
	s_nop 1
	v_cndmask_b32_e64 v56, 0, 32, vcc
	v_ldexp_f32 v55, v55, v56
	v_log_f32_e32 v55, v55
	s_nop 0
	v_mul_f32_e32 v56, 0x3f317217, v55
	v_fma_f32 v56, v55, s3, -v56
	v_fmac_f32_e32 v56, 0x3377d1cf, v55
	v_fmac_f32_e32 v56, 0x3f317217, v55
	v_cmp_lt_f32_e64 s[6:7], |v55|, s96
	s_nop 1
	v_cndmask_b32_e64 v55, v55, v56, s[6:7]
	v_cndmask_b32_e32 v56, 0, v244, vcc
	v_sub_f32_e32 v55, v55, v56
	v_sub_f32_e32 v54, v54, v55
	v_fmamk_f32 v99, v54, 0x3d800000, v96
	v_mul_f32_e32 v54, 0x3fb8aa3b, v99
	v_exp_f32_e32 v98, v54
	v_add_co_u32_e32 v54, vcc, s1, v52
	s_ashr_i32 s7, s30, 31
	s_nop 0
	v_addc_co_u32_e32 v55, vcc, 0, v53, vcc
	global_load_ushort v130, v[54:55], off offset:3328
	global_load_ushort v133, v[54:55], off offset:2560
	v_add_co_u32_e32 v54, vcc, s79, v52
	s_add_u32 s6, s5, s30
	s_nop 0
	v_addc_co_u32_e32 v55, vcc, 0, v53, vcc
	global_load_ushort v160, v[54:55], off offset:2304
	global_load_ushort v161, v[54:55], off offset:1536
	v_add_co_u32_e32 v54, vcc, s41, v52
	s_addc_u32 s7, s4, s7
	s_nop 0
	v_addc_co_u32_e32 v55, vcc, 0, v53, vcc
	global_load_ushort v158, v[54:55], off offset:1280
	global_load_ushort v159, v[54:55], off offset:512
	v_add_co_u32_e32 v54, vcc, s50, v52
	s_lshl_b64 s[4:5], s[6:7], 8
	s_nop 0
	v_addc_co_u32_e32 v55, vcc, 0, v53, vcc
	global_load_ushort v156, v[54:55], off offset:256
	v_add_co_u32_e32 v54, vcc, s93, v52
	s_add_u32 s4, s21, s4
	s_nop 0
	v_addc_co_u32_e32 v55, vcc, 0, v53, vcc
	global_load_ushort v157, v[54:55], off offset:3584
	v_add_co_u32_e32 v54, vcc, s52, v52
	s_addc_u32 s5, s22, s5
	s_nop 0
	v_addc_co_u32_e32 v55, vcc, 0, v53, vcc
	global_load_ushort v154, v[54:55], off offset:3328
	global_load_ushort v155, v[54:55], off offset:2560
	v_add_co_u32_e32 v54, vcc, s48, v52
	s_waitcnt vmcnt(9)
	v_lshlrev_b32_e32 v130, 16, v130
	v_addc_co_u32_e32 v55, vcc, 0, v53, vcc
	global_load_ushort v152, v[54:55], off offset:2304
	global_load_ushort v153, v[54:55], off offset:1536
	v_add_co_u32_e32 v54, vcc, s45, v52
	s_waitcnt vmcnt(10)
	v_lshlrev_b32_e32 v133, 16, v133
	v_addc_co_u32_e32 v55, vcc, 0, v53, vcc
	global_load_ushort v150, v[54:55], off offset:1280
	global_load_ushort v151, v[54:55], off offset:512
	v_add_co_u32_e32 v54, vcc, s54, v52
	v_mul_f32_e32 v162, v129, v130
	s_nop 0
	v_addc_co_u32_e32 v55, vcc, 0, v53, vcc
	global_load_ushort v148, v[54:55], off offset:256
	v_add_co_u32_e32 v54, vcc, s78, v52
	v_mul_f32_e32 v129, 0x3e000000, v133
	s_nop 0
	v_addc_co_u32_e32 v55, vcc, 0, v53, vcc
	global_load_ushort v149, v[54:55], off offset:3584
	v_add_co_u32_e32 v54, vcc, s55, v52
	v_mul_f32_e32 v129, v129, v134
	s_nop 0
	v_addc_co_u32_e32 v55, vcc, 0, v53, vcc
	global_load_ushort v145, v[54:55], off offset:3328
	global_load_ushort v146, v[54:55], off offset:2560
	v_add_co_u32_e32 v54, vcc, s65, v52
	v_cvt_pk_bf16_f32 v163, v129, s0
	s_nop 0
	v_addc_co_u32_e32 v55, vcc, 0, v53, vcc
	global_load_ushort v143, v[54:55], off offset:2304
	global_load_ushort v144, v[54:55], off offset:1536
	v_add_co_u32_e32 v54, vcc, s56, v52
	s_waitcnt vmcnt(17)
	v_lshlrev_b32_e32 v160, 16, v160
	v_addc_co_u32_e32 v55, vcc, 0, v53, vcc
	global_load_ushort v141, v[54:55], off offset:1280
	global_load_ushort v142, v[54:55], off offset:512
	v_add_co_u32_e32 v54, vcc, s51, v52
	s_waitcnt vmcnt(18)
	v_lshlrev_b32_e32 v161, 16, v161
	v_addc_co_u32_e32 v55, vcc, 0, v53, vcc
	global_load_ushort v139, v[54:55], off offset:256
	v_add_co_u32_e32 v54, vcc, s61, v52
	s_waitcnt vmcnt(18)
	v_lshlrev_b32_e32 v158, 16, v158
	v_addc_co_u32_e32 v55, vcc, 0, v53, vcc
	global_load_ushort v140, v[54:55], off offset:3584
	v_add_co_u32_e32 v54, vcc, s66, v52
	s_waitcnt vmcnt(18)
	v_lshlrev_b32_e32 v159, 16, v159
	v_addc_co_u32_e32 v55, vcc, 0, v53, vcc
	global_load_ushort v137, v[54:55], off offset:3328
	global_load_ushort v138, v[54:55], off offset:2560
	v_add_co_u32_e32 v54, vcc, s67, v52
	s_waitcnt vmcnt(19)
	v_lshlrev_b32_e32 v156, 16, v156
	v_addc_co_u32_e32 v55, vcc, 0, v53, vcc
	global_load_ushort v135, v[54:55], off offset:2304
	global_load_ushort v136, v[54:55], off offset:1536
	v_add_co_u32_e32 v54, vcc, s68, v52
	s_waitcnt vmcnt(20)
	v_lshlrev_b32_e32 v157, 16, v157
	v_addc_co_u32_e32 v55, vcc, 0, v53, vcc
	global_load_ushort v131, v[54:55], off offset:1280
	global_load_ushort v132, v[54:55], off offset:512
	v_add_co_u32_e32 v54, vcc, s72, v52
	global_store_dword v70, v98, s[4:5]
	s_mul_i32 s5, s8, 0xc000
	s_mul_hi_i32 s4, s8, 0xc000
	s_add_u32 s8, s23, s5
	v_addc_co_u32_e32 v55, vcc, 0, v53, vcc
	s_addc_u32 s9, s24, s4
	global_load_ushort v58, v[54:55], off offset:256
	v_add_co_u32_e32 v54, vcc, s73, v52
	s_add_u32 s8, s8, s10
	s_nop 0
	v_addc_co_u32_e32 v55, vcc, 0, v53, vcc
	s_addc_u32 s9, s9, s11
	s_add_u32 s5, s25, s5
	v_add_co_u32_e32 v164, vcc, s76, v52
	s_addc_u32 s4, s26, s4
	s_nop 0
	v_addc_co_u32_e32 v165, vcc, 0, v53, vcc
	global_load_ushort v59, v[54:55], off offset:3584
	s_add_u32 s10, s5, s10
	global_load_ushort v133, v[164:165], off offset:3328
	global_load_ushort v134, v[164:165], off offset:2560
	v_add_co_u32_e32 v164, vcc, s80, v52
	s_addc_u32 s11, s4, s11
	s_nop 0
	v_addc_co_u32_e32 v165, vcc, 0, v53, vcc
	s_mov_b32 s4, 0x33000
	v_add_co_u32_e32 v166, vcc, s4, v52
	s_mov_b32 s4, 0x36000
	s_nop 0
	v_addc_co_u32_e32 v167, vcc, 0, v53, vcc
	global_load_ushort v129, v[164:165], off offset:2304
	global_load_ushort v130, v[164:165], off offset:1536
	s_nop 0
	global_load_ushort v164, v[166:167], off offset:1280
	global_load_ushort v165, v[166:167], off offset:512
	v_add_co_u32_e32 v166, vcc, s4, v52
	s_mov_b32 s4, 0x35000
	s_nop 0
	v_addc_co_u32_e32 v167, vcc, 0, v53, vcc
	v_add_co_u32_e32 v168, vcc, s4, v52
	s_mov_b32 s4, 0x38000
	s_nop 0
	v_addc_co_u32_e32 v169, vcc, 0, v53, vcc
	global_load_ushort v166, v[166:167], off offset:256
	v_lshl_add_u64 v[54:55], s[8:9], 0, v[4:5]
	global_load_ushort v174, v[168:169], off offset:3584
	v_add_co_u32_e32 v168, vcc, s4, v52
	s_mov_b32 s4, 0x3b000
	s_nop 0
	v_addc_co_u32_e32 v169, vcc, 0, v53, vcc
	v_add_co_u32_e32 v170, vcc, s4, v52
	s_mov_b32 s4, 0x3e000
	s_nop 0
	v_addc_co_u32_e32 v171, vcc, 0, v53, vcc
	v_add_co_u32_e32 v176, vcc, s4, v52
	s_mov_b32 s4, 0x41000
	s_nop 0
	v_addc_co_u32_e32 v177, vcc, 0, v53, vcc
	global_load_ushort v172, v[168:169], off offset:3328
	global_load_ushort v173, v[168:169], off offset:2560
	s_nop 0
	global_load_ushort v168, v[170:171], off offset:2304
	global_load_ushort v169, v[170:171], off offset:1536
	s_nop 0
	global_load_ushort v170, v[176:177], off offset:1280
	global_load_ushort v171, v[176:177], off offset:512
	v_add_co_u32_e32 v176, vcc, s4, v52
	s_mov_b32 s4, 0x40000
	s_nop 0
	v_addc_co_u32_e32 v177, vcc, 0, v53, vcc
	global_load_ushort v167, v[176:177], off offset:256
	v_add_co_u32_e32 v176, vcc, s4, v52
	s_mov_b32 s4, 0x43000
	s_nop 0
	v_addc_co_u32_e32 v177, vcc, 0, v53, vcc
	global_load_ushort v182, v[176:177], off offset:3584
	v_add_co_u32_e32 v176, vcc, s4, v52
	s_mov_b32 s4, 0x46000
	s_nop 0
	v_addc_co_u32_e32 v177, vcc, 0, v53, vcc
	global_load_ushort v179, v[176:177], off offset:3328
	global_load_ushort v180, v[176:177], off offset:2560
	v_add_co_u32_e32 v176, vcc, s4, v52
	s_mov_b32 s4, 0x49000
	s_nop 0
	v_addc_co_u32_e32 v177, vcc, 0, v53, vcc
	v_add_co_u32_e32 v184, vcc, s4, v52
	s_mov_b32 s4, 0x4c000
	s_nop 0
	v_addc_co_u32_e32 v185, vcc, 0, v53, vcc
	global_load_ushort v175, v[176:177], off offset:2304
	s_nop 0
	global_load_ushort v176, v[176:177], off offset:1536
	s_nop 0
	global_load_ushort v177, v[184:185], off offset:1280
	global_load_ushort v178, v[184:185], off offset:512
	v_add_co_u32_e32 v184, vcc, s4, v52
	s_mov_b32 s4, 0x4b000
	s_nop 0
	v_addc_co_u32_e32 v185, vcc, 0, v53, vcc
	global_load_ushort v181, v[184:185], off offset:256
	v_add_co_u32_e32 v184, vcc, s4, v52
	s_mov_b32 s4, 0x4e000
	s_nop 0
	v_addc_co_u32_e32 v185, vcc, 0, v53, vcc
	global_load_ushort v190, v[184:185], off offset:3584
	v_add_co_u32_e32 v184, vcc, s4, v52
	s_mov_b32 s4, 0x51000
	s_nop 0
	v_addc_co_u32_e32 v185, vcc, 0, v53, vcc
	global_load_ushort v187, v[184:185], off offset:3328
	global_load_ushort v188, v[184:185], off offset:2560
	v_add_co_u32_e32 v184, vcc, s4, v52
	s_mov_b32 s4, 0x54000
	s_nop 0
	v_addc_co_u32_e32 v185, vcc, 0, v53, vcc
	v_add_co_u32_e32 v192, vcc, s4, v52
	s_mov_b32 s4, 0x57000
	s_nop 0
	v_addc_co_u32_e32 v193, vcc, 0, v53, vcc
	global_load_ushort v183, v[184:185], off offset:2304
	s_nop 0
	global_load_ushort v184, v[184:185], off offset:1536
	s_nop 0
	global_load_ushort v185, v[192:193], off offset:1280
	global_load_ushort v186, v[192:193], off offset:512
	v_add_co_u32_e32 v192, vcc, s4, v52
	s_mov_b32 s4, 0x56000
	s_nop 0
	v_addc_co_u32_e32 v193, vcc, 0, v53, vcc
	global_load_ushort v189, v[192:193], off offset:256
	v_add_co_u32_e32 v192, vcc, s4, v52
	global_store_short v4, v163, s[8:9]
	s_nop 0
	v_addc_co_u32_e32 v193, vcc, 0, v53, vcc
	global_load_ushort v191, v[192:193], off offset:3584
	v_cvt_pk_bf16_f32 v163, v162, s0
	v_mul_f32_e32 v162, v162, v98
	v_lshlrev_b32_e32 v192, 5, v60
	global_store_short v4, v163, s[10:11]
	v_cvt_pk_bf16_f32 v163, v162, s0
	v_add3_u32 v162, s13, v192, v147
	ds_write_b16 v162, v163
	v_mul_f32_e32 v163, 0x3fb8aa3b, v113
	v_mul_f32_e32 v113, 0xbfb8aa3b, v113
	v_exp_f32_e32 v113, v113
	v_exp_f32_e32 v163, v163
	v_lshl_add_u64 v[56:57], s[10:11], 0, v[4:5]
	s_waitcnt vmcnt(34)
	v_lshlrev_b32_e32 v59, 16, v59
	v_mul_f32_e32 v113, v113, v160
	v_mul_f32_e32 v160, 0x3e000000, v161
	v_mul_f32_e32 v160, v160, v163
	v_cvt_pk_bf16_f32 v160, v160, s0
	global_store_short v4, v160, s[8:9] offset:768
	v_cvt_pk_bf16_f32 v160, v113, s0
	v_mul_f32_e32 v113, v113, v98
	v_cvt_pk_bf16_f32 v113, v113, s0
	ds_write_b16 v162, v113 offset:128
	v_mul_f32_e32 v113, 0x3fb8aa3b, v114
	v_mul_f32_e32 v114, 0xbfb8aa3b, v114
	v_exp_f32_e32 v114, v114
	v_exp_f32_e32 v113, v113
	global_store_short v4, v160, s[10:11] offset:768
	v_mul_f32_e32 v59, 0x3e000000, v59
	v_mul_f32_e32 v114, v114, v158
	v_mul_f32_e32 v158, 0x3e000000, v159
	v_mul_f32_e32 v113, v158, v113
	v_cvt_pk_bf16_f32 v113, v113, s0
	global_store_short v4, v113, s[8:9] offset:1536
	v_cvt_pk_bf16_f32 v113, v114, s0
	global_store_short v4, v113, s[10:11] offset:1536
	v_mul_f32_e32 v113, v114, v98
	v_cvt_pk_bf16_f32 v114, v113, s0
	v_xor_b32_e32 v113, 32, v192
	v_add3_u32 v113, s13, v113, v147
	ds_write_b16 v113, v114 offset:256
	v_mul_f32_e32 v114, 0x3fb8aa3b, v115
	v_mul_f32_e32 v115, 0xbfb8aa3b, v115
	v_exp_f32_e32 v115, v115
	v_exp_f32_e32 v114, v114
	v_lshlrev_b32_e32 v58, 16, v58
	s_mov_b32 s4, 0x59000
	v_mul_f32_e32 v115, v115, v156
	v_mul_f32_e32 v156, 0x3e000000, v157
	v_mul_f32_e32 v114, v156, v114
	v_cvt_pk_bf16_f32 v114, v114, s0
	global_store_short v4, v114, s[8:9] offset:2304
	v_cvt_pk_bf16_f32 v114, v115, s0
	global_store_short v4, v114, s[10:11] offset:2304
	v_mul_f32_e32 v114, v115, v98
	v_cvt_pk_bf16_f32 v114, v114, s0
	v_mul_f32_e32 v115, 0xbfb8aa3b, v116
	ds_write_b16 v113, v114 offset:384
	v_mul_f32_e32 v114, 0x3fb8aa3b, v116
	v_exp_f32_e32 v115, v115
	v_exp_f32_e32 v114, v114
	v_lshlrev_b32_e32 v116, 16, v154
	v_lshlrev_b32_e32 v154, 16, v155
	v_mul_f32_e32 v115, v115, v116
	v_mul_f32_e32 v116, 0x3e000000, v154
	v_mul_f32_e32 v114, v116, v114
	v_cvt_pk_bf16_f32 v114, v114, s0
	global_store_short v4, v114, s[8:9] offset:3072
	v_cvt_pk_bf16_f32 v114, v115, s0
	global_store_short v4, v114, s[10:11] offset:3072
	v_mul_f32_e32 v114, v115, v98
	v_cvt_pk_bf16_f32 v114, v114, s0
	v_mul_f32_e32 v115, 0xbfb8aa3b, v117
	ds_write_b16 v162, v114 offset:512
	v_mul_f32_e32 v114, 0x3fb8aa3b, v117
	v_exp_f32_e32 v115, v115
	v_exp_f32_e32 v114, v114
	v_lshlrev_b32_e32 v116, 16, v152
	v_lshlrev_b32_e32 v117, 16, v153
	v_mul_f32_e32 v115, v115, v116
	v_mul_f32_e32 v116, 0x3e000000, v117
	v_mul_f32_e32 v114, v116, v114
	v_cvt_pk_bf16_f32 v114, v114, s0
	global_store_short v4, v114, s[8:9] offset:3840
	v_cvt_pk_bf16_f32 v114, v115, s0
	global_store_short v4, v114, s[10:11] offset:3840
	v_mul_f32_e32 v4, v115, v98
	v_cvt_pk_bf16_f32 v4, v4, s0
	v_mul_f32_e32 v114, 0xbfb8aa3b, v118
	ds_write_b16 v162, v4 offset:640
	v_mul_f32_e32 v4, 0x3fb8aa3b, v118
	v_exp_f32_e32 v114, v114
	v_exp_f32_e32 v4, v4
	v_lshlrev_b32_e32 v115, 16, v150
	v_lshlrev_b32_e32 v116, 16, v151
	v_mul_f32_e32 v118, v114, v115
	v_mul_f32_e32 v114, 0x3e000000, v116
	v_mul_f32_e32 v4, v114, v4
	v_add_co_u32_e32 v114, vcc, s1, v54
	v_cvt_pk_bf16_f32 v4, v4, s0
	s_nop 0
	v_addc_co_u32_e32 v115, vcc, 0, v55, vcc
	v_add_co_u32_e32 v116, vcc, s1, v56
	global_store_short v[114:115], v4, off offset:512
	v_cvt_pk_bf16_f32 v4, v118, s0
	v_addc_co_u32_e32 v117, vcc, 0, v57, vcc
	global_store_short v[116:117], v4, off offset:512
	v_mul_f32_e32 v4, v118, v98
	v_cvt_pk_bf16_f32 v4, v4, s0
	v_mul_f32_e32 v118, 0xbfb8aa3b, v119
	ds_write_b16 v113, v4 offset:768
	v_mul_f32_e32 v4, 0x3fb8aa3b, v119
	v_exp_f32_e32 v118, v118
	v_exp_f32_e32 v4, v4
	v_lshlrev_b32_e32 v119, 16, v148
	v_lshlrev_b32_e32 v148, 16, v149
	v_mul_f32_e32 v118, v118, v119
	v_mul_f32_e32 v119, 0x3e000000, v148
	v_mul_f32_e32 v4, v119, v4
	v_cvt_pk_bf16_f32 v4, v4, s0
	global_store_short v[114:115], v4, off offset:1280
	v_cvt_pk_bf16_f32 v4, v118, s0
	global_store_short v[116:117], v4, off offset:1280
	v_mul_f32_e32 v4, v118, v98
	v_cvt_pk_bf16_f32 v4, v4, s0
	v_mul_f32_e32 v118, 0xbfb8aa3b, v120
	ds_write_b16 v113, v4 offset:896
	v_mul_f32_e32 v4, 0x3fb8aa3b, v120
	v_exp_f32_e32 v118, v118
	v_exp_f32_e32 v4, v4
	v_lshlrev_b32_e32 v119, 16, v145
	v_lshlrev_b32_e32 v120, 16, v146
	v_mul_f32_e32 v118, v118, v119
	v_mul_f32_e32 v119, 0x3e000000, v120
	v_mul_f32_e32 v4, v119, v4
	v_cvt_pk_bf16_f32 v4, v4, s0
	global_store_short v[114:115], v4, off offset:2048
	v_cvt_pk_bf16_f32 v4, v118, s0
	global_store_short v[116:117], v4, off offset:2048
	v_mul_f32_e32 v4, v118, v98
	v_cvt_pk_bf16_f32 v118, v4, s0
	v_xor_b32_e32 v4, 64, v192
	v_add3_u32 v4, s13, v4, v147
	v_mul_f32_e32 v119, 0xbfb8aa3b, v121
	ds_write_b16 v4, v118 offset:1024
	v_mul_f32_e32 v118, 0x3fb8aa3b, v121
	v_exp_f32_e32 v119, v119
	v_exp_f32_e32 v118, v118
	v_lshlrev_b32_e32 v120, 16, v143
	v_lshlrev_b32_e32 v121, 16, v144
	v_mul_f32_e32 v119, v119, v120
	v_mul_f32_e32 v120, 0x3e000000, v121
	v_mul_f32_e32 v118, v120, v118
	v_cvt_pk_bf16_f32 v118, v118, s0
	global_store_short v[114:115], v118, off offset:2816
	v_cvt_pk_bf16_f32 v118, v119, s0
	global_store_short v[116:117], v118, off offset:2816
	v_mul_f32_e32 v118, v119, v98
	v_cvt_pk_bf16_f32 v118, v118, s0
	v_mul_f32_e32 v119, 0xbfb8aa3b, v122
	ds_write_b16 v4, v118 offset:1152
	v_mul_f32_e32 v118, 0x3fb8aa3b, v122
	v_exp_f32_e32 v119, v119
	v_exp_f32_e32 v118, v118
	v_lshlrev_b32_e32 v120, 16, v141
	v_lshlrev_b32_e32 v121, 16, v142
	v_mul_f32_e32 v119, v119, v120
	v_mul_f32_e32 v120, 0x3e000000, v121
	v_mul_f32_e32 v118, v120, v118
	v_cvt_pk_bf16_f32 v118, v118, s0
	global_store_short v[114:115], v118, off offset:3584
	v_cvt_pk_bf16_f32 v114, v119, s0
	global_store_short v[116:117], v114, off offset:3584
	v_mul_f32_e32 v114, v119, v98
	v_cvt_pk_bf16_f32 v115, v114, s0
	v_xor_b32_e32 v114, 0x60, v192
	v_add3_u32 v114, s13, v114, v147
	v_mul_f32_e32 v116, 0xbfb8aa3b, v123
	ds_write_b16 v114, v115 offset:1280
	v_mul_f32_e32 v115, 0x3fb8aa3b, v123
	v_exp_f32_e32 v116, v116
	v_exp_f32_e32 v115, v115
	v_lshlrev_b32_e32 v117, 16, v139
	v_lshlrev_b32_e32 v118, 16, v140
	v_mul_f32_e32 v120, v116, v117
	v_mul_f32_e32 v116, 0x3e000000, v118
	v_mul_f32_e32 v115, v116, v115
	v_add_co_u32_e32 v116, vcc, s75, v54
	v_cvt_pk_bf16_f32 v115, v115, s0
	s_nop 0
	v_addc_co_u32_e32 v117, vcc, 0, v55, vcc
	v_add_co_u32_e32 v118, vcc, s75, v56
	global_store_short v[116:117], v115, off offset:256
	v_cvt_pk_bf16_f32 v115, v120, s0
	v_addc_co_u32_e32 v119, vcc, 0, v57, vcc
	global_store_short v[118:119], v115, off offset:256
	v_mul_f32_e32 v115, v120, v98
	v_cvt_pk_bf16_f32 v115, v115, s0
	v_mul_f32_e32 v120, 0xbfb8aa3b, v124
	ds_write_b16 v114, v115 offset:1408
	v_mul_f32_e32 v115, 0x3fb8aa3b, v124
	v_exp_f32_e32 v120, v120
	v_exp_f32_e32 v115, v115
	v_lshlrev_b32_e32 v121, 16, v137
	v_lshlrev_b32_e32 v122, 16, v138
	v_mul_f32_e32 v120, v120, v121
	v_mul_f32_e32 v121, 0x3e000000, v122
	v_mul_f32_e32 v115, v121, v115
	v_cvt_pk_bf16_f32 v115, v115, s0
	global_store_short v[116:117], v115, off offset:1024
	v_cvt_pk_bf16_f32 v115, v120, s0
	global_store_short v[118:119], v115, off offset:1024
	v_mul_f32_e32 v115, v120, v98
	v_cvt_pk_bf16_f32 v115, v115, s0
	v_mul_f32_e32 v120, 0xbfb8aa3b, v125
	ds_write_b16 v4, v115 offset:1536
	v_mul_f32_e32 v115, 0x3fb8aa3b, v125
	v_exp_f32_e32 v120, v120
	v_exp_f32_e32 v115, v115
	v_lshlrev_b32_e32 v121, 16, v135
	v_lshlrev_b32_e32 v122, 16, v136
	v_mul_f32_e32 v120, v120, v121
	v_mul_f32_e32 v121, 0x3e000000, v122
	v_mul_f32_e32 v115, v121, v115
	v_cvt_pk_bf16_f32 v115, v115, s0
	global_store_short v[116:117], v115, off offset:1792
	v_cvt_pk_bf16_f32 v115, v120, s0
	global_store_short v[118:119], v115, off offset:1792
	v_mul_f32_e32 v115, v120, v98
	v_cvt_pk_bf16_f32 v115, v115, s0
	v_mul_f32_e32 v120, 0xbfb8aa3b, v126
	ds_write_b16 v4, v115 offset:1664
	v_mul_f32_e32 v115, 0x3fb8aa3b, v126
	v_exp_f32_e32 v120, v120
	v_exp_f32_e32 v115, v115
	v_lshlrev_b32_e32 v121, 16, v131
	v_lshlrev_b32_e32 v122, 16, v132
	v_mul_f32_e32 v120, v120, v121
	v_mul_f32_e32 v121, 0x3e000000, v122
	v_mul_f32_e32 v115, v121, v115
	v_cvt_pk_bf16_f32 v115, v115, s0
	global_store_short v[116:117], v115, off offset:2560
	v_cvt_pk_bf16_f32 v115, v120, s0
	global_store_short v[118:119], v115, off offset:2560
	v_mul_f32_e32 v115, v120, v98
	v_cvt_pk_bf16_f32 v115, v115, s0
	ds_write_b16 v114, v115 offset:1792
	v_mul_f32_e32 v115, 0x3fb8aa3b, v127
	v_exp_f32_e32 v115, v115
	v_mul_f32_e32 v120, 0xbfb8aa3b, v127
	v_exp_f32_e32 v120, v120
	s_waitcnt vmcnt(59)
	v_lshlrev_b32_e32 v129, 16, v129
	v_mul_f32_e32 v59, v59, v115
	v_cvt_pk_bf16_f32 v59, v59, s0
	v_mul_f32_e32 v58, v120, v58
	global_store_short v[116:117], v59, off offset:3328
	v_cvt_pk_bf16_f32 v59, v58, s0
	v_mul_f32_e32 v58, v58, v98
	global_store_short v[118:119], v59, off offset:3328
	v_cvt_pk_bf16_f32 v58, v58, s0
	v_mul_f32_e32 v59, 0xbfb8aa3b, v128
	ds_write_b16 v114, v58 offset:1920
	v_mul_f32_e32 v58, 0x3fb8aa3b, v128
	v_exp_f32_e32 v59, v59
	v_exp_f32_e32 v58, v58
	v_lshlrev_b32_e32 v115, 16, v133
	v_lshlrev_b32_e32 v116, 16, v134
	v_mul_f32_e32 v147, v59, v115
	v_mul_f32_e32 v59, 0x3e000000, v116
	v_mul_f32_e32 v58, v58, v59
	v_cvt_pk_bf16_f32 v148, v58, s0
	v_add_co_u32_e32 v58, vcc, s74, v54
	s_waitcnt vmcnt(60)
	v_lshlrev_b32_e32 v130, 16, v130
	v_addc_co_u32_e32 v59, vcc, 0, v55, vcc
	v_add_co_u32_e32 v116, vcc, s4, v52
	s_mov_b32 s4, 0x5c000
	s_nop 0
	v_addc_co_u32_e32 v117, vcc, 0, v53, vcc
	global_load_ushort v149, v[116:117], off offset:3328
	global_load_ushort v150, v[116:117], off offset:2560
	v_add_co_u32_e32 v116, vcc, s4, v52
	s_mov_b32 s4, 0x5f000
	s_nop 0
	v_addc_co_u32_e32 v117, vcc, 0, v53, vcc
	v_add_co_u32_e32 v118, vcc, s4, v52
	s_mov_b32 s4, 0x62000
	s_nop 0
	v_addc_co_u32_e32 v119, vcc, 0, v53, vcc
	v_add_co_u32_e32 v120, vcc, s4, v52
	s_mov_b32 s4, 0x61000
	s_nop 0
	v_addc_co_u32_e32 v121, vcc, 0, v53, vcc
	global_load_ushort v115, v[116:117], off offset:2304
	s_nop 0
	global_load_ushort v116, v[116:117], off offset:1536
	s_nop 0
	global_load_ushort v117, v[118:119], off offset:1280
	s_nop 0
	global_load_ushort v118, v[118:119], off offset:512
	s_nop 0
	global_load_ushort v119, v[120:121], off offset:256
	v_add_co_u32_e32 v120, vcc, s4, v52
	s_mov_b32 s4, 0x64000
	s_nop 0
	v_addc_co_u32_e32 v121, vcc, 0, v53, vcc
	v_add_co_u32_e32 v122, vcc, s4, v52
	s_mov_b32 s4, 0x67000
	s_nop 0
	v_addc_co_u32_e32 v123, vcc, 0, v53, vcc
	v_add_co_u32_e32 v124, vcc, s4, v52
	s_mov_b32 s4, 0x6a000
	s_nop 0
	v_addc_co_u32_e32 v125, vcc, 0, v53, vcc
	v_add_co_u32_e32 v132, vcc, s4, v52
	s_mov_b32 s4, 0x6d000
	s_nop 0
	v_addc_co_u32_e32 v133, vcc, 0, v53, vcc
	global_load_ushort v120, v[120:121], off offset:3584
	s_nop 0
	global_load_ushort v121, v[122:123], off offset:3328
	s_nop 0
	global_load_ushort v122, v[122:123], off offset:2560
	s_nop 0
	global_load_ushort v123, v[124:125], off offset:2304
	s_nop 0
	global_load_ushort v124, v[124:125], off offset:1536
	s_nop 0
	global_load_ushort v126, v[132:133], off offset:1280
	global_load_ushort v127, v[132:133], off offset:512
	v_add_co_u32_e32 v132, vcc, s4, v52
	s_mov_b32 s4, 0x6c000
	s_nop 0
	v_addc_co_u32_e32 v133, vcc, 0, v53, vcc
	global_load_ushort v125, v[132:133], off offset:256
	v_add_co_u32_e32 v132, vcc, s4, v52
	s_mov_b32 s4, 0x6f000
	s_nop 0
	v_addc_co_u32_e32 v133, vcc, 0, v53, vcc
	global_load_ushort v135, v[132:133], off offset:3584
	v_add_co_u32_e32 v132, vcc, s4, v52
	s_mov_b32 s4, 0x72000
	s_nop 0
	v_addc_co_u32_e32 v133, vcc, 0, v53, vcc
	v_add_co_u32_e32 v136, vcc, s4, v52
	s_mov_b32 s4, 0x75000
	s_nop 0
	v_addc_co_u32_e32 v137, vcc, 0, v53, vcc
	v_add_co_u32_e32 v138, vcc, s4, v52
	global_load_ushort v131, v[132:133], off offset:3328
	s_nop 0
	global_load_ushort v132, v[132:133], off offset:2560
	v_addc_co_u32_e32 v139, vcc, 0, v53, vcc
	global_load_ushort v133, v[136:137], off offset:2304
	global_load_ushort v134, v[136:137], off offset:1536
	s_nop 0
	global_load_ushort v136, v[138:139], off offset:1280
	global_load_ushort v137, v[138:139], off offset:512
	v_add_co_u32_e32 v138, vcc, s84, v52
	s_mov_b32 s4, 0x77000
	s_nop 0
	v_addc_co_u32_e32 v139, vcc, 0, v53, vcc
	global_load_ushort v128, v[138:139], off offset:256
	v_add_co_u32_e32 v138, vcc, s4, v52
	s_mov_b32 s4, 0x7a000
	s_nop 0
	v_addc_co_u32_e32 v139, vcc, 0, v53, vcc
	v_add_co_u32_e32 v140, vcc, s4, v52
	s_mov_b32 s4, 0x7d000
	s_nop 0
	v_addc_co_u32_e32 v141, vcc, 0, v53, vcc
	v_add_co_u32_e32 v142, vcc, s4, v52
	s_mov_b32 s4, 0x80000
	s_nop 0
	v_addc_co_u32_e32 v143, vcc, 0, v53, vcc
	v_add_co_u32_e32 v152, vcc, s4, v52
	global_load_ushort v144, v[138:139], off offset:3584
	s_nop 0
	v_addc_co_u32_e32 v153, vcc, 0, v53, vcc
	global_load_ushort v138, v[140:141], off offset:3328
	global_load_ushort v139, v[140:141], off offset:2560
	s_nop 0
	global_load_ushort v140, v[142:143], off offset:2304
	global_load_ushort v141, v[142:143], off offset:1536
	s_nop 0
	global_load_ushort v142, v[152:153], off offset:1280
	global_load_ushort v143, v[152:153], off offset:512
	s_mov_b32 s4, 0x83000
	global_store_short v[58:59], v148, off
	v_cvt_pk_bf16_f32 v148, v147, s0
	v_mul_f32_e32 v147, v147, v98
	v_cvt_pk_bf16_f32 v147, v147, s0
	ds_write_b16 v162, v147 offset:2048
	v_mul_f32_e32 v147, 0x3fb8aa3b, v91
	v_mul_f32_e32 v91, 0xbfb8aa3b, v91
	v_exp_f32_e32 v91, v91
	v_exp_f32_e32 v147, v147
	v_add_co_u32_e32 v152, vcc, s4, v52
	v_mul_f32_e32 v91, v91, v129
	v_mul_f32_e32 v129, 0x3e000000, v130
	v_mul_f32_e32 v129, v147, v129
	v_cvt_pk_bf16_f32 v129, v129, s0
	global_store_short v[58:59], v129, off offset:768
	v_cvt_pk_bf16_f32 v129, v91, s0
	v_mul_f32_e32 v91, v91, v98
	v_addc_co_u32_e32 v153, vcc, 0, v53, vcc
	s_mov_b32 s4, 0x82000
	v_cvt_pk_bf16_f32 v91, v91, s0
	global_load_ushort v145, v[152:153], off offset:256
	v_add_co_u32_e32 v152, vcc, s4, v52
	ds_write_b16 v162, v91 offset:2176
	v_mul_f32_e32 v91, 0x3fb8aa3b, v93
	v_mul_f32_e32 v93, 0xbfb8aa3b, v93
	v_addc_co_u32_e32 v153, vcc, 0, v53, vcc
	v_exp_f32_e32 v93, v93
	global_load_ushort v146, v[152:153], off offset:3584
	v_add_co_u32_e32 v152, vcc, s74, v56
	v_exp_f32_e32 v91, v91
	s_nop 0
	v_addc_co_u32_e32 v153, vcc, 0, v57, vcc
	global_store_short v[152:153], v129, off offset:768
	s_waitcnt vmcnt(62)
	v_lshlrev_b32_e32 v129, 16, v164
	v_lshlrev_b32_e32 v130, 16, v165
	v_mul_f32_e32 v93, v93, v129
	v_mul_f32_e32 v129, 0x3e000000, v130
	v_mul_f32_e32 v91, v91, v129
	v_cvt_pk_bf16_f32 v91, v91, s0
	global_store_short v[58:59], v91, off offset:1536
	v_cvt_pk_bf16_f32 v91, v93, s0
	global_store_short v[152:153], v91, off offset:1536
	v_mul_f32_e32 v91, v93, v98
	v_cvt_pk_bf16_f32 v91, v91, s0
	v_mul_f32_e32 v93, 0xbfb8aa3b, v95
	ds_write_b16 v113, v91 offset:2304
	v_mul_f32_e32 v91, 0x3fb8aa3b, v95
	v_exp_f32_e32 v93, v93
	v_exp_f32_e32 v91, v91
	v_lshlrev_b32_e32 v95, 16, v166
	v_lshlrev_b32_e32 v129, 16, v174
	v_mul_f32_e32 v93, v93, v95
	v_mul_f32_e32 v95, 0x3e000000, v129
	v_mul_f32_e32 v91, v91, v95
	v_cvt_pk_bf16_f32 v91, v91, s0
	global_store_short v[58:59], v91, off offset:2304
	v_cvt_pk_bf16_f32 v91, v93, s0
	global_store_short v[152:153], v91, off offset:2304
	v_mul_f32_e32 v91, v93, v98
	v_cvt_pk_bf16_f32 v91, v91, s0
	v_mul_f32_e32 v93, 0xbfb8aa3b, v97
	ds_write_b16 v113, v91 offset:2432
	v_mul_f32_e32 v91, 0x3fb8aa3b, v97
	v_exp_f32_e32 v93, v93
	v_exp_f32_e32 v91, v91
	v_lshlrev_b32_e32 v95, 16, v172
	v_lshlrev_b32_e32 v97, 16, v173
	v_mul_f32_e32 v93, v93, v95
	v_mul_f32_e32 v95, 0x3e000000, v97
	v_mul_f32_e32 v91, v91, v95
	v_cvt_pk_bf16_f32 v91, v91, s0
	global_store_short v[58:59], v91, off offset:3072
	v_cvt_pk_bf16_f32 v91, v93, s0
	global_store_short v[152:153], v91, off offset:3072
	v_mul_f32_e32 v91, v98, v93
	v_cvt_pk_bf16_f32 v91, v91, s0
	v_mul_f32_e32 v93, 0xbfb8aa3b, v100
	ds_write_b16 v162, v91 offset:2560
	v_mul_f32_e32 v91, 0x3fb8aa3b, v100
	v_exp_f32_e32 v93, v93
	v_exp_f32_e32 v91, v91
	v_lshlrev_b32_e32 v95, 16, v168
	v_lshlrev_b32_e32 v97, 16, v169
	v_mul_f32_e32 v93, v93, v95
	v_mul_f32_e32 v95, 0x3e000000, v97
	v_mul_f32_e32 v91, v91, v95
	v_cvt_pk_bf16_f32 v91, v91, s0
	global_store_short v[58:59], v91, off offset:3840
	v_cvt_pk_bf16_f32 v58, v93, s0
	global_store_short v[152:153], v58, off offset:3840
	v_mul_f32_e32 v58, v98, v93
	v_cvt_pk_bf16_f32 v58, v58, s0
	v_mul_f32_e32 v59, 0xbfb8aa3b, v101
	ds_write_b16 v162, v58 offset:2688
	v_mul_f32_e32 v58, 0x3fb8aa3b, v101
	v_exp_f32_e32 v59, v59
	v_exp_f32_e32 v58, v58
	v_lshlrev_b32_e32 v91, 16, v170
	v_lshlrev_b32_e32 v93, 16, v171
	v_mul_f32_e32 v91, v59, v91
	v_mul_f32_e32 v59, 0x3e000000, v93
	v_mul_f32_e32 v58, v58, v59
	v_cvt_pk_bf16_f32 v93, v58, s0
	v_add_co_u32_e32 v58, vcc, s79, v54
	v_lshlrev_b32_e32 v95, 16, v167
	s_nop 0
	v_addc_co_u32_e32 v59, vcc, 0, v55, vcc
	v_add_co_u32_e32 v100, vcc, s79, v56
	global_store_short v[58:59], v93, off offset:512
	v_cvt_pk_bf16_f32 v93, v91, s0
	v_addc_co_u32_e32 v101, vcc, 0, v57, vcc
	v_mul_f32_e32 v91, v98, v91
	global_store_short v[100:101], v93, off offset:512
	v_cvt_pk_bf16_f32 v91, v91, s0
	v_mul_f32_e32 v93, 0xbfb8aa3b, v102
	ds_write_b16 v113, v91 offset:2816
	v_mul_f32_e32 v91, 0x3fb8aa3b, v102
	v_exp_f32_e32 v93, v93
	v_exp_f32_e32 v91, v91
	v_lshlrev_b32_e32 v97, 16, v182
	s_mov_b32 s4, 0x85000
	v_mul_f32_e32 v93, v93, v95
	v_mul_f32_e32 v95, 0x3e000000, v97
	v_mul_f32_e32 v91, v91, v95
	v_cvt_pk_bf16_f32 v91, v91, s0
	global_store_short v[58:59], v91, off offset:1280
	v_cvt_pk_bf16_f32 v91, v93, s0
	global_store_short v[100:101], v91, off offset:1280
	v_mul_f32_e32 v91, v98, v93
	v_cvt_pk_bf16_f32 v91, v91, s0
	v_mul_f32_e32 v93, 0xbfb8aa3b, v103
	ds_write_b16 v113, v91 offset:2944
	v_mul_f32_e32 v91, 0x3fb8aa3b, v103
	v_exp_f32_e32 v93, v93
	v_exp_f32_e32 v91, v91
	v_lshlrev_b32_e32 v95, 16, v179
	v_lshlrev_b32_e32 v97, 16, v180
	v_mul_f32_e32 v93, v93, v95
	v_mul_f32_e32 v95, 0x3e000000, v97
	v_mul_f32_e32 v91, v91, v95
	v_cvt_pk_bf16_f32 v91, v91, s0
	global_store_short v[58:59], v91, off offset:2048
	v_cvt_pk_bf16_f32 v91, v93, s0
	global_store_short v[100:101], v91, off offset:2048
	v_mul_f32_e32 v91, v98, v93
	v_cvt_pk_bf16_f32 v91, v91, s0
	v_mul_f32_e32 v93, 0xbfb8aa3b, v104
	ds_write_b16 v4, v91 offset:3072
	v_mul_f32_e32 v91, 0x3fb8aa3b, v104
	v_exp_f32_e32 v93, v93
	v_exp_f32_e32 v91, v91
	v_lshlrev_b32_e32 v95, 16, v175
	v_lshlrev_b32_e32 v97, 16, v176
	v_mul_f32_e32 v93, v93, v95
	v_mul_f32_e32 v95, 0x3e000000, v97
	v_mul_f32_e32 v91, v91, v95
	v_cvt_pk_bf16_f32 v91, v91, s0
	global_store_short v[58:59], v91, off offset:2816
	v_cvt_pk_bf16_f32 v91, v93, s0
	global_store_short v[100:101], v91, off offset:2816
	v_mul_f32_e32 v91, v98, v93
	v_cvt_pk_bf16_f32 v91, v91, s0
	v_mul_f32_e32 v93, 0xbfb8aa3b, v105
	ds_write_b16 v4, v91 offset:3200
	v_mul_f32_e32 v91, 0x3fb8aa3b, v105
	v_exp_f32_e32 v93, v93
	v_exp_f32_e32 v91, v91
	v_lshlrev_b32_e32 v95, 16, v177
	v_lshlrev_b32_e32 v97, 16, v178
	v_mul_f32_e32 v93, v93, v95
	v_mul_f32_e32 v95, 0x3e000000, v97
	v_mul_f32_e32 v91, v91, v95
	v_cvt_pk_bf16_f32 v91, v91, s0
	global_store_short v[58:59], v91, off offset:3584
	v_cvt_pk_bf16_f32 v58, v93, s0
	global_store_short v[100:101], v58, off offset:3584
	v_mul_f32_e32 v58, v98, v93
	v_cvt_pk_bf16_f32 v58, v58, s0
	v_mul_f32_e32 v59, 0xbfb8aa3b, v106
	ds_write_b16 v114, v58 offset:3328
	v_mul_f32_e32 v58, 0x3fb8aa3b, v106
	v_exp_f32_e32 v59, v59
	v_exp_f32_e32 v58, v58
	v_lshlrev_b32_e32 v91, 16, v181
	v_lshlrev_b32_e32 v93, 16, v190
	v_mul_f32_e32 v91, v59, v91
	v_mul_f32_e32 v59, 0x3e000000, v93
	v_mul_f32_e32 v58, v58, v59
	v_cvt_pk_bf16_f32 v93, v58, s0
	v_add_co_u32_e32 v58, vcc, s40, v54
	v_lshlrev_b32_e32 v95, 16, v187
	s_nop 0
	v_addc_co_u32_e32 v59, vcc, 0, v55, vcc
	v_add_co_u32_e32 v100, vcc, s40, v56
	global_store_short v[58:59], v93, off offset:256
	v_cvt_pk_bf16_f32 v93, v91, s0
	v_addc_co_u32_e32 v101, vcc, 0, v57, vcc
	v_mul_f32_e32 v91, v98, v91
	global_store_short v[100:101], v93, off offset:256
	v_cvt_pk_bf16_f32 v91, v91, s0
	v_mul_f32_e32 v93, 0xbfb8aa3b, v107
	ds_write_b16 v114, v91 offset:3456
	v_mul_f32_e32 v91, 0x3fb8aa3b, v107
	v_exp_f32_e32 v93, v93
	v_exp_f32_e32 v91, v91
	v_lshlrev_b32_e32 v97, 16, v188
	global_store_short v[152:153], v148, off
	v_mul_f32_e32 v93, v93, v95
	v_mul_f32_e32 v95, 0x3e000000, v97
	v_mul_f32_e32 v91, v91, v95
	v_cvt_pk_bf16_f32 v91, v91, s0
	global_store_short v[58:59], v91, off offset:1024
	v_cvt_pk_bf16_f32 v91, v93, s0
	global_store_short v[100:101], v91, off offset:1024
	v_mul_f32_e32 v91, v98, v93
	v_cvt_pk_bf16_f32 v91, v91, s0
	v_mul_f32_e32 v93, 0xbfb8aa3b, v109
	ds_write_b16 v4, v91 offset:3584
	v_mul_f32_e32 v91, 0x3fb8aa3b, v109
	v_exp_f32_e32 v93, v93
	v_exp_f32_e32 v91, v91
	v_lshlrev_b32_e32 v95, 16, v183
	v_lshlrev_b32_e32 v97, 16, v184
	v_mul_f32_e32 v93, v93, v95
	v_mul_f32_e32 v95, 0x3e000000, v97
	v_mul_f32_e32 v91, v91, v95
	v_cvt_pk_bf16_f32 v91, v91, s0
	global_store_short v[58:59], v91, off offset:1792
	v_cvt_pk_bf16_f32 v91, v93, s0
	global_store_short v[100:101], v91, off offset:1792
	v_mul_f32_e32 v91, v98, v93
	v_cvt_pk_bf16_f32 v91, v91, s0
	v_mul_f32_e32 v93, 0xbfb8aa3b, v110
	ds_write_b16 v4, v91 offset:3712
	v_mul_f32_e32 v91, 0x3fb8aa3b, v110
	v_exp_f32_e32 v93, v93
	v_exp_f32_e32 v91, v91
	v_lshlrev_b32_e32 v95, 16, v185
	v_lshlrev_b32_e32 v97, 16, v186
	v_mul_f32_e32 v93, v93, v95
	v_mul_f32_e32 v95, 0x3e000000, v97
	v_mul_f32_e32 v91, v91, v95
	v_cvt_pk_bf16_f32 v91, v91, s0
	global_store_short v[58:59], v91, off offset:2560
	v_cvt_pk_bf16_f32 v91, v93, s0
	global_store_short v[100:101], v91, off offset:2560
	v_mul_f32_e32 v91, v98, v93
	v_cvt_pk_bf16_f32 v91, v91, s0
	v_mul_f32_e32 v93, 0xbfb8aa3b, v111
	ds_write_b16 v114, v91 offset:3840
	v_mul_f32_e32 v91, 0x3fb8aa3b, v111
	v_exp_f32_e32 v93, v93
	v_exp_f32_e32 v91, v91
	v_lshlrev_b32_e32 v95, 16, v189
	v_lshlrev_b32_e32 v97, 16, v191
	v_mul_f32_e32 v93, v93, v95
	v_mul_f32_e32 v95, 0x3e000000, v97
	v_mul_f32_e32 v91, v91, v95
	v_cvt_pk_bf16_f32 v91, v91, s0
	global_store_short v[58:59], v91, off offset:3328
	v_cvt_pk_bf16_f32 v58, v93, s0
	global_store_short v[100:101], v58, off offset:3328
	v_mul_f32_e32 v58, v98, v93
	v_cvt_pk_bf16_f32 v58, v58, s0
	v_mul_f32_e32 v59, 0xbfb8aa3b, v112
	ds_write_b16 v114, v58 offset:3968
	v_mul_f32_e32 v58, 0x3fb8aa3b, v112
	v_exp_f32_e32 v59, v59
	v_exp_f32_e32 v58, v58
	s_waitcnt vmcnt(62)
	v_lshlrev_b32_e32 v91, 16, v149
	v_lshlrev_b32_e32 v93, 16, v150
	v_mul_f32_e32 v91, v59, v91
	v_mul_f32_e32 v59, 0x3e000000, v93
	v_mul_f32_e32 v58, v58, v59
	v_cvt_pk_bf16_f32 v93, v58, s0
	v_add_co_u32_e32 v58, vcc, s62, v54
	s_nop 1
	v_addc_co_u32_e32 v59, vcc, 0, v55, vcc
	v_add_co_u32_e32 v100, vcc, s4, v52
	s_mov_b32 s4, 0x88000
	s_nop 0
	v_addc_co_u32_e32 v101, vcc, 0, v53, vcc
	v_add_co_u32_e32 v102, vcc, s4, v52
	s_mov_b32 s4, 0x8b000
	s_nop 0
	v_addc_co_u32_e32 v103, vcc, 0, v53, vcc
	v_add_co_u32_e32 v104, vcc, s4, v52
	s_mov_b32 s4, 0x8e000
	s_nop 0
	v_addc_co_u32_e32 v105, vcc, 0, v53, vcc
	global_load_ushort v95, v[100:101], off offset:3328
	global_load_ushort v97, v[100:101], off offset:2560
	s_nop 0
	global_load_ushort v100, v[102:103], off offset:2304
	global_load_ushort v101, v[102:103], off offset:1536
	s_nop 0
	global_load_ushort v102, v[104:105], off offset:1280
	global_load_ushort v103, v[104:105], off offset:512
	v_add_co_u32_e32 v104, vcc, s4, v52
	s_mov_b32 s4, 0x8d000
	s_nop 0
	v_addc_co_u32_e32 v105, vcc, 0, v53, vcc
	v_add_co_u32_e32 v106, vcc, s4, v52
	global_load_ushort v104, v[104:105], off offset:256
	s_nop 0
	v_addc_co_u32_e32 v107, vcc, 0, v53, vcc
	global_load_ushort v129, v[106:107], off offset:3584
	v_add_co_u32_e32 v106, vcc, s85, v52
	s_mov_b32 s4, 0x93000
	s_nop 0
	v_addc_co_u32_e32 v107, vcc, 0, v53, vcc
	v_add_co_u32_e32 v110, vcc, s4, v52
	s_mov_b32 s4, 0x96000
	s_nop 0
	v_addc_co_u32_e32 v111, vcc, 0, v53, vcc
	v_add_co_u32_e32 v148, vcc, s4, v52
	s_mov_b32 s4, 0x99000
	s_nop 0
	v_addc_co_u32_e32 v149, vcc, 0, v53, vcc
	global_load_ushort v105, v[106:107], off offset:3328
	s_nop 0
	global_load_ushort v106, v[106:107], off offset:2560
	s_nop 0
	global_load_ushort v107, v[110:111], off offset:2304
	global_load_ushort v109, v[110:111], off offset:1536
	s_nop 0
	global_load_ushort v111, v[148:149], off offset:1280
	global_load_ushort v112, v[148:149], off offset:512
	v_add_co_u32_e32 v148, vcc, s4, v52
	s_mov_b32 s4, 0x98000
	s_nop 0
	v_addc_co_u32_e32 v149, vcc, 0, v53, vcc
	global_load_ushort v110, v[148:149], off offset:256
	v_add_co_u32_e32 v148, vcc, s4, v52
	s_mov_b32 s4, 0x9b000
	s_nop 0
	v_addc_co_u32_e32 v149, vcc, 0, v53, vcc
	global_load_ushort v150, v[148:149], off offset:3584
	v_add_co_u32_e32 v148, vcc, s4, v52
	s_mov_b32 s4, 0x9e000
	s_nop 0
	v_addc_co_u32_e32 v149, vcc, 0, v53, vcc
	v_add_co_u32_e32 v152, vcc, s4, v52
	s_mov_b32 s4, 0xa1000
	s_nop 0
	v_addc_co_u32_e32 v153, vcc, 0, v53, vcc
	global_load_ushort v130, v[148:149], off offset:3328
	global_load_ushort v147, v[148:149], off offset:2560
	s_nop 0
	global_load_ushort v148, v[152:153], off offset:2304
	global_load_ushort v149, v[152:153], off offset:1536
	v_add_co_u32_e32 v152, vcc, s4, v52
	s_mov_b32 s4, 0xa4000
	s_nop 0
	v_addc_co_u32_e32 v153, vcc, 0, v53, vcc
	v_add_co_u32_e32 v154, vcc, s4, v52
	s_mov_b32 s4, 0xa3000
	s_nop 0
	v_addc_co_u32_e32 v155, vcc, 0, v53, vcc
	global_load_ushort v151, v[152:153], off offset:1280
	s_nop 0
	global_load_ushort v152, v[152:153], off offset:512
	s_nop 0
	global_load_ushort v153, v[154:155], off offset:256
	v_add_co_u32_e32 v154, vcc, s4, v52
	s_mov_b32 s4, 0xa6000
	s_nop 0
	v_addc_co_u32_e32 v155, vcc, 0, v53, vcc
	v_add_co_u32_e32 v156, vcc, s4, v52
	s_mov_b32 s4, 0xa9000
	s_nop 0
	v_addc_co_u32_e32 v157, vcc, 0, v53, vcc
	v_add_co_u32_e32 v158, vcc, s4, v52
	s_mov_b32 s4, 0xac000
	s_nop 0
	v_addc_co_u32_e32 v159, vcc, 0, v53, vcc
	v_add_co_u32_e32 v164, vcc, s4, v52
	s_mov_b32 s4, 0xaf000
	s_nop 0
	v_addc_co_u32_e32 v165, vcc, 0, v53, vcc
	global_load_ushort v160, v[154:155], off offset:3584
	s_nop 0
	global_load_ushort v154, v[156:157], off offset:3328
	global_load_ushort v155, v[156:157], off offset:2560
	s_nop 0
	global_load_ushort v156, v[158:159], off offset:2304
	global_load_ushort v157, v[158:159], off offset:1536
	s_nop 0
	global_load_ushort v158, v[164:165], off offset:1280
	global_load_ushort v159, v[164:165], off offset:512
	v_add_co_u32_e32 v164, vcc, s4, v52
	s_mov_b32 s4, 0xae000
	s_nop 0
	v_addc_co_u32_e32 v165, vcc, 0, v53, vcc
	v_add_co_u32_e32 v52, vcc, s4, v52
	global_load_ushort v161, v[164:165], off offset:256
	s_nop 0
	v_addc_co_u32_e32 v53, vcc, 0, v53, vcc
	global_load_ushort v52, v[52:53], off offset:3584
	v_add_co_u32_e32 v164, vcc, s62, v56
	v_cvt_pk_bf16_f32 v53, v91, s0
	s_nop 0
	v_addc_co_u32_e32 v165, vcc, 0, v57, vcc
	global_store_short v[164:165], v53, off
	v_mul_f32_e32 v53, v98, v91
	v_cvt_pk_bf16_f32 v53, v53, s0
	ds_write_b16 v162, v53 offset:4096
	v_mul_f32_e32 v53, 0x3fb8aa3b, v62
	v_mul_f32_e32 v62, 0xbfb8aa3b, v62
	v_exp_f32_e32 v62, v62
	v_exp_f32_e32 v53, v53
	global_store_short v[58:59], v93, off
	s_waitcnt vmcnt(62)
	v_lshlrev_b32_e32 v91, 16, v115
	v_lshlrev_b32_e32 v93, 16, v116
	v_mul_f32_e32 v62, v62, v91
	v_mul_f32_e32 v91, 0x3e000000, v93
	v_mul_f32_e32 v53, v53, v91
	v_cvt_pk_bf16_f32 v53, v53, s0
	global_store_short v[58:59], v53, off offset:768
	v_cvt_pk_bf16_f32 v53, v62, s0
	global_store_short v[164:165], v53, off offset:768
	v_mul_f32_e32 v53, v98, v62
	v_cvt_pk_bf16_f32 v53, v53, s0
	v_mul_f32_e32 v62, 0xbfb8aa3b, v63
	ds_write_b16 v162, v53 offset:4224
	v_mul_f32_e32 v53, 0x3fb8aa3b, v63
	v_exp_f32_e32 v62, v62
	v_exp_f32_e32 v53, v53
	v_lshlrev_b32_e32 v63, 16, v117
	v_lshlrev_b32_e32 v91, 16, v118
	v_mul_f32_e32 v62, v62, v63
	v_mul_f32_e32 v63, 0x3e000000, v91
	v_mul_f32_e32 v53, v53, v63
	v_cvt_pk_bf16_f32 v53, v53, s0
	global_store_short v[58:59], v53, off offset:1536
	v_cvt_pk_bf16_f32 v53, v62, s0
	global_store_short v[164:165], v53, off offset:1536
	v_mul_f32_e32 v53, v98, v62
	v_cvt_pk_bf16_f32 v53, v53, s0
	v_mul_f32_e32 v62, 0xbfb8aa3b, v64
	ds_write_b16 v113, v53 offset:4352
	v_mul_f32_e32 v53, 0x3fb8aa3b, v64
	v_exp_f32_e32 v62, v62
	v_exp_f32_e32 v53, v53
	v_lshlrev_b32_e32 v63, 16, v119
	v_lshlrev_b32_e32 v64, 16, v120
	v_mul_f32_e32 v62, v62, v63
	v_mul_f32_e32 v63, 0x3e000000, v64
	v_mul_f32_e32 v53, v53, v63
	v_cvt_pk_bf16_f32 v53, v53, s0
	global_store_short v[58:59], v53, off offset:2304
	v_cvt_pk_bf16_f32 v53, v62, s0
	global_store_short v[164:165], v53, off offset:2304
	v_mul_f32_e32 v53, v98, v62
	v_cvt_pk_bf16_f32 v53, v53, s0
	v_mul_f32_e32 v62, 0xbfb8aa3b, v65
	ds_write_b16 v113, v53 offset:4480
	v_mul_f32_e32 v53, 0x3fb8aa3b, v65
	v_exp_f32_e32 v62, v62
	v_exp_f32_e32 v53, v53
	v_lshlrev_b32_e32 v63, 16, v121
	v_lshlrev_b32_e32 v64, 16, v122
	v_mul_f32_e32 v62, v62, v63
	v_mul_f32_e32 v63, 0x3e000000, v64
	v_mul_f32_e32 v53, v53, v63
	v_cvt_pk_bf16_f32 v53, v53, s0
	global_store_short v[58:59], v53, off offset:3072
	v_cvt_pk_bf16_f32 v53, v62, s0
	global_store_short v[164:165], v53, off offset:3072
	v_mul_f32_e32 v53, v98, v62
	v_cvt_pk_bf16_f32 v53, v53, s0
	v_mul_f32_e32 v62, 0xbfb8aa3b, v66
	ds_write_b16 v162, v53 offset:4608
	v_mul_f32_e32 v53, 0x3fb8aa3b, v66
	v_exp_f32_e32 v62, v62
	v_exp_f32_e32 v53, v53
	v_lshlrev_b32_e32 v63, 16, v123
	v_lshlrev_b32_e32 v64, 16, v124
	v_mul_f32_e32 v62, v62, v63
	v_mul_f32_e32 v63, 0x3e000000, v64
	v_mul_f32_e32 v53, v53, v63
	v_cvt_pk_bf16_f32 v53, v53, s0
	global_store_short v[58:59], v53, off offset:3840
	v_cvt_pk_bf16_f32 v53, v62, s0
	global_store_short v[164:165], v53, off offset:3840
	v_mul_f32_e32 v53, v98, v62
	v_cvt_pk_bf16_f32 v53, v53, s0
	v_mul_f32_e32 v58, 0xbfb8aa3b, v67
	ds_write_b16 v162, v53 offset:4736
	v_mul_f32_e32 v53, 0x3fb8aa3b, v67
	v_exp_f32_e32 v58, v58
	v_exp_f32_e32 v53, v53
	v_lshlrev_b32_e32 v59, 16, v126
	v_lshlrev_b32_e32 v62, 16, v127
	v_mul_f32_e32 v64, v58, v59
	v_mul_f32_e32 v58, 0x3e000000, v62
	v_mul_f32_e32 v53, v53, v58
	v_add_co_u32_e32 v58, vcc, s41, v54
	v_cvt_pk_bf16_f32 v53, v53, s0
	s_nop 0
	v_addc_co_u32_e32 v59, vcc, 0, v55, vcc
	v_add_co_u32_e32 v62, vcc, s41, v56
	global_store_short v[58:59], v53, off offset:512
	v_cvt_pk_bf16_f32 v53, v64, s0
	v_addc_co_u32_e32 v63, vcc, 0, v57, vcc
	global_store_short v[62:63], v53, off offset:512
	v_mul_f32_e32 v53, v98, v64
	v_cvt_pk_bf16_f32 v53, v53, s0
	ds_write_b16 v113, v53 offset:4864
	v_mul_f32_e32 v53, 0x3fb8aa3b, v61
	v_mul_f32_e32 v61, 0xbfb8aa3b, v61
	v_exp_f32_e32 v61, v61
	v_exp_f32_e32 v53, v53
	v_lshlrev_b32_e32 v64, 16, v125
	v_lshlrev_b32_e32 v65, 16, v135
	v_mul_f32_e32 v61, v61, v64
	v_mul_f32_e32 v64, 0x3e000000, v65
	v_mul_f32_e32 v53, v53, v64
	v_cvt_pk_bf16_f32 v53, v53, s0
	global_store_short v[58:59], v53, off offset:1280
	v_cvt_pk_bf16_f32 v53, v61, s0
	global_store_short v[62:63], v53, off offset:1280
	v_mul_f32_e32 v53, v98, v61
	v_cvt_pk_bf16_f32 v53, v53, s0
	v_mul_f32_e32 v61, 0xbfb8aa3b, v68
	ds_write_b16 v113, v53 offset:4992
	v_mul_f32_e32 v53, 0x3fb8aa3b, v68
	v_exp_f32_e32 v61, v61
	v_exp_f32_e32 v53, v53
	v_lshlrev_b32_e32 v64, 16, v131
	v_lshlrev_b32_e32 v65, 16, v132
	v_mul_f32_e32 v61, v61, v64
	v_mul_f32_e32 v64, 0x3e000000, v65
	v_mul_f32_e32 v53, v53, v64
	v_cvt_pk_bf16_f32 v53, v53, s0
	global_store_short v[58:59], v53, off offset:2048
	v_cvt_pk_bf16_f32 v53, v61, s0
	global_store_short v[62:63], v53, off offset:2048
	v_mul_f32_e32 v53, v98, v61
	v_cvt_pk_bf16_f32 v53, v53, s0
	v_mul_f32_e32 v61, 0xbfb8aa3b, v69
	ds_write_b16 v4, v53 offset:5120
	v_mul_f32_e32 v53, 0x3fb8aa3b, v69
	v_exp_f32_e32 v61, v61
	v_exp_f32_e32 v53, v53
	v_lshlrev_b32_e32 v64, 16, v133
	v_lshlrev_b32_e32 v65, 16, v134
	v_mul_f32_e32 v61, v61, v64
	v_mul_f32_e32 v64, 0x3e000000, v65
	v_mul_f32_e32 v53, v53, v64
	v_cvt_pk_bf16_f32 v53, v53, s0
	global_store_short v[58:59], v53, off offset:2816
	v_cvt_pk_bf16_f32 v53, v61, s0
	global_store_short v[62:63], v53, off offset:2816
	v_mul_f32_e32 v53, v98, v61
	v_cvt_pk_bf16_f32 v53, v53, s0
	v_mul_f32_e32 v61, 0xbfb8aa3b, v73
	ds_write_b16 v4, v53 offset:5248
	v_mul_f32_e32 v53, 0x3fb8aa3b, v73
	v_exp_f32_e32 v61, v61
	v_exp_f32_e32 v53, v53
	v_lshlrev_b32_e32 v64, 16, v136
	v_lshlrev_b32_e32 v65, 16, v137
	v_mul_f32_e32 v61, v61, v64
	v_mul_f32_e32 v64, 0x3e000000, v65
	v_mul_f32_e32 v53, v53, v64
	v_cvt_pk_bf16_f32 v53, v53, s0
	global_store_short v[58:59], v53, off offset:3584
	v_cvt_pk_bf16_f32 v53, v61, s0
	global_store_short v[62:63], v53, off offset:3584
	v_mul_f32_e32 v53, v98, v61
	v_cvt_pk_bf16_f32 v53, v53, s0
	v_mul_f32_e32 v58, 0xbfb8aa3b, v74
	ds_write_b16 v114, v53 offset:5376
	v_mul_f32_e32 v53, 0x3fb8aa3b, v74
	v_exp_f32_e32 v58, v58
	v_exp_f32_e32 v53, v53
	v_lshlrev_b32_e32 v59, 16, v128
	v_lshlrev_b32_e32 v61, 16, v144
	v_mul_f32_e32 v64, v58, v59
	v_mul_f32_e32 v58, 0x3e000000, v61
	v_mul_f32_e32 v53, v53, v58
	v_add_co_u32_e32 v58, vcc, s49, v54
	v_cvt_pk_bf16_f32 v53, v53, s0
	s_nop 0
	v_addc_co_u32_e32 v59, vcc, 0, v55, vcc
	v_add_co_u32_e32 v62, vcc, s49, v56
	global_store_short v[58:59], v53, off offset:256
	v_cvt_pk_bf16_f32 v53, v64, s0
	v_addc_co_u32_e32 v63, vcc, 0, v57, vcc
	global_store_short v[62:63], v53, off offset:256
	v_mul_f32_e32 v53, v98, v64
	v_cvt_pk_bf16_f32 v53, v53, s0
	v_mul_f32_e32 v61, 0xbfb8aa3b, v75
	ds_write_b16 v114, v53 offset:5504
	v_mul_f32_e32 v53, 0x3fb8aa3b, v75
	v_exp_f32_e32 v61, v61
	v_exp_f32_e32 v53, v53
	v_lshlrev_b32_e32 v64, 16, v138
	v_lshlrev_b32_e32 v65, 16, v139
	v_mul_f32_e32 v61, v61, v64
	v_mul_f32_e32 v64, 0x3e000000, v65
	v_mul_f32_e32 v53, v53, v64
	v_cvt_pk_bf16_f32 v53, v53, s0
	global_store_short v[58:59], v53, off offset:1024
	v_cvt_pk_bf16_f32 v53, v61, s0
	global_store_short v[62:63], v53, off offset:1024
	v_mul_f32_e32 v53, v98, v61
	v_cvt_pk_bf16_f32 v53, v53, s0
	v_mul_f32_e32 v61, 0xbfb8aa3b, v76
	ds_write_b16 v4, v53 offset:5632
	v_mul_f32_e32 v53, 0x3fb8aa3b, v76
	v_exp_f32_e32 v61, v61
	v_exp_f32_e32 v53, v53
	v_lshlrev_b32_e32 v64, 16, v140
	v_lshlrev_b32_e32 v65, 16, v141
	v_mul_f32_e32 v61, v61, v64
	v_mul_f32_e32 v64, 0x3e000000, v65
	v_mul_f32_e32 v53, v53, v64
	v_cvt_pk_bf16_f32 v53, v53, s0
	global_store_short v[58:59], v53, off offset:1792
	v_cvt_pk_bf16_f32 v53, v61, s0
	global_store_short v[62:63], v53, off offset:1792
	v_mul_f32_e32 v53, v98, v61
	v_cvt_pk_bf16_f32 v53, v53, s0
	v_mul_f32_e32 v61, 0xbfb8aa3b, v77
	ds_write_b16 v4, v53 offset:5760
	v_mul_f32_e32 v53, 0x3fb8aa3b, v77
	v_exp_f32_e32 v61, v61
	v_exp_f32_e32 v53, v53
	v_lshlrev_b32_e32 v64, 16, v142
	v_lshlrev_b32_e32 v65, 16, v143
	v_mul_f32_e32 v61, v61, v64
	v_mul_f32_e32 v64, 0x3e000000, v65
	v_mul_f32_e32 v53, v53, v64
	v_cvt_pk_bf16_f32 v53, v53, s0
	global_store_short v[58:59], v53, off offset:2560
	v_cvt_pk_bf16_f32 v53, v61, s0
	global_store_short v[62:63], v53, off offset:2560
	v_mul_f32_e32 v53, v98, v61
	v_cvt_pk_bf16_f32 v53, v53, s0
	v_mul_f32_e32 v61, 0xbfb8aa3b, v78
	ds_write_b16 v114, v53 offset:5888
	v_mul_f32_e32 v53, 0x3fb8aa3b, v78
	v_exp_f32_e32 v61, v61
	v_exp_f32_e32 v53, v53
	v_lshlrev_b32_e32 v64, 16, v145
	v_lshlrev_b32_e32 v65, 16, v146
	v_mul_f32_e32 v61, v61, v64
	v_mul_f32_e32 v64, 0x3e000000, v65
	v_mul_f32_e32 v53, v53, v64
	v_cvt_pk_bf16_f32 v53, v53, s0
	global_store_short v[58:59], v53, off offset:3328
	v_cvt_pk_bf16_f32 v53, v61, s0
	global_store_short v[62:63], v53, off offset:3328
	v_mul_f32_e32 v53, v98, v61
	v_cvt_pk_bf16_f32 v53, v53, s0
	v_mul_f32_e32 v58, 0xbfb8aa3b, v79
	ds_write_b16 v114, v53 offset:6016
	v_mul_f32_e32 v53, 0x3fb8aa3b, v79
	v_exp_f32_e32 v58, v58
	v_exp_f32_e32 v53, v53
	s_waitcnt vmcnt(62)
	v_lshlrev_b32_e32 v59, 16, v95
	v_lshlrev_b32_e32 v61, 16, v97
	v_mul_f32_e32 v64, v58, v59
	v_mul_f32_e32 v58, 0x3e000000, v61
	v_mul_f32_e32 v53, v53, v58
	v_add_co_u32_e32 v58, vcc, s93, v54
	v_cvt_pk_bf16_f32 v53, v53, s0
	s_nop 0
	v_addc_co_u32_e32 v59, vcc, 0, v55, vcc
	v_add_co_u32_e32 v62, vcc, s93, v56
	global_store_short v[58:59], v53, off
	v_cvt_pk_bf16_f32 v53, v64, s0
	v_addc_co_u32_e32 v63, vcc, 0, v57, vcc
	global_store_short v[62:63], v53, off
	v_mul_f32_e32 v53, v98, v64
	v_cvt_pk_bf16_f32 v53, v53, s0
	v_mul_f32_e32 v61, 0xbfb8aa3b, v80
	ds_write_b16 v162, v53 offset:6144
	v_mul_f32_e32 v53, 0x3fb8aa3b, v80
	v_exp_f32_e32 v61, v61
	v_exp_f32_e32 v53, v53
	s_waitcnt vmcnt(62)
	v_lshlrev_b32_e32 v64, 16, v100
	v_lshlrev_b32_e32 v65, 16, v101
	v_mul_f32_e32 v61, v61, v64
	v_mul_f32_e32 v64, 0x3e000000, v65
	v_mul_f32_e32 v53, v53, v64
	v_cvt_pk_bf16_f32 v53, v53, s0
	global_store_short v[58:59], v53, off offset:768
	v_cvt_pk_bf16_f32 v53, v61, s0
	global_store_short v[62:63], v53, off offset:768
	v_mul_f32_e32 v53, v98, v61
	v_cvt_pk_bf16_f32 v53, v53, s0
	v_mul_f32_e32 v61, 0xbfb8aa3b, v81
	ds_write_b16 v162, v53 offset:6272
	v_mul_f32_e32 v53, 0x3fb8aa3b, v81
	v_exp_f32_e32 v61, v61
	v_exp_f32_e32 v53, v53
	s_waitcnt vmcnt(62)
	v_lshlrev_b32_e32 v64, 16, v102
	v_lshlrev_b32_e32 v65, 16, v103
	v_mul_f32_e32 v61, v61, v64
	v_mul_f32_e32 v64, 0x3e000000, v65
	v_mul_f32_e32 v53, v53, v64
	v_cvt_pk_bf16_f32 v53, v53, s0
	global_store_short v[58:59], v53, off offset:1536
	v_cvt_pk_bf16_f32 v53, v61, s0
	global_store_short v[62:63], v53, off offset:1536
	v_mul_f32_e32 v53, v98, v61
	v_cvt_pk_bf16_f32 v53, v53, s0
	v_mul_f32_e32 v61, 0xbfb8aa3b, v82
	ds_write_b16 v113, v53 offset:6400
	v_mul_f32_e32 v53, 0x3fb8aa3b, v82
	v_exp_f32_e32 v61, v61
	v_exp_f32_e32 v53, v53
	s_waitcnt vmcnt(62)
	v_lshlrev_b32_e32 v64, 16, v104
	v_lshlrev_b32_e32 v65, 16, v129
	v_mul_f32_e32 v61, v61, v64
	v_mul_f32_e32 v64, 0x3e000000, v65
	v_mul_f32_e32 v53, v53, v64
	v_cvt_pk_bf16_f32 v53, v53, s0
	global_store_short v[58:59], v53, off offset:2304
	v_cvt_pk_bf16_f32 v53, v61, s0
	global_store_short v[62:63], v53, off offset:2304
	v_mul_f32_e32 v53, v98, v61
	v_cvt_pk_bf16_f32 v53, v53, s0
	v_mul_f32_e32 v61, 0xbfb8aa3b, v83
	ds_write_b16 v113, v53 offset:6528
	v_mul_f32_e32 v53, 0x3fb8aa3b, v83
	v_exp_f32_e32 v61, v61
	v_exp_f32_e32 v53, v53
	s_waitcnt vmcnt(62)
	v_lshlrev_b32_e32 v64, 16, v105
	v_lshlrev_b32_e32 v65, 16, v106
	v_mul_f32_e32 v61, v61, v64
	v_mul_f32_e32 v64, 0x3e000000, v65
	v_mul_f32_e32 v53, v53, v64
	v_cvt_pk_bf16_f32 v53, v53, s0
	global_store_short v[58:59], v53, off offset:3072
	v_cvt_pk_bf16_f32 v53, v61, s0
	global_store_short v[62:63], v53, off offset:3072
	v_mul_f32_e32 v53, v98, v61
	v_cvt_pk_bf16_f32 v53, v53, s0
	v_mul_f32_e32 v61, 0xbfb8aa3b, v84
	ds_write_b16 v162, v53 offset:6656
	v_mul_f32_e32 v53, 0x3fb8aa3b, v84
	v_exp_f32_e32 v61, v61
	v_exp_f32_e32 v53, v53
	s_waitcnt vmcnt(62)
	v_lshlrev_b32_e32 v64, 16, v107
	v_lshlrev_b32_e32 v65, 16, v109
	v_mul_f32_e32 v61, v61, v64
	v_mul_f32_e32 v64, 0x3e000000, v65
	v_mul_f32_e32 v53, v53, v64
	v_cvt_pk_bf16_f32 v53, v53, s0
	global_store_short v[58:59], v53, off offset:3840
	v_cvt_pk_bf16_f32 v53, v61, s0
	global_store_short v[62:63], v53, off offset:3840
	v_mul_f32_e32 v53, v98, v61
	v_cvt_pk_bf16_f32 v53, v53, s0
	v_mul_f32_e32 v58, 0xbfb8aa3b, v85
	ds_write_b16 v162, v53 offset:6784
	v_mul_f32_e32 v53, 0x3fb8aa3b, v85
	v_exp_f32_e32 v58, v58
	v_exp_f32_e32 v53, v53
	s_waitcnt vmcnt(62)
	v_lshlrev_b32_e32 v59, 16, v111
	v_lshlrev_b32_e32 v61, 16, v112
	v_mul_f32_e32 v64, v58, v59
	v_mul_f32_e32 v58, 0x3e000000, v61
	v_mul_f32_e32 v53, v53, v58
	v_add_co_u32_e32 v58, vcc, s50, v54
	v_cvt_pk_bf16_f32 v53, v53, s0
	s_nop 0
	v_addc_co_u32_e32 v59, vcc, 0, v55, vcc
	v_add_co_u32_e32 v62, vcc, s50, v56
	global_store_short v[58:59], v53, off offset:512
	v_cvt_pk_bf16_f32 v53, v64, s0
	v_addc_co_u32_e32 v63, vcc, 0, v57, vcc
	global_store_short v[62:63], v53, off offset:512
	v_mul_f32_e32 v53, v98, v64
	v_cvt_pk_bf16_f32 v53, v53, s0
	v_mul_f32_e32 v61, 0xbfb8aa3b, v86
	ds_write_b16 v113, v53 offset:6912
	v_mul_f32_e32 v53, 0x3fb8aa3b, v86
	v_exp_f32_e32 v61, v61
	v_exp_f32_e32 v53, v53
	s_waitcnt vmcnt(62)
	v_lshlrev_b32_e32 v64, 16, v110
	v_lshlrev_b32_e32 v65, 16, v150
	v_mul_f32_e32 v61, v61, v64
	v_mul_f32_e32 v64, 0x3e000000, v65
	v_mul_f32_e32 v53, v53, v64
	v_cvt_pk_bf16_f32 v53, v53, s0
	global_store_short v[58:59], v53, off offset:1280
	v_cvt_pk_bf16_f32 v53, v61, s0
	global_store_short v[62:63], v53, off offset:1280
	v_mul_f32_e32 v53, v98, v61
	v_cvt_pk_bf16_f32 v53, v53, s0
	v_mul_f32_e32 v61, 0xbfb8aa3b, v87
	ds_write_b16 v113, v53 offset:7040
	v_mul_f32_e32 v53, 0x3fb8aa3b, v87
	v_exp_f32_e32 v61, v61
	v_exp_f32_e32 v53, v53
	s_waitcnt vmcnt(62)
	v_lshlrev_b32_e32 v64, 16, v130
	v_lshlrev_b32_e32 v65, 16, v147
	v_mul_f32_e32 v61, v61, v64
	v_mul_f32_e32 v64, 0x3e000000, v65
	v_mul_f32_e32 v53, v53, v64
	v_cvt_pk_bf16_f32 v53, v53, s0
	global_store_short v[58:59], v53, off offset:2048
	v_cvt_pk_bf16_f32 v53, v61, s0
	global_store_short v[62:63], v53, off offset:2048
	v_mul_f32_e32 v53, v98, v61
	v_cvt_pk_bf16_f32 v53, v53, s0
	v_mul_f32_e32 v61, 0xbfb8aa3b, v88
	ds_write_b16 v4, v53 offset:7168
	v_mul_f32_e32 v53, 0x3fb8aa3b, v88
	v_exp_f32_e32 v61, v61
	v_exp_f32_e32 v53, v53
	s_waitcnt vmcnt(62)
	v_lshlrev_b32_e32 v64, 16, v148
	v_lshlrev_b32_e32 v65, 16, v149
	v_mul_f32_e32 v61, v61, v64
	v_mul_f32_e32 v64, 0x3e000000, v65
	v_mul_f32_e32 v53, v53, v64
	v_cvt_pk_bf16_f32 v53, v53, s0
	global_store_short v[58:59], v53, off offset:2816
	v_cvt_pk_bf16_f32 v53, v61, s0
	global_store_short v[62:63], v53, off offset:2816
	v_mul_f32_e32 v53, v98, v61
	v_cvt_pk_bf16_f32 v53, v53, s0
	v_mul_f32_e32 v61, 0xbfb8aa3b, v89
	ds_write_b16 v4, v53 offset:7296
	v_mul_f32_e32 v53, 0x3fb8aa3b, v89
	v_exp_f32_e32 v61, v61
	v_exp_f32_e32 v53, v53
	s_waitcnt vmcnt(62)
	v_lshlrev_b32_e32 v64, 16, v151
	v_lshlrev_b32_e32 v65, 16, v152
	v_mul_f32_e32 v61, v61, v64
	v_mul_f32_e32 v64, 0x3e000000, v65
	v_mul_f32_e32 v53, v53, v64
	v_cvt_pk_bf16_f32 v53, v53, s0
	global_store_short v[58:59], v53, off offset:3584
	v_cvt_pk_bf16_f32 v53, v61, s0
	global_store_short v[62:63], v53, off offset:3584
	v_mul_f32_e32 v53, v98, v61
	v_cvt_pk_bf16_f32 v53, v53, s0
	v_mul_f32_e32 v58, 0xbfb8aa3b, v90
	ds_write_b16 v114, v53 offset:7424
	v_mul_f32_e32 v53, 0x3fb8aa3b, v90
	v_exp_f32_e32 v58, v58
	v_exp_f32_e32 v53, v53
	s_waitcnt vmcnt(62)
	v_lshlrev_b32_e32 v59, 16, v153
	v_lshlrev_b32_e32 v61, 16, v160
	v_mul_f32_e32 v58, v58, v59
	v_mul_f32_e32 v59, 0x3e000000, v61
	v_add_co_u32_e32 v54, vcc, s53, v54
	v_mul_f32_e32 v53, v53, v59
	s_nop 0
	v_addc_co_u32_e32 v55, vcc, 0, v55, vcc
	v_cvt_pk_bf16_f32 v53, v53, s0
	v_add_co_u32_e32 v56, vcc, s53, v56
	global_store_short v[54:55], v53, off offset:256
	v_cvt_pk_bf16_f32 v53, v58, s0
	v_addc_co_u32_e32 v57, vcc, 0, v57, vcc
	global_store_short v[56:57], v53, off offset:256
	v_mul_f32_e32 v53, v98, v58
	v_cvt_pk_bf16_f32 v53, v53, s0
	v_mul_f32_e32 v58, 0xbfb8aa3b, v92
	ds_write_b16 v114, v53 offset:7552
	v_mul_f32_e32 v53, 0x3fb8aa3b, v92
	v_exp_f32_e32 v58, v58
	v_exp_f32_e32 v53, v53
	s_waitcnt vmcnt(62)
	v_lshlrev_b32_e32 v59, 16, v154
	v_lshlrev_b32_e32 v61, 16, v155
	v_mul_f32_e32 v58, v58, v59
	v_mul_f32_e32 v59, 0x3e000000, v61
	v_mul_f32_e32 v53, v53, v59
	v_cvt_pk_bf16_f32 v53, v53, s0
	global_store_short v[54:55], v53, off offset:1024
	v_cvt_pk_bf16_f32 v53, v58, s0
	global_store_short v[56:57], v53, off offset:1024
	v_mul_f32_e32 v53, v98, v58
	v_cvt_pk_bf16_f32 v53, v53, s0
	v_mul_f32_e32 v58, 0xbfb8aa3b, v94
	ds_write_b16 v4, v53 offset:7680
	v_mul_f32_e32 v53, 0x3fb8aa3b, v94
	v_exp_f32_e32 v58, v58
	v_exp_f32_e32 v53, v53
	s_waitcnt vmcnt(62)
	v_lshlrev_b32_e32 v59, 16, v156
	v_lshlrev_b32_e32 v61, 16, v157
	v_mul_f32_e32 v58, v58, v59
	v_mul_f32_e32 v59, 0x3e000000, v61
	v_mul_f32_e32 v53, v53, v59
	v_cvt_pk_bf16_f32 v53, v53, s0
	global_store_short v[54:55], v53, off offset:1792
	v_cvt_pk_bf16_f32 v53, v58, s0
	global_store_short v[56:57], v53, off offset:1792
	v_mul_f32_e32 v53, v98, v58
	v_cvt_pk_bf16_f32 v53, v53, s0
	ds_write_b16 v4, v53 offset:7808
	v_mul_f32_e32 v53, 0xbfb8aa3b, v96
	v_mul_f32_e32 v4, 0x3fb8aa3b, v96
	v_exp_f32_e32 v53, v53
	v_exp_f32_e32 v4, v4
	s_waitcnt vmcnt(62)
	v_lshlrev_b32_e32 v58, 16, v158
	v_lshlrev_b32_e32 v59, 16, v159
	v_mul_f32_e32 v53, v53, v58
	v_mul_f32_e32 v58, 0x3e000000, v59
	v_mul_f32_e32 v4, v4, v58
	v_cvt_pk_bf16_f32 v4, v4, s0
	global_store_short v[54:55], v4, off offset:2560
	v_cvt_pk_bf16_f32 v4, v53, s0
	global_store_short v[56:57], v4, off offset:2560
	v_mul_f32_e32 v4, v98, v53
	v_cvt_pk_bf16_f32 v4, v4, s0
	ds_write_b16 v114, v4 offset:7936
	v_mul_f32_e32 v4, 0xbfb8aa3b, v99
	v_exp_f32_e32 v4, v4
	s_waitcnt vmcnt(62)
	v_lshlrev_b32_e32 v52, 16, v52
	v_mul_f32_e32 v52, 0x3e000000, v52
	v_lshlrev_b32_e32 v53, 16, v161
	v_mul_f32_e32 v52, v98, v52
	v_mul_f32_e32 v4, v4, v53
	v_cvt_pk_bf16_f32 v52, v52, s0
	global_store_short v[54:55], v52, off offset:3328
	v_cvt_pk_bf16_f32 v52, v4, s0
	v_mul_f32_e32 v4, v98, v4
	s_lshl_b64 s[4:5], s[6:7], 15
	v_cvt_pk_bf16_f32 v4, v4, s0
	s_add_u32 s4, s19, s4
	ds_write_b16 v114, v4 offset:8064
	s_addc_u32 s5, s20, s5
	v_lshlrev_b32_e32 v4, 8, v71
	global_store_short v[56:57], v52, off offset:3328
	v_lshl_add_u64 v[52:53], s[4:5], 0, v[4:5]
	v_and_b32_e32 v4, 48, v108
	v_lshl_add_u64 v[106:107], v[52:53], 0, v[4:5]
	v_lshlrev_b32_e32 v4, 4, v108
	v_lshlrev_b32_e32 v55, 5, v108
	v_lshlrev_b32_e32 v56, 3, v108
	v_bfe_u32 v53, v108, 1, 2
	v_and_b32_e32 v54, 16, v4
	v_lshlrev_b32_e32 v4, 10, v60
	v_and_b32_e32 v55, 0x180, v55
	v_and_b32_e32 v56, 24, v56
	v_or3_b32 v58, v55, v4, v56
	v_bitop3_b32 v4, v60, v53, 1 bitop3:0x6c
	v_lshlrev_b32_e32 v52, 7, v72
	v_lshl_add_u32 v4, v4, 5, s13
	v_add3_u32 v4, v4, v52, v54
	ds_write_b128 v4, v[34:37] offset:8192
	v_bitop3_b32 v34, v60, v53, 2 bitop3:0x36
	v_lshl_add_u32 v34, v34, 5, s13
	v_add3_u32 v109, v34, v52, v54
	ds_write_b128 v109, v[6:9] offset:9216
	ds_write_b128 v4, v[10:13] offset:10240
	ds_write_b128 v109, v[14:17] offset:11264
	ds_write_b128 v4, v[18:21] offset:12288
	ds_write_b128 v109, v[22:25] offset:13312
	ds_write_b128 v4, v[26:29] offset:14336
	ds_write_b128 v109, v[30:33] offset:15360
	global_load_dwordx4 v[6:9], v[50:51], off offset:128
	global_load_dwordx4 v[10:13], v[48:49], off offset:128
	global_load_dwordx4 v[14:17], v[46:47], off offset:128
	global_load_dwordx4 v[18:21], v[44:45], off offset:128
	global_load_dwordx4 v[22:25], v[42:43], off offset:128
	global_load_dwordx4 v[26:29], v[40:41], off offset:128
	global_load_dwordx4 v[30:33], v[38:39], off offset:128
	global_load_dwordx4 v[34:37], v[2:3], off offset:128
	v_and_b32_e32 v2, 0x60, v70
	v_or_b32_e32 v2, v2, v58
	v_add_u32_e32 v110, s13, v2
	v_bitop3_b32 v2, v70, 32, v245 bitop3:0x6c
	v_or_b32_e32 v2, v2, v58
	v_add_u32_e32 v111, s13, v2
	v_bitop3_b32 v2, v70, 64, v245 bitop3:0x6c
	s_waitcnt lgkmcnt(0)
	v_or_b32_e32 v2, v2, v58
	ds_read_b64_tr_b16 v[38:39], v110 offset:8192
	ds_read_b64_tr_b16 v[40:41], v110 offset:8704
	ds_read_b64_tr_b16 v[42:43], v110
	ds_read_b64_tr_b16 v[44:45], v110 offset:512
	v_add_u32_e32 v112, s13, v2
	v_bitop3_b32 v2, v70, v58, s63 bitop3:0xce
	ds_read_b64_tr_b16 v[50:51], v111 offset:8192
	ds_read_b64_tr_b16 v[52:53], v111 offset:8704
	ds_read_b64_tr_b16 v[46:47], v111
	ds_read_b64_tr_b16 v[48:49], v111 offset:512
	v_add_u32_e32 v113, s13, v2
	ds_read_b64_tr_b16 v[102:103], v112 offset:8192
	ds_read_b64_tr_b16 v[104:105], v112 offset:8704
	ds_read_b64_tr_b16 v[54:55], v112
	ds_read_b64_tr_b16 v[56:57], v112 offset:512
	ds_read_b64_tr_b16 v[114:115], v113 offset:8192
	ds_read_b64_tr_b16 v[116:117], v113 offset:8704
	ds_read_b64_tr_b16 v[118:119], v113
	ds_read_b64_tr_b16 v[120:121], v113 offset:512
	s_waitcnt lgkmcnt(12)
	v_mfma_f32_16x16x32_bf16 v[98:101], v[42:45], v[38:41], 0
	v_add_co_u32_e32 v2, vcc, s1, v106
	s_add_i32 s4, s18, 8
	s_waitcnt lgkmcnt(8)
	v_mfma_f32_16x16x32_bf16 v[94:97], v[46:49], v[38:41], 0
	v_addc_co_u32_e32 v3, vcc, 0, v107, vcc
	s_addk_i32 s28, 0x200
	s_waitcnt lgkmcnt(4)
	v_mfma_f32_16x16x32_bf16 v[90:93], v[54:57], v[38:41], 0
	s_addk_i32 s29, 0x400
	s_cmp_gt_i32 s18, 3
	s_mov_b32 s18, s4
	s_waitcnt lgkmcnt(0)
	v_mfma_f32_16x16x32_bf16 v[86:89], v[118:121], v[38:41], 0
	v_mfma_f32_16x16x32_bf16 v[74:77], v[42:45], v[50:53], 0
	v_mfma_f32_16x16x32_bf16 v[78:81], v[46:49], v[50:53], 0
	v_mfma_f32_16x16x32_bf16 v[82:85], v[54:57], v[50:53], 0
	v_mfma_f32_16x16x32_bf16 v[70:73], v[118:121], v[50:53], 0
	v_mfma_f32_16x16x32_bf16 v[66:69], v[42:45], v[102:105], 0
	v_mfma_f32_16x16x32_bf16 v[62:65], v[46:49], v[102:105], 0
	v_mfma_f32_16x16x32_bf16 v[58:61], v[54:57], v[102:105], 0
	v_mfma_f32_16x16x32_bf16 v[38:41], v[118:121], v[102:105], 0
	v_mfma_f32_16x16x32_bf16 v[42:45], v[42:45], v[114:117], 0
	v_mfma_f32_16x16x32_bf16 v[46:49], v[46:49], v[114:117], 0
	v_mfma_f32_16x16x32_bf16 v[50:53], v[54:57], v[114:117], 0
	v_mfma_f32_16x16x32_bf16 v[54:57], v[118:121], v[114:117], 0
	ds_read_b64_tr_b16 v[102:103], v110 offset:12288
	ds_read_b64_tr_b16 v[104:105], v110 offset:12800
	ds_read_b64_tr_b16 v[114:115], v110 offset:4096
	ds_read_b64_tr_b16 v[116:117], v110 offset:4608
	ds_read_b64_tr_b16 v[118:119], v111 offset:12288
	ds_read_b64_tr_b16 v[120:121], v111 offset:12800
	ds_read_b64_tr_b16 v[122:123], v111 offset:4096
	ds_read_b64_tr_b16 v[124:125], v111 offset:4608
	ds_read_b64_tr_b16 v[126:127], v112 offset:12288
	ds_read_b64_tr_b16 v[128:129], v112 offset:12800
	ds_read_b64_tr_b16 v[130:131], v112 offset:4096
	ds_read_b64_tr_b16 v[132:133], v112 offset:4608
	ds_read_b64_tr_b16 v[134:135], v113 offset:12288
	ds_read_b64_tr_b16 v[136:137], v113 offset:12800
	ds_read_b64_tr_b16 v[138:139], v113 offset:4096
	ds_read_b64_tr_b16 v[140:141], v113 offset:4608
	s_waitcnt lgkmcnt(12)
	v_mfma_f32_16x16x32_bf16 v[98:101], v[114:117], v[102:105], v[98:101]
	s_waitcnt lgkmcnt(8)
	v_mfma_f32_16x16x32_bf16 v[94:97], v[122:125], v[102:105], v[94:97]
	s_waitcnt lgkmcnt(4)
	v_mfma_f32_16x16x32_bf16 v[90:93], v[130:133], v[102:105], v[90:93]
	v_mfma_f32_16x16x32_bf16 v[74:77], v[114:117], v[118:121], v[74:77]
	s_waitcnt lgkmcnt(0)
	v_mfma_f32_16x16x32_bf16 v[86:89], v[138:141], v[102:105], v[86:89]
	s_nop 0
	global_store_dwordx4 v[106:107], v[98:101], off
	s_nop 0
	global_store_dwordx4 v[106:107], v[94:97], off offset:64
	s_nop 0
	global_store_dwordx4 v[106:107], v[90:93], off offset:128
	s_nop 1
	global_store_dwordx4 v[106:107], v[86:89], off offset:192
	v_mfma_f32_16x16x32_bf16 v[78:81], v[122:125], v[118:121], v[78:81]
	s_nop 0
	v_add_co_u32_e32 v86, vcc, s75, v106
	v_mfma_f32_16x16x32_bf16 v[82:85], v[130:133], v[118:121], v[82:85]
	s_nop 0
	v_addc_co_u32_e32 v87, vcc, 0, v107, vcc
	v_mfma_f32_16x16x32_bf16 v[70:73], v[138:141], v[118:121], v[70:73]
	v_mfma_f32_16x16x32_bf16 v[38:41], v[138:141], v[126:129], v[38:41]
	v_mfma_f32_16x16x32_bf16 v[66:69], v[114:117], v[126:129], v[66:69]
	v_mfma_f32_16x16x32_bf16 v[62:65], v[122:125], v[126:129], v[62:65]
	v_mfma_f32_16x16x32_bf16 v[58:61], v[130:133], v[126:129], v[58:61]
	global_store_dwordx4 v[86:87], v[74:77], off offset:-4096
	global_store_dwordx4 v[2:3], v[78:81], off offset:64
	global_store_dwordx4 v[2:3], v[82:85], off offset:128
	s_nop 0
	global_store_dwordx4 v[2:3], v[70:73], off offset:192
	s_nop 0
	global_store_dwordx4 v[86:87], v[66:69], off
	global_store_dwordx4 v[86:87], v[62:65], off offset:64
	global_store_dwordx4 v[86:87], v[58:61], off offset:128
	global_store_dwordx4 v[86:87], v[38:41], off offset:192
	v_mfma_f32_16x16x32_bf16 v[42:45], v[114:117], v[134:137], v[42:45]
	s_nop 0
	v_add_co_u32_e32 v38, vcc, s74, v106
	v_mfma_f32_16x16x32_bf16 v[46:49], v[122:125], v[134:137], v[46:49]
	s_nop 0
	v_addc_co_u32_e32 v39, vcc, 0, v107, vcc
	v_add_co_u32_e32 v2, vcc, s79, v106
	v_mfma_f32_16x16x32_bf16 v[50:53], v[130:133], v[134:137], v[50:53]
	s_nop 0
	v_addc_co_u32_e32 v3, vcc, 0, v107, vcc
	v_mfma_f32_16x16x32_bf16 v[54:57], v[138:141], v[134:137], v[54:57]
	global_store_dwordx4 v[2:3], v[42:45], off offset:-4096
	global_store_dwordx4 v[38:39], v[46:49], off offset:64
	s_nop 2
	global_store_dwordx4 v[38:39], v[50:53], off offset:128
	s_nop 1
	global_store_dwordx4 v[38:39], v[54:57], off offset:192
	s_waitcnt lgkmcnt(0)
	s_waitcnt vmcnt(16)
	ds_write_b128 v4, v[34:37] offset:8192
	ds_write_b128 v109, v[30:33] offset:9216
	ds_write_b128 v4, v[26:29] offset:10240
	ds_write_b128 v109, v[22:25] offset:11264
	ds_write_b128 v4, v[18:21] offset:12288
	ds_write_b128 v109, v[14:17] offset:13312
	ds_write_b128 v4, v[10:13] offset:14336
	ds_write_b128 v109, v[6:9] offset:15360
	s_waitcnt lgkmcnt(0)
	ds_read_b64_tr_b16 v[6:7], v110 offset:8192
	ds_read_b64_tr_b16 v[8:9], v110 offset:8704
	ds_read_b64_tr_b16 v[22:23], v110
	ds_read_b64_tr_b16 v[24:25], v110 offset:512
	ds_read_b64_tr_b16 v[10:11], v111 offset:8192
	ds_read_b64_tr_b16 v[12:13], v111 offset:8704
	ds_read_b64_tr_b16 v[26:27], v111
	ds_read_b64_tr_b16 v[28:29], v111 offset:512
	ds_read_b64_tr_b16 v[18:19], v112 offset:8192
	ds_read_b64_tr_b16 v[20:21], v112 offset:8704
	ds_read_b64_tr_b16 v[30:31], v112
	ds_read_b64_tr_b16 v[32:33], v112 offset:512
	ds_read_b64_tr_b16 v[34:35], v113 offset:8192
	ds_read_b64_tr_b16 v[36:37], v113 offset:8704
	ds_read_b64_tr_b16 v[70:71], v113
	ds_read_b64_tr_b16 v[72:73], v113 offset:512
	s_waitcnt lgkmcnt(12)
	v_mfma_f32_16x16x32_bf16 v[66:69], v[22:25], v[6:9], 0
	s_waitcnt lgkmcnt(8)
	v_mfma_f32_16x16x32_bf16 v[62:65], v[26:29], v[6:9], 0
	s_waitcnt lgkmcnt(4)
	v_mfma_f32_16x16x32_bf16 v[58:61], v[30:33], v[6:9], 0
	s_waitcnt lgkmcnt(0)
	v_mfma_f32_16x16x32_bf16 v[54:57], v[70:73], v[6:9], 0
	v_mfma_f32_16x16x32_bf16 v[42:45], v[22:25], v[10:13], 0
	v_mfma_f32_16x16x32_bf16 v[46:49], v[26:29], v[10:13], 0
	v_mfma_f32_16x16x32_bf16 v[50:53], v[30:33], v[10:13], 0
	v_mfma_f32_16x16x32_bf16 v[38:41], v[70:73], v[10:13], 0
	v_mfma_f32_16x16x32_bf16 v[6:9], v[22:25], v[18:21], 0
	v_mfma_f32_16x16x32_bf16 v[10:13], v[26:29], v[18:21], 0
	v_mfma_f32_16x16x32_bf16 v[14:17], v[30:33], v[18:21], 0
	v_mfma_f32_16x16x32_bf16 v[18:21], v[70:73], v[18:21], 0
	v_mfma_f32_16x16x32_bf16 v[22:25], v[22:25], v[34:37], 0
	v_mfma_f32_16x16x32_bf16 v[26:29], v[26:29], v[34:37], 0
	v_mfma_f32_16x16x32_bf16 v[30:33], v[30:33], v[34:37], 0
	v_mfma_f32_16x16x32_bf16 v[34:37], v[70:73], v[34:37], 0
	ds_read_b64_tr_b16 v[70:71], v110 offset:12288
	ds_read_b64_tr_b16 v[72:73], v110 offset:12800
	ds_read_b64_tr_b16 v[74:75], v110 offset:4096
	ds_read_b64_tr_b16 v[76:77], v110 offset:4608
	ds_read_b64_tr_b16 v[78:79], v111 offset:12288
	ds_read_b64_tr_b16 v[80:81], v111 offset:12800
	ds_read_b64_tr_b16 v[82:83], v111 offset:4096
	ds_read_b64_tr_b16 v[84:85], v111 offset:4608
	ds_read_b64_tr_b16 v[86:87], v112 offset:12288
	ds_read_b64_tr_b16 v[88:89], v112 offset:12800
	ds_read_b64_tr_b16 v[90:91], v112 offset:4096
	ds_read_b64_tr_b16 v[92:93], v112 offset:4608
	ds_read_b64_tr_b16 v[94:95], v113 offset:12288
	ds_read_b64_tr_b16 v[96:97], v113 offset:12800
	ds_read_b64_tr_b16 v[98:99], v113 offset:4096
	ds_read_b64_tr_b16 v[100:101], v113 offset:4608
	s_waitcnt lgkmcnt(12)
	v_mfma_f32_16x16x32_bf16 v[66:69], v[74:77], v[70:73], v[66:69]
	s_waitcnt lgkmcnt(8)
	v_mfma_f32_16x16x32_bf16 v[62:65], v[82:85], v[70:73], v[62:65]
	s_waitcnt lgkmcnt(4)
	v_mfma_f32_16x16x32_bf16 v[58:61], v[90:93], v[70:73], v[58:61]
	s_waitcnt lgkmcnt(0)
	v_mfma_f32_16x16x32_bf16 v[54:57], v[98:101], v[70:73], v[54:57]
	s_nop 1
	global_store_dwordx4 v[2:3], v[66:69], off
	s_nop 0
	global_store_dwordx4 v[2:3], v[62:65], off offset:64
	s_nop 0
	global_store_dwordx4 v[2:3], v[58:61], off offset:128
	s_nop 0
	global_store_dwordx4 v[2:3], v[54:57], off offset:192
	v_add_co_u32_e32 v2, vcc, s40, v106
	v_mfma_f32_16x16x32_bf16 v[42:45], v[74:77], v[78:81], v[42:45]
	s_nop 0
	v_addc_co_u32_e32 v3, vcc, 0, v107, vcc
	v_add_co_u32_e32 v54, vcc, s62, v106
	v_mfma_f32_16x16x32_bf16 v[46:49], v[82:85], v[78:81], v[46:49]
	s_nop 0
	v_addc_co_u32_e32 v55, vcc, 0, v107, vcc
	v_mfma_f32_16x16x32_bf16 v[50:53], v[90:93], v[78:81], v[50:53]
	v_mfma_f32_16x16x32_bf16 v[22:25], v[74:77], v[94:97], v[22:25]
	v_mfma_f32_16x16x32_bf16 v[38:41], v[98:101], v[78:81], v[38:41]
	v_mfma_f32_16x16x32_bf16 v[26:29], v[82:85], v[94:97], v[26:29]
	v_mfma_f32_16x16x32_bf16 v[6:9], v[74:77], v[86:89], v[6:9]
	v_mfma_f32_16x16x32_bf16 v[10:13], v[82:85], v[86:89], v[10:13]
	v_mfma_f32_16x16x32_bf16 v[14:17], v[90:93], v[86:89], v[14:17]
	v_mfma_f32_16x16x32_bf16 v[18:21], v[98:101], v[86:89], v[18:21]
	global_store_dwordx4 v[54:55], v[42:45], off offset:-4096
	global_store_dwordx4 v[2:3], v[46:49], off offset:64
	global_store_dwordx4 v[2:3], v[50:53], off offset:128
	global_store_dwordx4 v[2:3], v[38:41], off offset:192
	s_nop 0
	global_store_dwordx4 v[54:55], v[6:9], off
	global_store_dwordx4 v[54:55], v[10:13], off offset:64
	global_store_dwordx4 v[54:55], v[14:17], off offset:128
	global_store_dwordx4 v[54:55], v[18:21], off offset:192
	v_add_co_u32_e32 v2, vcc, 0x7000, v106
	v_mfma_f32_16x16x32_bf16 v[30:33], v[90:93], v[94:97], v[30:33]
	s_nop 0
	v_addc_co_u32_e32 v3, vcc, 0, v107, vcc
	v_mfma_f32_16x16x32_bf16 v[34:37], v[98:101], v[94:97], v[34:37]
	global_store_dwordx4 v[2:3], v[22:25], off
	global_store_dwordx4 v[2:3], v[26:29], off offset:64
	s_nop 2
	global_store_dwordx4 v[2:3], v[30:33], off offset:128
	s_nop 1
	global_store_dwordx4 v[2:3], v[34:37], off offset:192
	s_waitcnt lgkmcnt(0)
	s_cbranch_scc0 .LBB0_284
	s_branch .LBB0_281
